# A1/D/A2 (512-unit phases): u = 2*w'+k so each XCD owns one batch and a WG processes two adjacent query blocks
# baseline (speedup 1.0000x reference)
; #define LAS __attribute__((address_space(3)))
; DI float ex2(float x) { return __builtin_amdgcn_exp2f(x); }
; DI float a_bound(const bf16x8 (&qf)[2], const float* kmax_l, int b, int h) { return sqrtf(q_norm2(qf) * (kmax_l[b * 128 + 8 + 2 * h] + kmax_l[b * 128 + 9 + 2 * h])) * 1.01f + 0.05f; }
; #define LAUNDER() int tp = TID0(); const int tid = tp, lane = tp & 63, wave = __builtin_amdgcn_readfirstlane(tp >> 6); (void)tid; (void)lane; (void)wave
; DI void mixerA1_unit(int u, const bf16* PROJ, bf16* YC, float* LPA, const float* kmax_l, LAS char* vt, int wave, int lane) {
;     const int b = u >> 6, h = (u >> 4) & 3, qblk = u & 15, r = lane & 15, g = lane >> 4;
;     const bf16* kb = slab(PROJ, C_AK + h * 64, b); const bf16* vb = slab(PROJ, C_AV + h * 64, b);
;     const int t0 = qblk * 128 + wave * 16, tq = t0 + r;
;     bf16x8 qf[2];
; #pragma unroll
;     for (int ks = 0; ks < 2; ++ks) qf[ks] = *(const bf16x8*)(slab(PROJ, C_AQ + h * 64, b) + (size_t)tq * 64 + 32 * ks + 8 * g);
;     const float nslope2 = -ex2(-(float)(2 * h + 1)) * LOG2E;
;     const float bound = a_bound(qf, kmax_l, b, h);
;     const f32x4 cinit = {-bound, -bound, -bound, -bound};
;     f32x4 o[4], ol = {0.f, 0.f, 0.f, 0.f};
; #pragma unroll
;     for (int c = 0; c < 4; ++c) o[c] = ol;
;     TileRegs R0, R1, R2;
;     const int tb0 = t0 - 64;
;     tile_load(R0, kb, vb, tb0, 1, lane); tile_load(R1, kb, vb, tb0 + 32, 1, lane); tile_load(R2, kb, vb, tb0 + 64, 1, lane);
;     f32x4 sA[2], sB[2];
;     a_stage(sA, R0, vt, 0, qf, cinit, tb0, 1, 64, tq, nslope2, lane);        tile_load(R0, kb, vb, tb0 + 96, 1, lane);
; __global__ void __launch_bounds__(512) fwd_kernel(Args a) {
;     ...
;             if (EN_A) { LAUNDER(); LAS char* vt = (LAS char*)lds + wave * 16384;
;                 for (int u = blockIdx.x; u < 512; u += G) { mixerA1_unit(u, PROJ, YC, LPA, KMAX + l * 1024, vt, wave, lane); } }
.LBB0_356:
	v_readlane_b32 s0, v253, 0
	v_readlane_b32 s4, v254, 31
	s_waitcnt vmcnt(63) expcnt(7) lgkmcnt(15)
	s_barrier
	v_mbcnt_lo_u32_b32 v4, -1, 0
	v_mbcnt_hi_u32_b32 v4, -1, v4
	v_readlane_b32 s5, v254, 32
	v_add_u32_e32 v5, s0, v4
	v_readlane_b32 s94, v255, 33
	v_readfirstlane_b32 s0, v5
	v_cndmask_b32_e64 v5, 0, 1, s[4:5]
	v_readlane_b32 s96, v255, 19
	v_cmp_ne_u32_e64 s[36:37], 1, v5
	s_andn2_b64 vcc, exec, s[4:5]
	v_readlane_b32 s95, v255, 34
	v_readlane_b32 s97, v255, 20
	s_cbranch_vccnz .LBB0_361
	s_ashr_i32 s5, s0, 6
	s_lshl_b32 s0, s5, 14
	s_add_i32 s16, s0, 0
	v_readlane_b32 s0, v255, 27
	v_readlane_b32 s1, v255, 28
	s_lshl_b32 s34, s0, 10
	s_lshl_b64 s[0:1], s[34:35], 2
	v_readlane_b32 s20, v253, 42
	v_bfe_u32 v7, v4, 4, 2
	s_add_u32 s2, s20, s0
	v_and_b32_e32 v109, 15, v4
	v_lshlrev_b32_e32 v131, 2, v7
	v_mov_b32_e32 v10, s16
	s_movk_i32 s0, 0x90
	v_bfe_u32 v11, v4, 2, 4
	v_mad_u32_u24 v132, v109, s0, v10
	v_mad_u32_u24 v10, v11, s0, v10
	v_sub_u32_e32 v11, v131, v109
	v_add_u32_e32 v12, 1, v11
	v_and_b32_e32 v8, 64, v224
	v_cvt_f32_i32_e32 v134, v12
	v_add_u32_e32 v12, 2, v11
	v_xor_b32_e32 v6, 16, v224
	v_add_u32_e32 v8, 64, v8
	v_cvt_f32_i32_e32 v135, v12
	v_add_u32_e32 v12, 3, v11
	v_cmp_lt_i32_e32 vcc, v6, v8
	v_cvt_f32_i32_e32 v136, v12
	v_add_u32_e32 v12, 16, v11
	v_cndmask_b32_e32 v6, v224, v6, vcc
	v_cvt_f32_u32_e32 v137, v12
	v_add_u32_e32 v12, 17, v11
	v_lshlrev_b32_e32 v124, 2, v6
	v_xor_b32_e32 v6, 32, v224
	v_cvt_f32_i32_e32 v133, v11
	v_cvt_f32_u32_e32 v138, v12
	v_add_u32_e32 v12, 18, v11
	v_add_u32_e32 v11, 19, v11
	v_and_b32_e32 v5, 63, v4
	v_cmp_lt_i32_e32 vcc, v6, v8
	v_bfe_u32 v126, v4, 3, 3
	v_lshlrev_b32_e32 v9, 4, v4
	v_cvt_f32_u32_e32 v139, v12
	v_cvt_f32_u32_e32 v140, v11
	v_lshlrev_b32_e32 v108, 3, v7
	v_cndmask_b32_e32 v6, v224, v6, vcc
	v_lshlrev_b32_e32 v8, 3, v5
	v_or_b32_e32 v127, 8, v126
	v_and_b32_e32 v9, 0x70, v9
	v_and_b32_e32 v7, 48, v4
	v_and_b32_e32 v4, 7, v4
	v_readlane_b32 s21, v253, 43
	v_lshlrev_b32_e32 v125, 2, v6
	v_and_b32_e32 v6, 56, v8
	v_add_u32_e32 v9, s16, v9
	v_mul_u32_u24_e32 v130, 0x90, v126
	v_and_b32_e32 v8, 24, v8
	v_lshl_add_u32 v141, v4, 4, s16
	v_lshlrev_b32_e32 v4, 3, v4
	v_mul_u32_u24_e32 v11, 0x90, v127
	s_addc_u32 s4, s21, s1
	s_lshl_b32 s5, s5, 4
	v_or_b32_e32 v128, 16, v126
	v_or_b32_e32 v129, 24, v126
	v_cmp_gt_u32_e32 vcc, 16, v5
	v_lshlrev_b32_e32 v110, 1, v6
	v_add_u32_e32 v142, v9, v130
	v_add_u32_e32 v143, v132, v7
	v_add_u32_e32 v144, v10, v8
	v_lshlrev_b32_e32 v112, 1, v4
	v_add_u32_e32 v145, v141, v11
	v_readlane_b32 s16, v255, 7
	v_readlane_b32 s26, v255, 40
	s_lshl_b32 s26, s26, 1
	s_branch .LBB0_359
.LBB0_358:
	s_or_b64 exec, exec, s[0:1]
	s_add_i32 s26, s26, 1
	s_addk_i32 s16, 0x80
	s_bitcmp0_b32 s26, 0
	s_cbranch_scc1 .LBB0_361

; #define LAS __attribute__((address_space(3)))
; DI float q_norm2(const bf16x8 (&qf)[2]) { float a = sumsq8(qf[0]) + sumsq8(qf[1]); a += __shfl_xor(a, 16); a += __shfl_xor(a, 32); return a; }
; DI void mixerD2_unit(int u, const bf16* PROJ, bf16* YC, float rmax, const float* kmax_l, LAS char* vt, int wave, int lane) {
;     const int b = u >> 6, h = (u >> 4) & 3, wu = (u & 15) * 8 + wave, rr = wu >> 2, cb = wu & 3, r = lane & 15, g = lane >> 4;
;     const bf16* kb = slab(PROJ, C_DK + h * 64, b); const bf16* vb = slab(PROJ, C_DV + h * 64, b);
;     const int qcol = 16 * cb + r, tq = 64 * rr + qcol;
;     const int cs = min(max(qcol - 8, 0), 48), rs = min(max(rr - 4, 0), 24), c0 = min(max(16 * cb - 8, 0), 32);
;     LAS float* rp = (LAS float*)(vt + 12288);
;     bf16x8 qf[2];
; #pragma unroll
;     for (int ks = 0; ks < 2; ++ks) qf[ks] = *(const bf16x8*)(slab(PROJ, C_DQ + h * 64, b) + (size_t)tq * 64 + 32 * ks + 8 * g);
;     const float bound = sqrtf(q_norm2(qf) * (kmax_l[b * 128 + 104 + 2 * h] + kmax_l[b * 128 + 105 + 2 * h])) * 1.01f + 0.05f + rmax;
;     const f32x4 cinit = {-bound, -bound, -bound, -bound};
;     f32x4 o[4], ol = {0.f, 0.f, 0.f, 0.f};
; #pragma unroll
;     for (int c = 0; c < 4; ++c) o[c] = ol;
;     const int tb0 = 64 * rs + c0, dr0 = rs - rr + 7;
;     const int kc0 = c0 + 4 * g - cs;
;     const LAS float* rpl = rp + dr0 * 31 + (c0 + 4 * g - qcol + 15);
;     TileRegs R0, R1, R2;
;     tile_load(R0, kb, vb, tb0, 1, lane); tile_load(R1, kb, vb, tb0 + 64, 1, lane); tile_load(R2, kb, vb, tb0 + 128, 1, lane);
; __global__ void __launch_bounds__(512) fwd_kernel(Args a) {
;     ...
;                 for (int u = blockIdx.x; u < 512; u += G) { const int hd = (u >> 4) & 3; if (hd != hcur) { rmax = d_stage_rpb(a.in[14] + l * 4 * 15 * 31, hd, vt, lane); hcur = hd; }
;                     mixerD2_unit(u, PROJ, YC, rmax, KMAX + l * 1024, vt, wave, lane); } }
.LBB0_361:
	v_readlane_b32 s0, v253, 0
	v_mbcnt_lo_u32_b32 v4, -1, 0
	v_mbcnt_hi_u32_b32 v4, -1, v4
	s_and_b64 vcc, exec, s[36:37]
	s_nop 0
	v_add_u32_e32 v5, s0, v4
	s_nop 0
	v_readfirstlane_b32 s0, v5
	s_cbranch_vccnz .LBB0_369
	s_ashr_i32 s2, s0, 6
	v_readlane_b32 s26, v255, 27
	v_readlane_b32 s1, v254, 26
	s_lshl_b32 s0, s2, 14
	s_lshl_b32 s34, s26, 10
	s_add_i32 s20, s0, 0
	s_lshl_b64 s[0:1], s[34:35], 2
	v_readlane_b32 s4, v253, 42
	v_readlane_b32 s5, v253, 43
	s_add_u32 s4, s4, s0
	s_addc_u32 s5, s5, s1
	s_lshl_b32 s0, s2, 4
	s_and_b32 s16, s0, 48
	v_and_b32_e32 v5, 15, v4
	v_sub_u32_e64 v8, s16, 8 clamp
	v_or_b32_e32 v78, s16, v5
	v_readfirstlane_b32 s0, v8
	v_bfe_u32 v6, v4, 4, 2
	v_sub_u32_e64 v7, v78, 8 clamp
	v_and_b32_e32 v10, 64, v224
	s_min_u32 s33, s0, 32
	v_lshlrev_b32_e32 v68, 3, v6
	v_xor_b32_e32 v9, 16, v224
	v_add_u32_e32 v10, 64, v10
	v_min_u32_e32 v7, 48, v7
	v_lshl_add_u32 v6, v6, 2, s33
	v_cmp_lt_i32_e32 vcc, v9, v10
	v_sub_u32_e32 v7, v6, v7
	v_mov_b32_e32 v8, s20
	s_movk_i32 s1, 0x90
	v_cndmask_b32_e32 v9, v224, v9, vcc
	v_mad_u32_u24 v87, v5, s1, v8
	v_add_u32_e32 v5, 1, v7
	v_lshlrev_b32_e32 v79, 2, v9
	v_xor_b32_e32 v9, 32, v224
	v_cmp_gt_u32_e64 s[38:39], 16, v5
	v_add_u32_e32 v5, 2, v7
	v_cmp_lt_i32_e32 vcc, v9, v10
	v_cmp_gt_u32_e64 s[40:41], 16, v5
	v_add_u32_e32 v5, 3, v7
	v_and_b32_e32 v69, 63, v4
	v_cndmask_b32_e32 v9, v224, v9, vcc
	v_cmp_gt_u32_e64 s[42:43], 16, v5
	v_add_u32_e32 v5, 17, v7
	v_lshlrev_b32_e32 v80, 2, v9
	v_sub_u32_e32 v6, v6, v78
	v_lshlrev_b32_e32 v9, 3, v69
	s_movk_i32 s0, 0xffef
	v_cmp_gt_u32_e64 s[46:47], 16, v5
	v_add_u32_e32 v5, 18, v7
	v_lshl_add_u32 v81, v6, 2, s20
	v_and_b32_e32 v6, 56, v9
	v_cmp_gt_u32_e64 s[36:37], 16, v7
	v_cmp_lt_u32_e64 s[44:45], s0, v7
	v_cmp_gt_u32_e64 s[48:49], 16, v5
	v_add_u32_e32 v5, 19, v7
	v_and_b32_e32 v7, 24, v9
	v_xor_b32_e32 v9, 1, v224
	v_cmp_lt_i32_e32 vcc, v9, v10
	v_lshlrev_b32_e32 v11, 4, v4
	v_cmp_gt_u32_e64 s[50:51], 16, v5
	v_cndmask_b32_e32 v9, v224, v9, vcc
	v_lshlrev_b32_e32 v89, 2, v9
	v_xor_b32_e32 v9, 2, v224
	v_cmp_lt_i32_e32 vcc, v9, v10
	v_bfe_u32 v5, v4, 2, 4
	v_bfe_u32 v82, v4, 3, 3
	v_cndmask_b32_e32 v9, v224, v9, vcc
	v_lshlrev_b32_e32 v90, 2, v9
	v_xor_b32_e32 v9, 4, v224
	v_cmp_lt_i32_e32 vcc, v9, v10
	v_and_b32_e32 v11, 0x70, v11
	v_mad_u32_u24 v5, v5, s1, v8
	v_cndmask_b32_e32 v9, v224, v9, vcc
	v_and_b32_e32 v8, 7, v4
	v_lshlrev_b32_e32 v91, 2, v9
	v_xor_b32_e32 v9, 8, v224
	v_readlane_b32 s52, v253, 5
	v_or_b32_e32 v83, 8, v82
	v_add_u32_e32 v11, s20, v11
	v_lshl_add_u32 v88, v8, 4, s20
	v_cmp_lt_i32_e32 vcc, v9, v10
	s_addk_i32 s20, 0x3000
	s_mul_i32 s1, s26, 0x1d10
	v_readlane_b32 s64, v253, 17
	v_readlane_b32 s66, v253, 19
	v_mul_u32_u24_e32 v86, 0x90, v82
	v_and_b32_e32 v12, 48, v4
	v_lshlrev_b32_e32 v4, 3, v8
	v_mul_u32_u24_e32 v8, 0x90, v83
	v_cndmask_b32_e32 v9, v224, v9, vcc
	v_lshl_add_u32 v93, v69, 2, s20
	s_mul_hi_u32 s0, s26, 0x1d10
	v_readlane_b32 s65, v253, 18
	v_readlane_b32 s66, v253, 23
	s_add_u32 s20, s64, s1
	s_mov_b32 s34, -1
	v_or_b32_e32 v84, 16, v82
	v_or_b32_e32 v85, 24, v82
	v_lshlrev_b32_e32 v92, 2, v9
	v_or_b32_e32 v94, 0xffffffc0, v69
	s_addc_u32 s21, s65, s0
	v_mov_b32_e32 v99, 0
	v_lshlrev_b32_e32 v70, 1, v6
	v_add_u32_e32 v95, v11, v86
	v_add_u32_e32 v96, v87, v12
	v_add_u32_e32 v97, v5, v7
	v_lshlrev_b32_e32 v72, 1, v4
	v_add_u32_e32 v98, v88, v8
	v_readlane_b32 s52, v255, 40
	s_lshl_b32 s52, s52, 1
	v_readlane_b32 s27, v255, 28
	v_readlane_b32 s53, v253, 6
	v_readlane_b32 s54, v253, 7
	v_readlane_b32 s55, v253, 8
	v_readlane_b32 s56, v253, 9
	v_readlane_b32 s57, v253, 10
	v_readlane_b32 s58, v253, 11
	v_readlane_b32 s59, v253, 12
	v_readlane_b32 s60, v253, 13
	v_readlane_b32 s61, v253, 14
	v_readlane_b32 s62, v253, 15
	v_readlane_b32 s63, v253, 16
	v_readlane_b32 s67, v253, 20
	s_branch .LBB0_364
.LBB0_363:
	s_lshl_b32 s0, s52, 3
	s_and_b32 s0, s0, 0x78
	s_ashr_i32 s26, s52, 6
	s_add_i32 s0, s0, s2
	s_ashr_i32 s0, s0, 2
	s_ashr_i32 s27, s26, 31
	s_lshl_b32 s1, s53, 21
	s_add_u32 s1, s10, s1
	s_addc_u32 s55, s11, 0
	s_lshl_b32 s54, s0, 6
	s_max_i32 s57, s0, 4
	s_lshl_b64 s[30:31], s[26:27], 18
	v_or_b32_e32 v4, s54, v78
	s_add_i32 s57, s57, -4
	v_ashrrev_i32_e32 v5, 31, v4
	s_add_u32 s30, s1, s30
	v_lshlrev_b64 v[4:5], 7, v[4:5]
	s_addc_u32 s31, s55, s31
	v_lshl_add_u64 v[4:5], s[30:31], 0, v[4:5]
	v_lshlrev_b32_e32 v188, 1, v68
	v_lshl_add_u64 v[4:5], v[4:5], 0, v[188:189]
	s_mov_b64 s[60:61], 0x6000000
	s_mov_b32 s1, 0x6000000
	v_lshl_add_u64 v[8:9], v[4:5], 0, s[60:61]
	v_add_co_u32_e32 v4, vcc, s1, v4
	s_min_u32 s1, s57, 24
	s_nop 0
	v_addc_co_u32_e32 v5, vcc, 0, v5, vcc
	global_load_dwordx4 v[4:7], v[4:5], off
	s_nop 0
	global_load_dwordx4 v[8:11], v[8:9], off offset:64
	s_lshl_b32 s55, s26, 7
	s_lshl_b32 s57, s53, 1
	s_or_b32 s60, s57, s55
	s_ashr_i32 s61, s60, 31
	s_lshl_b64 s[60:61], s[60:61], 2
	s_add_u32 s60, s4, s60
	s_addc_u32 s61, s5, s61
	global_load_dwordx2 v[12:13], v189, s[60:61] offset:416
	v_mov_b32_e32 v71, v189
	v_lshl_add_u64 v[14:15], s[30:31], 0, v[70:71]
	s_mov_b64 s[60:61], 0x6800000
	s_lshl_b32 s55, s1, 6
	v_lshl_add_u64 v[74:75], v[14:15], 0, s[60:61]
	s_mov_b64 s[60:61], 0x7000000
	s_or_b32 s55, s55, s33
	v_lshl_add_u64 v[76:77], v[14:15], 0, s[60:61]
	v_or_b32_e32 v14, s55, v82
	v_lshlrev_b32_e32 v188, 7, v14
	v_lshl_add_u64 v[14:15], v[74:75], 0, v[188:189]
	v_lshl_add_u64 v[20:21], v[76:77], 0, v[188:189]
	v_add_lshl_u32 v188, s55, v83, 7
	global_load_dwordx4 v[16:19], v[14:15], off
	s_nop 0
	global_load_dwordx4 v[20:23], v[20:21], off
	v_lshl_add_u64 v[14:15], v[74:75], 0, v[188:189]
	v_lshl_add_u64 v[28:29], v[76:77], 0, v[188:189]
	v_add_lshl_u32 v188, s55, v84, 7
	global_load_dwordx4 v[24:27], v[14:15], off
	s_nop 0
	global_load_dwordx4 v[28:31], v[28:29], off
	v_lshl_add_u64 v[14:15], v[74:75], 0, v[188:189]
	v_lshl_add_u64 v[36:37], v[76:77], 0, v[188:189]
	v_add_lshl_u32 v188, s55, v85, 7
	global_load_dwordx4 v[32:35], v[14:15], off
	s_nop 0
	global_load_dwordx4 v[36:39], v[36:37], off
	v_lshl_add_u64 v[14:15], v[74:75], 0, v[188:189]
	v_lshl_add_u64 v[44:45], v[76:77], 0, v[188:189]
	global_load_dwordx4 v[40:43], v[14:15], off
	s_nop 0
	global_load_dwordx4 v[44:47], v[44:45], off
	s_add_i32 s57, s55, 64
	s_sub_i32 s0, s1, s0
	s_mulk_i32 s0, 0x7c
	v_add_u32_e32 v71, s0, v81
	v_add_u32_e32 v73, 0x33a0, v71
	s_or_b32 s54, s54, s16
	s_waitcnt vmcnt(10)
; #define LAS __attribute__((address_space(3)))
; #define MFMA16(a, b, c) __builtin_amdgcn_mfma_f32_16x16x32_bf16((a), (b), (c), 0, 0, 0)
; DI bf16x8 k_frag(const LAS char* vt, int t, int ks, int lane) { return k_frag_at(vt + KT_OFF, t, ks, lane); }
; DI float q_norm2(const bf16x8 (&qf)[2]) { float a = sumsq8(qf[0]) + sumsq8(qf[1]); a += __shfl_xor(a, 16); a += __shfl_xor(a, 32); return a; }
; DI void d_compute(f32x4 (&o)[4], f32x4& ol, const TileRegs& R, const bf16x8 (&qf)[2], const f32x4 cinit, int kr, int kc0, const LAS float* rpl, LAS char* vt, int lane) {
;     tile_v_to_lds(R, vt, lane);
;     const LAS float* rr_ = rpl + kr * 31;
;     f32x4 st[2];
; #pragma unroll
;     for (int t = 0; t < 2; ++t) {
;         st[t] = MFMA16(k_frag(vt, t, 0, lane), qf[0], cinit); st[t] = MFMA16(k_frag(vt, t, 1, lane), qf[1], st[t]);
; #pragma unroll
;         for (int i = 0; i < 4; ++i) { const bool ok = (unsigned)(kc0 + 16 * t + i) <= 15u;
;             const float v = st[t][i] + rr_[16 * t + i];
;             st[t][i] = ok ? v : -1e30f; }
;     }
;     fb_update(o, ol, st[0], st[1], vt, lane);
;     asm volatile("" ::: "memory");
; }
; DI void mixerD2_unit(int u, const bf16* PROJ, bf16* YC, float rmax, const float* kmax_l, LAS char* vt, int wave, int lane) {
;     ...
;     for (int ks = 0; ks < 2; ++ks) qf[ks] = *(const bf16x8*)(slab(PROJ, C_DQ + h * 64, b) + (size_t)tq * 64 + 32 * ks + 8 * g);
;     const float bound = sqrtf(q_norm2(qf) * (kmax_l[b * 128 + 104 + 2 * h] + kmax_l[b * 128 + 105 + 2 * h])) * 1.01f + 0.05f + rmax;
;     const f32x4 cinit = {-bound, -bound, -bound, -bound};
;     f32x4 o[4], ol = {0.f, 0.f, 0.f, 0.f};
; #pragma unroll
;     for (int c = 0; c < 4; ++c) o[c] = ol;
;     const int tb0 = 64 * rs + c0, dr0 = rs - rr + 7;
;     const int kc0 = c0 + 4 * g - cs;
;     const LAS float* rpl = rp + dr0 * 31 + (c0 + 4 * g - qcol + 15);
;     TileRegs R0, R1, R2;
;     tile_load(R0, kb, vb, tb0, 1, lane); tile_load(R1, kb, vb, tb0 + 64, 1, lane); tile_load(R2, kb, vb, tb0 + 128, 1, lane);
;     d_compute(o, ol, R0, qf, cinit, 0, kc0, rpl, vt, lane); tile_load(R0, kb, vb, tb0 + 192, 1, lane);
;     d_compute(o, ol, R1, qf, cinit, 1, kc0, rpl, vt, lane); tile_load(R1, kb, vb, tb0 + 256, 1, lane);
	v_and_b32_e32 v48, 0xffff0000, v4
	s_waitcnt vmcnt(9)
	v_and_b32_e32 v49, 0xffff0000, v8
	v_and_b32_e32 v53, 0xffff0000, v9
	v_and_b32_e32 v52, 0xffff0000, v5
	v_lshlrev_b32_e32 v14, 16, v4
	v_lshlrev_b32_e32 v15, 16, v8
	v_lshlrev_b32_e32 v50, 16, v5
	v_lshlrev_b32_e32 v51, 16, v9
	v_and_b32_e32 v57, 0xffff0000, v10
	v_and_b32_e32 v56, 0xffff0000, v6
	v_pk_mul_f32 v[48:49], v[48:49], v[48:49]
	v_pk_mul_f32 v[52:53], v[52:53], v[52:53]
	v_lshlrev_b32_e32 v54, 16, v6
	v_lshlrev_b32_e32 v55, 16, v10
	v_and_b32_e32 v61, 0xffff0000, v11
	v_and_b32_e32 v60, 0xffff0000, v7
	v_pk_mul_f32 v[56:57], v[56:57], v[56:57]
	v_pk_fma_f32 v[14:15], v[14:15], v[14:15], v[48:49]
	v_pk_fma_f32 v[48:49], v[50:51], v[50:51], v[52:53]
	v_lshlrev_b32_e32 v58, 16, v7
	v_lshlrev_b32_e32 v59, 16, v11
	v_pk_mul_f32 v[60:61], v[60:61], v[60:61]
	v_pk_fma_f32 v[50:51], v[54:55], v[54:55], v[56:57]
	v_pk_add_f32 v[14:15], v[14:15], v[48:49]
	v_pk_fma_f32 v[52:53], v[58:59], v[58:59], v[60:61]
	v_pk_add_f32 v[14:15], v[50:51], v[14:15]
	s_waitcnt vmcnt(8)
	v_mov_b32_e32 v48, v13
	v_pk_add_f32 v[14:15], v[52:53], v[14:15]
	s_nop 0
	v_add_f32_e32 v14, v14, v15
	ds_bpermute_b32 v15, v79, v14
	s_waitcnt lgkmcnt(0)
	v_add_f32_e32 v15, v14, v15
	ds_bpermute_b32 v49, v80, v15
	v_mov_b32_e32 v14, v12
	s_waitcnt lgkmcnt(0)
	v_pk_add_f32 v[12:13], v[14:15], v[48:49]
	s_nop 0
	v_mul_f32_e32 v12, v12, v13
	v_mul_f32_e32 v13, 0x4f800000, v12
	v_cmp_gt_f32_e32 vcc, s92, v12
	v_or_b32_e32 v14, s57, v82
	v_lshlrev_b32_e32 v188, 7, v14
	v_cndmask_b32_e32 v12, v12, v13, vcc
	v_sqrt_f32_e32 v13, v12
	v_lshl_add_u64 v[48:49], v[74:75], 0, v[188:189]
	v_lshl_add_u64 v[52:53], v[76:77], 0, v[188:189]
	v_add_lshl_u32 v188, s57, v83, 7
	v_add_u32_e32 v14, -1, v13
	v_lshl_add_u64 v[56:57], v[74:75], 0, v[188:189]
	v_lshl_add_u64 v[60:61], v[76:77], 0, v[188:189]
	v_add_lshl_u32 v188, s57, v84, 7
	v_add_u32_e32 v15, 1, v13
	v_fma_f32 v50, -v14, v13, v12
	v_lshl_add_u64 v[64:65], v[74:75], 0, v[188:189]
	v_lshl_add_u64 v[100:101], v[76:77], 0, v[188:189]
	v_add_lshl_u32 v188, s57, v85, 7
	v_fma_f32 v51, -v15, v13, v12
	v_cmp_ge_f32_e64 s[0:1], 0, v50
	v_lshl_add_u64 v[104:105], v[74:75], 0, v[188:189]
	v_lshl_add_u64 v[108:109], v[76:77], 0, v[188:189]
	v_cndmask_b32_e64 v13, v13, v14, s[0:1]
	v_cmp_lt_f32_e64 s[0:1], 0, v51
	global_load_dwordx4 v[48:51], v[48:49], off
	s_nop 0
	global_load_dwordx4 v[52:55], v[52:53], off
	s_nop 0
	global_load_dwordx4 v[56:59], v[56:57], off
	s_nop 0
	global_load_dwordx4 v[60:63], v[60:61], off
	s_nop 0
	global_load_dwordx4 v[64:67], v[64:65], off
	s_nop 0
	global_load_dwordx4 v[100:103], v[100:101], off
	s_nop 0
	global_load_dwordx4 v[104:107], v[104:105], off
	s_nop 0
	global_load_dwordx4 v[108:111], v[108:109], off
	s_waitcnt vmcnt(14)
	ds_write_b128 v95, v[20:23]
	ds_write_b128 v95, v[16:19] offset:4608
	s_waitcnt vmcnt(12)
	ds_write_b128 v95, v[28:31] offset:1152
	ds_write_b128 v95, v[24:27] offset:5760
	s_waitcnt vmcnt(10)
	ds_write_b128 v95, v[36:39] offset:2304
	ds_write_b128 v95, v[32:35] offset:6912
	s_waitcnt vmcnt(8)
	ds_write_b128 v95, v[44:47] offset:3456
	ds_write_b128 v95, v[40:43] offset:8064
	ds_read_b128 v[16:19], v96 offset:4608
	ds_read_b128 v[36:39], v96 offset:4672
	v_cndmask_b32_e64 v13, v13, v15, s[0:1]
	v_mul_f32_e32 v14, 0x37800000, v13
	v_cndmask_b32_e32 v13, v13, v14, vcc
	v_cmp_class_f32_e32 vcc, v12, v226
	s_add_i32 s0, s55, 0x80
	v_or_b32_e32 v112, s0, v82
	v_cndmask_b32_e32 v12, v13, v12, vcc
	v_fmamk_f32 v12, v12, 0x3f8147ae, v227
	v_add_f32_e32 v12, v99, v12
	v_xor_b32_e32 v12, 0x80000000, v12
	v_mov_b32_e32 v13, v12
	v_mov_b32_e32 v14, v12
	v_mov_b32_e32 v15, v12
	v_lshlrev_b32_e32 v188, 7, v112
	v_lshl_add_u64 v[20:21], v[74:75], 0, v[188:189]
	s_waitcnt lgkmcnt(1)
	v_mfma_f32_16x16x32_bf16 v[16:19], v[16:19], v[4:7], v[12:15]
	v_lshl_add_u64 v[24:25], v[76:77], 0, v[188:189]
	v_add_lshl_u32 v188, s0, v83, 7
	v_lshl_add_u64 v[28:29], v[74:75], 0, v[188:189]
	v_lshl_add_u64 v[32:33], v[76:77], 0, v[188:189]
	global_load_dwordx4 v[20:23], v[20:21], off
	s_nop 0
	global_load_dwordx4 v[24:27], v[24:25], off
	s_nop 0
	global_load_dwordx4 v[28:31], v[28:29], off
	s_nop 0
	global_load_dwordx4 v[32:35], v[32:33], off
	ds_read2_b32 v[40:41], v73 offset1:1
	s_waitcnt lgkmcnt(1)
	v_mfma_f32_16x16x32_bf16 v[16:19], v[36:39], v[8:11], v[16:19]
	v_add_u32_e32 v44, 0x33e0, v71
	v_add_u32_e32 v45, 0x33e8, v71
	v_add_lshl_u32 v188, s0, v84, 7
	s_waitcnt lgkmcnt(0)
	s_nop 3
	v_add_f32_e32 v16, v16, v40
	v_cndmask_b32_e64 v73, v234, v16, s[36:37]
	v_add_f32_e32 v16, v17, v41
	v_cndmask_b32_e64 v114, v234, v16, s[38:39]
	v_add_u32_e32 v16, 0x33a8, v71
	ds_read_b128 v[36:39], v96 offset:6912
	ds_read2_b32 v[16:17], v16 offset1:1
	ds_read_b128 v[40:43], v96 offset:6976
	s_waitcnt lgkmcnt(2)
	v_mfma_f32_16x16x32_bf16 v[36:39], v[36:39], v[4:7], v[12:15]
	s_waitcnt lgkmcnt(1)
	v_add_f32_e32 v16, v18, v16
	v_cndmask_b32_e64 v115, v234, v16, s[40:41]
	v_add_f32_e32 v16, v19, v17
	v_cndmask_b32_e64 v116, v234, v16, s[42:43]
	s_waitcnt lgkmcnt(0)
	v_mfma_f32_16x16x32_bf16 v[16:19], v[40:43], v[8:11], v[36:39]
	ds_read2_b32 v[46:47], v44 offset1:1
	ds_read2_b32 v[112:113], v45 offset1:1
	ds_read_b64_tr_b16 v[44:45], v97
	v_exp_f32_e32 v36, v73
	v_exp_f32_e32 v37, v115
	s_waitcnt lgkmcnt(2)
	s_nop 1
	v_add_f32_e32 v16, v16, v46
	v_add_f32_e32 v17, v17, v47
	ds_read_b64_tr_b16 v[46:47], v97 offset:2304
	s_waitcnt lgkmcnt(2)
; #define LAS __attribute__((address_space(3)))
; #define MFMA16(a, b, c) __builtin_amdgcn_mfma_f32_16x16x32_bf16((a), (b), (c), 0, 0, 0)
; DI float ex2(float x) { return __builtin_amdgcn_exp2f(x); }
; DI s16x4 vtr(const LAS char* p) { return __builtin_bit_cast(s16x4, __builtin_amdgcn_ds_read_tr16_b64_v4i16((LAS s16x4*)p)); }
; DI bf16x8 cat8(s16x4 lo, s16x4 hi) { return __builtin_shufflevector(lo, hi, 0, 1, 2, 3, 4, 5, 6, 7); }
; DI bf16x8 pack8(f32x4 a, f32x4 b) { u32x4 w; w.x = pk2(a[0], a[1]); w.y = pk2(a[2], a[3]); w.z = pk2(b[0], b[1]); w.w = pk2(b[2], b[3]); return __builtin_bit_cast(bf16x8, w); }
; DI bf16x8 k_frag(const LAS char* vt, int t, int ks, int lane) { return k_frag_at(vt + KT_OFF, t, ks, lane); }
; DI void fb_update(f32x4 (&o)[4], f32x4& ol, const f32x4 st0, const f32x4 st1, const LAS char* vt, int lane) {
;     f32x4 p0, p1;
; #pragma unroll
;     for (int i = 0; i < 4; ++i) { p0[i] = ex2(st0[i]); p1[i] = ex2(st1[i]); }
;     const bf16x8 pf = pack8(p0, p1);
;     const bf16x8 ones = {0x3F80, 0x3F80, 0x3F80, 0x3F80, 0x3F80, 0x3F80, 0x3F80, 0x3F80};
;     ol = MFMA16(ones, pf, ol);
;     const int g = lane >> 4, q = (lane & 15) >> 2, p = lane & 3;
;     const LAS char* v0 = vt + (4 * g + q) * VT_PITCH + 8 * p;
;     const LAS char* v1 = v0 + 16 * VT_PITCH;
; #pragma unroll
;     for (int c = 0; c < 4; ++c) { const bf16x8 vf = cat8(vtr(v0 + 32 * c), vtr(v1 + 32 * c)); o[c] = MFMA16(vf, pf, o[c]); }
; }
; DI void d_compute(f32x4 (&o)[4], f32x4& ol, const TileRegs& R, const bf16x8 (&qf)[2], const f32x4 cinit, int kr, int kc0, const LAS float* rpl, LAS char* vt, int lane) {
;     tile_v_to_lds(R, vt, lane);
;     const LAS float* rr_ = rpl + kr * 31;
;     f32x4 st[2];
; #pragma unroll
;     for (int t = 0; t < 2; ++t) {
;         st[t] = MFMA16(k_frag(vt, t, 0, lane), qf[0], cinit); st[t] = MFMA16(k_frag(vt, t, 1, lane), qf[1], st[t]);
; #pragma unroll
;         for (int i = 0; i < 4; ++i) { const bool ok = (unsigned)(kc0 + 16 * t + i) <= 15u;
;             const float v = st[t][i] + rr_[16 * t + i];
;             st[t][i] = ok ? v : -1e30f; }
;     }
;     fb_update(o, ol, st[0], st[1], vt, lane);
;     asm volatile("" ::: "memory");
; }
	v_add_f32_e32 v18, v18, v112
	v_add_f32_e32 v19, v19, v113
	v_cndmask_b32_e64 v16, v234, v16, s[44:45]
	v_cndmask_b32_e64 v17, v234, v17, s[46:47]
	v_cndmask_b32_e64 v18, v234, v18, s[48:49]
	v_cndmask_b32_e64 v19, v234, v19, s[50:51]
	v_exp_f32_e32 v38, v16
	v_exp_f32_e32 v16, v114
	v_exp_f32_e32 v39, v17
	v_exp_f32_e32 v40, v18
	v_exp_f32_e32 v41, v116
	v_exp_f32_e32 v42, v19
	v_cvt_pk_bf16_f32 v36, v36, v16
	v_cvt_pk_bf16_f32 v38, v38, v39
	v_cvt_pk_bf16_f32 v37, v37, v41
	v_cvt_pk_bf16_f32 v39, v40, v42
	ds_read_b64_tr_b16 v[112:113], v97 offset:32
	ds_read_b64_tr_b16 v[114:115], v97 offset:2336
	s_waitcnt lgkmcnt(2)
	v_mfma_f32_16x16x32_bf16 v[124:127], v[44:47], v[36:39], 0
	v_lshl_add_u64 v[44:45], v[74:75], 0, v[188:189]
	v_lshl_add_u64 v[46:47], v[76:77], 0, v[188:189]
	v_add_lshl_u32 v188, s0, v85, 7
	ds_read_b64_tr_b16 v[116:117], v97 offset:64
	ds_read_b64_tr_b16 v[120:121], v97 offset:96
	ds_read_b64_tr_b16 v[118:119], v97 offset:2368
	ds_read_b64_tr_b16 v[122:123], v97 offset:2400
	global_load_dwordx4 v[128:131], v[44:45], off
	global_load_dwordx4 v[132:135], v[46:47], off
	v_lshl_add_u64 v[44:45], v[74:75], 0, v[188:189]
	v_lshl_add_u64 v[46:47], v[76:77], 0, v[188:189]
	global_load_dwordx4 v[136:139], v[44:45], off
	global_load_dwordx4 v[140:143], v[46:47], off
	s_waitcnt vmcnt(14)
	ds_write_b128 v95, v[52:55]
	ds_write_b128 v95, v[48:51] offset:4608
	s_waitcnt vmcnt(12)
	ds_write_b128 v95, v[60:63] offset:1152
	ds_write_b128 v95, v[56:59] offset:5760
	s_waitcnt vmcnt(10)
	ds_write_b128 v95, v[100:103] offset:2304
	ds_write_b128 v95, v[64:67] offset:6912
	s_waitcnt vmcnt(8)
	ds_write_b128 v95, v[108:111] offset:3456
	ds_write_b128 v95, v[104:107] offset:8064
	ds_read_b128 v[48:51], v96 offset:4608
	ds_read_b128 v[56:59], v96 offset:4672
	v_mov_b64_e32 v[16:17], s[84:85]
	v_mov_b64_e32 v[18:19], s[86:87]
	s_add_i32 s0, s55, 0xc0
	s_waitcnt lgkmcnt(14)
	v_mfma_f32_16x16x32_bf16 v[112:115], v[112:115], v[36:39], 0
	v_add_u32_e32 v64, 0x341c, v71
	v_add_u32_e32 v65, 0x345c, v71
	v_add_u32_e32 v66, 0x3464, v71
	v_mfma_f32_16x16x32_bf16 v[40:43], v[16:19], v[36:39], 0
	s_waitcnt lgkmcnt(11)
	v_mfma_f32_16x16x32_bf16 v[116:119], v[116:119], v[36:39], 0
	s_waitcnt lgkmcnt(10)
	v_mfma_f32_16x16x32_bf16 v[120:123], v[120:123], v[36:39], 0
	v_or_b32_e32 v36, s0, v82
	v_lshlrev_b32_e32 v188, 7, v36
	v_lshl_add_u64 v[36:37], v[74:75], 0, v[188:189]
	s_waitcnt lgkmcnt(1)
	v_mfma_f32_16x16x32_bf16 v[48:51], v[48:51], v[4:7], v[12:15]
	v_lshl_add_u64 v[44:45], v[76:77], 0, v[188:189]
	v_add_lshl_u32 v188, s0, v83, 7
	v_lshl_add_u64 v[52:53], v[74:75], 0, v[188:189]
	v_lshl_add_u64 v[60:61], v[76:77], 0, v[188:189]
	global_load_dwordx4 v[36:39], v[36:37], off
	s_nop 0
	global_load_dwordx4 v[44:47], v[44:45], off
	s_nop 0
	global_load_dwordx4 v[52:55], v[52:53], off
	s_nop 0
	global_load_dwordx4 v[60:63], v[60:61], off
	s_waitcnt lgkmcnt(0)
	v_mfma_f32_16x16x32_bf16 v[48:51], v[56:59], v[8:11], v[48:51]
	ds_read2_b32 v[100:101], v64 offset1:1
	ds_read_b128 v[56:59], v96 offset:6912
	v_add_u32_e32 v64, 0x3424, v71
	ds_read2_b32 v[102:103], v64 offset1:1
	ds_read2_b32 v[104:105], v65 offset1:1
	ds_read2_b32 v[106:107], v66 offset1:1
	ds_read_b128 v[64:67], v96 offset:6976
	s_waitcnt lgkmcnt(5)
	v_add_f32_e32 v48, v48, v100
	s_waitcnt lgkmcnt(4)
	v_mfma_f32_16x16x32_bf16 v[56:59], v[56:59], v[4:7], v[12:15]
	v_cndmask_b32_e64 v73, v234, v48, s[36:37]
	v_add_f32_e32 v48, v49, v101
	v_cndmask_b32_e64 v100, v234, v48, s[38:39]
	s_waitcnt lgkmcnt(3)
	v_add_f32_e32 v48, v50, v102
	v_cndmask_b32_e64 v101, v234, v48, s[40:41]
	v_add_f32_e32 v48, v51, v103
	v_cndmask_b32_e64 v102, v234, v48, s[42:43]
	s_waitcnt lgkmcnt(0)
	v_mfma_f32_16x16x32_bf16 v[48:51], v[64:67], v[8:11], v[56:59]
	v_add_lshl_u32 v188, s0, v84, 7
	s_nop 1
	v_exp_f32_e32 v56, v73
	v_exp_f32_e32 v59, v102
	s_nop 2
	v_add_f32_e32 v48, v48, v104
	v_add_f32_e32 v49, v49, v105
	v_cndmask_b32_e64 v48, v234, v48, s[44:45]
	v_cndmask_b32_e64 v49, v234, v49, s[46:47]
	v_exp_f32_e32 v57, v48
	v_exp_f32_e32 v48, v100
	v_exp_f32_e32 v58, v49
	v_exp_f32_e32 v49, v101
	v_add_f32_e32 v50, v50, v106
	v_add_f32_e32 v51, v51, v107
	v_cndmask_b32_e64 v50, v234, v50, s[48:49]
	v_cndmask_b32_e64 v51, v234, v51, s[50:51]
	v_exp_f32_e32 v64, v50
	v_exp_f32_e32 v51, v51
	v_cvt_pk_bf16_f32 v48, v56, v48
	v_cvt_pk_bf16_f32 v49, v49, v59
	v_cvt_pk_bf16_f32 v50, v57, v58
	ds_read_b64_tr_b16 v[58:59], v97 offset:2304
	ds_read_b64_tr_b16 v[56:57], v97
	v_cvt_pk_bf16_f32 v51, v64, v51
	v_add_u32_e32 v73, 0x3590, v71
	s_nop 0
	v_mfma_f32_16x16x32_bf16 v[100:103], v[16:19], v[48:51], v[40:43]
	s_nop 2
	ds_read_b64_tr_b16 v[42:43], v97 offset:2336
	ds_read_b64_tr_b16 v[40:41], v97 offset:32
	ds_read_b64_tr_b16 v[64:65], v97 offset:64
	ds_read_b64_tr_b16 v[104:105], v97 offset:96
	ds_read_b64_tr_b16 v[66:67], v97 offset:2368
	ds_read_b64_tr_b16 v[106:107], v97 offset:2400
	s_waitcnt lgkmcnt(6)
	v_mfma_f32_16x16x32_bf16 v[108:111], v[56:59], v[48:51], v[124:127]
	v_lshl_add_u64 v[56:57], v[74:75], 0, v[188:189]
	v_lshl_add_u64 v[58:59], v[76:77], 0, v[188:189]
	v_add_lshl_u32 v188, s0, v85, 7
	s_waitcnt lgkmcnt(4)
	v_mfma_f32_16x16x32_bf16 v[112:115], v[40:43], v[48:51], v[112:115]
	v_lshl_add_u64 v[40:41], v[74:75], 0, v[188:189]
	global_load_dwordx4 v[124:127], v[56:57], off
	global_load_dwordx4 v[144:147], v[58:59], off
	v_lshl_add_u64 v[42:43], v[76:77], 0, v[188:189]
	global_load_dwordx4 v[148:151], v[40:41], off
	global_load_dwordx4 v[152:155], v[42:43], off
	s_waitcnt vmcnt(14)
	ds_write_b128 v95, v[24:27]
	ds_write_b128 v95, v[20:23] offset:4608
	s_waitcnt vmcnt(12)
; #define LAS __attribute__((address_space(3)))
; #define MFMA16(a, b, c) __builtin_amdgcn_mfma_f32_16x16x32_bf16((a), (b), (c), 0, 0, 0)
; DI float ex2(float x) { return __builtin_amdgcn_exp2f(x); }
; DI s16x4 vtr(const LAS char* p) { return __builtin_bit_cast(s16x4, __builtin_amdgcn_ds_read_tr16_b64_v4i16((LAS s16x4*)p)); }
; DI bf16x8 cat8(s16x4 lo, s16x4 hi) { return __builtin_shufflevector(lo, hi, 0, 1, 2, 3, 4, 5, 6, 7); }
; DI bf16x8 pack8(f32x4 a, f32x4 b) { u32x4 w; w.x = pk2(a[0], a[1]); w.y = pk2(a[2], a[3]); w.z = pk2(b[0], b[1]); w.w = pk2(b[2], b[3]); return __builtin_bit_cast(bf16x8, w); }
; DI bf16x8 k_frag(const LAS char* vt, int t, int ks, int lane) { return k_frag_at(vt + KT_OFF, t, ks, lane); }
; DI void fb_update(f32x4 (&o)[4], f32x4& ol, const f32x4 st0, const f32x4 st1, const LAS char* vt, int lane) {
;     f32x4 p0, p1;
; #pragma unroll
;     for (int i = 0; i < 4; ++i) { p0[i] = ex2(st0[i]); p1[i] = ex2(st1[i]); }
;     const bf16x8 pf = pack8(p0, p1);
;     const bf16x8 ones = {0x3F80, 0x3F80, 0x3F80, 0x3F80, 0x3F80, 0x3F80, 0x3F80, 0x3F80};
;     ol = MFMA16(ones, pf, ol);
;     const int g = lane >> 4, q = (lane & 15) >> 2, p = lane & 3;
;     const LAS char* v0 = vt + (4 * g + q) * VT_PITCH + 8 * p;
;     const LAS char* v1 = v0 + 16 * VT_PITCH;
; #pragma unroll
;     for (int c = 0; c < 4; ++c) { const bf16x8 vf = cat8(vtr(v0 + 32 * c), vtr(v1 + 32 * c)); o[c] = MFMA16(vf, pf, o[c]); }
; }
; DI void d_compute(f32x4 (&o)[4], f32x4& ol, const TileRegs& R, const bf16x8 (&qf)[2], const f32x4 cinit, int kr, int kc0, const LAS float* rpl, LAS char* vt, int lane) {
;     tile_v_to_lds(R, vt, lane);
;     const LAS float* rr_ = rpl + kr * 31;
;     f32x4 st[2];
; #pragma unroll
;     for (int t = 0; t < 2; ++t) {
;         st[t] = MFMA16(k_frag(vt, t, 0, lane), qf[0], cinit); st[t] = MFMA16(k_frag(vt, t, 1, lane), qf[1], st[t]);
; #pragma unroll
;         for (int i = 0; i < 4; ++i) { const bool ok = (unsigned)(kc0 + 16 * t + i) <= 15u;
;             const float v = st[t][i] + rr_[16 * t + i];
;             st[t][i] = ok ? v : -1e30f; }
;     }
;     fb_update(o, ol, st[0], st[1], vt, lane);
;     asm volatile("" ::: "memory");
; }
	ds_write_b128 v95, v[32:35] offset:1152
	ds_write_b128 v95, v[28:31] offset:5760
	s_waitcnt vmcnt(10)
	ds_write_b128 v95, v[132:135] offset:2304
	ds_write_b128 v95, v[128:131] offset:6912
	s_waitcnt vmcnt(8)
	ds_write_b128 v95, v[140:143] offset:3456
	ds_write_b128 v95, v[136:139] offset:8064
	ds_read_b128 v[20:23], v96 offset:4608
	ds_read_b128 v[24:27], v96 offset:4672
	s_add_i32 s0, s55, 0x100
	v_or_b32_e32 v40, s0, v82
	v_lshlrev_b32_e32 v188, 7, v40
	s_waitcnt lgkmcnt(1)
	v_mfma_f32_16x16x32_bf16 v[20:23], v[20:23], v[4:7], v[12:15]
	v_lshl_add_u64 v[28:29], v[74:75], 0, v[188:189]
	v_lshl_add_u64 v[30:31], v[76:77], 0, v[188:189]
	v_add_lshl_u32 v188, s0, v83, 7
	v_mfma_f32_16x16x32_bf16 v[116:119], v[64:67], v[48:51], v[116:119]
	v_mfma_f32_16x16x32_bf16 v[104:107], v[104:107], v[48:51], v[120:123]
	global_load_dwordx4 v[40:43], v[28:29], off
	global_load_dwordx4 v[48:51], v[30:31], off
	v_lshl_add_u64 v[28:29], v[74:75], 0, v[188:189]
	v_lshl_add_u64 v[30:31], v[76:77], 0, v[188:189]
	global_load_dwordx4 v[56:59], v[28:29], off
	global_load_dwordx4 v[64:67], v[30:31], off
	v_add_u32_e32 v28, 0x3498, v71
	s_waitcnt lgkmcnt(0)
	v_mfma_f32_16x16x32_bf16 v[20:23], v[24:27], v[8:11], v[20:23]
	ds_read2_b32 v[32:33], v28 offset1:1
	ds_read_b128 v[24:27], v96 offset:6912
	v_add_u32_e32 v28, 0x34a0, v71
	v_add_u32_e32 v29, 0x34d8, v71
	v_add_u32_e32 v30, 0x34e0, v71
	ds_read2_b32 v[34:35], v28 offset1:1
	ds_read2_b32 v[120:121], v29 offset1:1
	ds_read2_b32 v[122:123], v30 offset1:1
	ds_read_b128 v[28:31], v96 offset:6976
	s_waitcnt lgkmcnt(5)
	v_add_f32_e32 v20, v20, v32
	s_waitcnt lgkmcnt(4)
	v_mfma_f32_16x16x32_bf16 v[24:27], v[24:27], v[4:7], v[12:15]
	v_cndmask_b32_e64 v32, v234, v20, s[36:37]
	v_add_f32_e32 v20, v21, v33
	v_cndmask_b32_e64 v33, v234, v20, s[38:39]
	s_waitcnt lgkmcnt(3)
	v_add_f32_e32 v20, v22, v34
	v_cndmask_b32_e64 v34, v234, v20, s[40:41]
	v_add_f32_e32 v20, v23, v35
	v_cndmask_b32_e64 v35, v234, v20, s[42:43]
	s_waitcnt lgkmcnt(0)
	v_mfma_f32_16x16x32_bf16 v[20:23], v[28:31], v[8:11], v[24:27]
	v_add_lshl_u32 v188, s0, v84, 7
	s_nop 1
	v_exp_f32_e32 v24, v32
	v_exp_f32_e32 v27, v35
	s_nop 2
	v_add_f32_e32 v20, v20, v120
	v_add_f32_e32 v21, v21, v121
	v_cndmask_b32_e64 v20, v234, v20, s[44:45]
	v_cndmask_b32_e64 v21, v234, v21, s[46:47]
	v_exp_f32_e32 v25, v20
	v_exp_f32_e32 v20, v33
	v_exp_f32_e32 v26, v21
	v_exp_f32_e32 v21, v34
	v_add_f32_e32 v22, v22, v122
	v_add_f32_e32 v23, v23, v123
	v_cndmask_b32_e64 v22, v234, v22, s[48:49]
	v_cndmask_b32_e64 v23, v234, v23, s[50:51]
	v_exp_f32_e32 v28, v22
	v_exp_f32_e32 v23, v23
	v_cvt_pk_bf16_f32 v20, v24, v20
	v_cvt_pk_bf16_f32 v21, v21, v27
	v_cvt_pk_bf16_f32 v22, v25, v26
	ds_read_b64_tr_b16 v[26:27], v97 offset:2304
	ds_read_b64_tr_b16 v[24:25], v97
	v_cvt_pk_bf16_f32 v23, v28, v23
	ds_read_b64_tr_b16 v[30:31], v97 offset:2336
	ds_read_b64_tr_b16 v[28:29], v97 offset:32
	ds_read_b64_tr_b16 v[32:33], v97 offset:64
	ds_read_b64_tr_b16 v[120:121], v97 offset:96
	ds_read_b64_tr_b16 v[34:35], v97 offset:2368
	ds_read_b64_tr_b16 v[122:123], v97 offset:2400
	s_waitcnt lgkmcnt(6)
	v_mfma_f32_16x16x32_bf16 v[108:111], v[24:27], v[20:23], v[108:111]
	v_lshl_add_u64 v[24:25], v[74:75], 0, v[188:189]
	v_lshl_add_u64 v[26:27], v[76:77], 0, v[188:189]
	v_add_lshl_u32 v188, s0, v85, 7
	global_load_dwordx4 v[128:131], v[24:25], off
	global_load_dwordx4 v[132:135], v[26:27], off
	v_lshl_add_u64 v[24:25], v[74:75], 0, v[188:189]
	v_lshl_add_u64 v[26:27], v[76:77], 0, v[188:189]
	global_load_dwordx4 v[136:139], v[24:25], off
	global_load_dwordx4 v[140:143], v[26:27], off
	s_waitcnt vmcnt(14)
	ds_write_b128 v95, v[44:47]
	ds_write_b128 v95, v[36:39] offset:4608
	s_waitcnt vmcnt(12)
	ds_write_b128 v95, v[60:63] offset:1152
	ds_write_b128 v95, v[52:55] offset:5760
	s_waitcnt vmcnt(10)
	ds_write_b128 v95, v[144:147] offset:2304
	ds_write_b128 v95, v[124:127] offset:6912
	s_waitcnt vmcnt(8)
	ds_write_b128 v95, v[152:155] offset:3456
	ds_write_b128 v95, v[148:151] offset:8064
	s_waitcnt lgkmcnt(12)
	v_mfma_f32_16x16x32_bf16 v[112:115], v[28:31], v[20:23], v[112:115]
	ds_read_b128 v[28:31], v96 offset:4608
	ds_read_b128 v[36:39], v96 offset:4672
	s_add_i32 s0, s55, 0x140
	v_mfma_f32_16x16x32_bf16 v[100:103], v[16:19], v[20:23], v[100:103]
	v_add_u32_e32 v52, 0x3514, v71
	v_add_u32_e32 v53, 0x3554, v71
	v_add_u32_e32 v54, 0x355c, v71
	s_waitcnt lgkmcnt(11)
	v_mfma_f32_16x16x32_bf16 v[116:119], v[32:35], v[20:23], v[116:119]
	s_waitcnt lgkmcnt(10)
	v_mfma_f32_16x16x32_bf16 v[104:107], v[120:123], v[20:23], v[104:107]
	v_or_b32_e32 v20, s0, v82
	v_lshlrev_b32_e32 v188, 7, v20
	v_lshl_add_u64 v[20:21], v[74:75], 0, v[188:189]
	s_waitcnt lgkmcnt(1)
	v_mfma_f32_16x16x32_bf16 v[44:47], v[28:31], v[4:7], v[12:15]
	v_lshl_add_u64 v[24:25], v[76:77], 0, v[188:189]
	v_add_lshl_u32 v188, s0, v83, 7
	v_lshl_add_u64 v[32:33], v[74:75], 0, v[188:189]
	v_lshl_add_u64 v[34:35], v[76:77], 0, v[188:189]
	global_load_dwordx4 v[20:23], v[20:21], off
	s_nop 0
	global_load_dwordx4 v[24:27], v[24:25], off
	s_nop 0
	global_load_dwordx4 v[28:31], v[32:33], off
	s_nop 0
	global_load_dwordx4 v[32:35], v[34:35], off
	s_waitcnt lgkmcnt(0)
	v_mfma_f32_16x16x32_bf16 v[36:39], v[36:39], v[8:11], v[44:47]
	ds_read2_b32 v[60:61], v52 offset1:1
	v_add_lshl_u32 v188, s0, v84, 7
	s_nop 0
	ds_read_b128 v[44:47], v96 offset:6912
	v_add_u32_e32 v52, 0x351c, v71
	ds_read2_b32 v[62:63], v52 offset1:1
	ds_read2_b32 v[120:121], v53 offset1:1
	ds_read2_b32 v[122:123], v54 offset1:1
	ds_read_b128 v[52:55], v96 offset:6976
	s_waitcnt lgkmcnt(5)
	v_add_f32_e32 v36, v36, v60
	s_waitcnt lgkmcnt(4)
; #define LAS __attribute__((address_space(3)))
; #define MFMA16(a, b, c) __builtin_amdgcn_mfma_f32_16x16x32_bf16((a), (b), (c), 0, 0, 0)
; DI float ex2(float x) { return __builtin_amdgcn_exp2f(x); }
; DI s16x4 vtr(const LAS char* p) { return __builtin_bit_cast(s16x4, __builtin_amdgcn_ds_read_tr16_b64_v4i16((LAS s16x4*)p)); }
; DI bf16x8 cat8(s16x4 lo, s16x4 hi) { return __builtin_shufflevector(lo, hi, 0, 1, 2, 3, 4, 5, 6, 7); }
; DI bf16x8 pack8(f32x4 a, f32x4 b) { u32x4 w; w.x = pk2(a[0], a[1]); w.y = pk2(a[2], a[3]); w.z = pk2(b[0], b[1]); w.w = pk2(b[2], b[3]); return __builtin_bit_cast(bf16x8, w); }
; DI bf16x8 k_frag(const LAS char* vt, int t, int ks, int lane) { return k_frag_at(vt + KT_OFF, t, ks, lane); }
; DI void fb_update(f32x4 (&o)[4], f32x4& ol, const f32x4 st0, const f32x4 st1, const LAS char* vt, int lane) {
;     f32x4 p0, p1;
; #pragma unroll
;     for (int i = 0; i < 4; ++i) { p0[i] = ex2(st0[i]); p1[i] = ex2(st1[i]); }
;     const bf16x8 pf = pack8(p0, p1);
;     const bf16x8 ones = {0x3F80, 0x3F80, 0x3F80, 0x3F80, 0x3F80, 0x3F80, 0x3F80, 0x3F80};
;     ol = MFMA16(ones, pf, ol);
;     const int g = lane >> 4, q = (lane & 15) >> 2, p = lane & 3;
;     const LAS char* v0 = vt + (4 * g + q) * VT_PITCH + 8 * p;
;     const LAS char* v1 = v0 + 16 * VT_PITCH;
; #pragma unroll
;     for (int c = 0; c < 4; ++c) { const bf16x8 vf = cat8(vtr(v0 + 32 * c), vtr(v1 + 32 * c)); o[c] = MFMA16(vf, pf, o[c]); }
; }
; DI void d_compute(f32x4 (&o)[4], f32x4& ol, const TileRegs& R, const bf16x8 (&qf)[2], const f32x4 cinit, int kr, int kc0, const LAS float* rpl, LAS char* vt, int lane) {
;     tile_v_to_lds(R, vt, lane);
;     const LAS float* rr_ = rpl + kr * 31;
;     f32x4 st[2];
; #pragma unroll
;     for (int t = 0; t < 2; ++t) {
;         st[t] = MFMA16(k_frag(vt, t, 0, lane), qf[0], cinit); st[t] = MFMA16(k_frag(vt, t, 1, lane), qf[1], st[t]);
; #pragma unroll
;         for (int i = 0; i < 4; ++i) { const bool ok = (unsigned)(kc0 + 16 * t + i) <= 15u;
;             const float v = st[t][i] + rr_[16 * t + i];
;             st[t][i] = ok ? v : -1e30f; }
;     }
;     fb_update(o, ol, st[0], st[1], vt, lane);
;     asm volatile("" ::: "memory");
; }
	v_mfma_f32_16x16x32_bf16 v[44:47], v[44:47], v[4:7], v[12:15]
	v_cndmask_b32_e64 v60, v234, v36, s[36:37]
	v_add_f32_e32 v36, v37, v61
	v_cndmask_b32_e64 v61, v234, v36, s[38:39]
	s_waitcnt lgkmcnt(3)
	v_add_f32_e32 v36, v38, v62
	v_cndmask_b32_e64 v62, v234, v36, s[40:41]
	v_add_f32_e32 v36, v39, v63
	v_cndmask_b32_e64 v63, v234, v36, s[42:43]
	s_waitcnt lgkmcnt(0)
	v_mfma_f32_16x16x32_bf16 v[36:39], v[52:55], v[8:11], v[44:47]
	s_nop 2
	v_exp_f32_e32 v44, v60
	v_exp_f32_e32 v47, v63
	s_nop 2
	v_add_f32_e32 v36, v36, v120
	v_add_f32_e32 v37, v37, v121
	v_cndmask_b32_e64 v36, v234, v36, s[44:45]
	v_cndmask_b32_e64 v37, v234, v37, s[46:47]
	v_add_f32_e32 v38, v38, v122
	v_add_f32_e32 v39, v39, v123
	v_exp_f32_e32 v45, v36
	v_exp_f32_e32 v36, v61
	v_exp_f32_e32 v46, v37
	v_exp_f32_e32 v37, v62
	v_cndmask_b32_e64 v38, v234, v38, s[48:49]
	v_cndmask_b32_e64 v39, v234, v39, s[50:51]
	v_exp_f32_e32 v52, v38
	v_exp_f32_e32 v39, v39
	v_cvt_pk_bf16_f32 v36, v44, v36
	v_cvt_pk_bf16_f32 v37, v37, v47
	v_cvt_pk_bf16_f32 v38, v45, v46
	ds_read_b64_tr_b16 v[46:47], v97 offset:2304
	ds_read_b64_tr_b16 v[44:45], v97
	v_cvt_pk_bf16_f32 v39, v52, v39
	s_nop 1
	v_mfma_f32_16x16x32_bf16 v[60:63], v[16:19], v[36:39], v[100:103]
	ds_read_b64_tr_b16 v[54:55], v97 offset:2336
	ds_read_b64_tr_b16 v[52:53], v97 offset:32
	s_nop 0
	ds_read_b64_tr_b16 v[100:101], v97 offset:64
	ds_read_b64_tr_b16 v[120:121], v97 offset:96
	ds_read_b64_tr_b16 v[102:103], v97 offset:2368
	ds_read_b64_tr_b16 v[122:123], v97 offset:2400
	s_waitcnt lgkmcnt(6)
	v_mfma_f32_16x16x32_bf16 v[108:111], v[44:47], v[36:39], v[108:111]
	v_lshl_add_u64 v[44:45], v[74:75], 0, v[188:189]
	v_lshl_add_u64 v[46:47], v[76:77], 0, v[188:189]
	v_add_lshl_u32 v188, s0, v85, 7
	global_load_dwordx4 v[124:127], v[44:45], off
	global_load_dwordx4 v[144:147], v[46:47], off
	v_lshl_add_u64 v[44:45], v[74:75], 0, v[188:189]
	s_waitcnt lgkmcnt(1)
	v_mfma_f32_16x16x32_bf16 v[100:103], v[100:103], v[36:39], v[116:119]
	v_lshl_add_u64 v[46:47], v[76:77], 0, v[188:189]
	s_nop 1
	global_load_dwordx4 v[116:119], v[44:45], off
	global_load_dwordx4 v[148:151], v[46:47], off
	s_waitcnt vmcnt(14)
	ds_write_b128 v95, v[48:51]
	ds_write_b128 v95, v[40:43] offset:4608
	s_waitcnt vmcnt(12)
	ds_write_b128 v95, v[64:67] offset:1152
	ds_write_b128 v95, v[56:59] offset:5760
	s_waitcnt vmcnt(10)
	ds_write_b128 v95, v[132:135] offset:2304
	ds_write_b128 v95, v[128:131] offset:6912
	s_waitcnt vmcnt(8)
	ds_write_b128 v95, v[140:143] offset:3456
	ds_write_b128 v95, v[136:139] offset:8064
	ds_read_b128 v[40:43], v96 offset:4608
	ds_read_b128 v[64:67], v96 offset:4672
	s_add_i32 s0, s55, 0x180
	v_or_b32_e32 v44, s0, v82
	s_waitcnt lgkmcnt(1)
	v_mfma_f32_16x16x32_bf16 v[40:43], v[40:43], v[4:7], v[12:15]
	v_lshlrev_b32_e32 v188, 7, v44
	v_lshl_add_u64 v[44:45], v[74:75], 0, v[188:189]
	v_lshl_add_u64 v[48:49], v[76:77], 0, v[188:189]
	v_add_lshl_u32 v188, s0, v83, 7
	v_mfma_f32_16x16x32_bf16 v[112:115], v[52:55], v[36:39], v[112:115]
	v_lshl_add_u64 v[52:53], v[74:75], 0, v[188:189]
	v_lshl_add_u64 v[56:57], v[76:77], 0, v[188:189]
	global_load_dwordx4 v[44:47], v[44:45], off
	s_nop 0
	global_load_dwordx4 v[48:51], v[48:49], off
	v_mfma_f32_16x16x32_bf16 v[36:39], v[120:123], v[36:39], v[104:107]
	global_load_dwordx4 v[52:55], v[52:53], off
	s_nop 0
	global_load_dwordx4 v[56:59], v[56:57], off
	ds_read2_b32 v[120:121], v73 offset1:1
	v_add_u32_e32 v104, 0x35d0, v71
	s_waitcnt lgkmcnt(1)
	v_mfma_f32_16x16x32_bf16 v[40:43], v[64:67], v[8:11], v[40:43]
	ds_read_b128 v[64:67], v96 offset:6912
	v_add_u32_e32 v73, 0x3598, v71
	v_add_u32_e32 v105, 0x35d8, v71
	ds_read2_b32 v[122:123], v73 offset1:1
	ds_read2_b32 v[128:129], v104 offset1:1
	ds_read2_b32 v[130:131], v105 offset1:1
	ds_read_b128 v[104:107], v96 offset:6976
	s_waitcnt lgkmcnt(5)
	v_add_f32_e32 v40, v40, v120
	s_waitcnt lgkmcnt(4)
	v_mfma_f32_16x16x32_bf16 v[64:67], v[64:67], v[4:7], v[12:15]
	v_cndmask_b32_e64 v73, v234, v40, s[36:37]
	v_add_f32_e32 v40, v41, v121
	v_cndmask_b32_e64 v120, v234, v40, s[38:39]
	s_waitcnt lgkmcnt(3)
	v_add_f32_e32 v40, v42, v122
	v_cndmask_b32_e64 v121, v234, v40, s[40:41]
	v_add_f32_e32 v40, v43, v123
	v_cndmask_b32_e64 v122, v234, v40, s[42:43]
	s_waitcnt lgkmcnt(0)
	v_mfma_f32_16x16x32_bf16 v[40:43], v[104:107], v[8:11], v[64:67]
	v_add_lshl_u32 v188, s0, v84, 7
	s_addk_i32 s55, 0x1c0
	v_lshl_add_u64 v[132:133], v[76:77], 0, v[188:189]
	v_exp_f32_e32 v64, v73
	v_exp_f32_e32 v67, v122
	s_nop 2
	v_add_f32_e32 v40, v40, v128
	v_add_f32_e32 v41, v41, v129
	v_cndmask_b32_e64 v40, v234, v40, s[44:45]
	v_cndmask_b32_e64 v41, v234, v41, s[46:47]
	v_exp_f32_e32 v65, v40
	v_exp_f32_e32 v40, v120
	v_exp_f32_e32 v66, v41
	v_exp_f32_e32 v41, v121
	v_add_f32_e32 v42, v42, v130
	v_add_f32_e32 v43, v43, v131
	v_cndmask_b32_e64 v42, v234, v42, s[48:49]
	v_cndmask_b32_e64 v43, v234, v43, s[50:51]
	v_exp_f32_e32 v73, v42
	v_exp_f32_e32 v43, v43
	v_cvt_pk_bf16_f32 v40, v64, v40
	v_cvt_pk_bf16_f32 v41, v41, v67
	v_cvt_pk_bf16_f32 v42, v65, v66
	ds_read_b64_tr_b16 v[66:67], v97 offset:2304
	ds_read_b64_tr_b16 v[64:65], v97
	ds_read_b64_tr_b16 v[106:107], v97 offset:2336
	ds_read_b64_tr_b16 v[104:105], v97 offset:32
	ds_read_b64_tr_b16 v[120:121], v97 offset:64
	ds_read_b64_tr_b16 v[128:129], v97 offset:96
	ds_read_b64_tr_b16 v[122:123], v97 offset:2368
	ds_read_b64_tr_b16 v[130:131], v97 offset:2400
	v_cvt_pk_bf16_f32 v43, v73, v43
	v_add_u32_e32 v73, s55, v83
	v_min_u32_e32 v73, 0x7ff, v73
	s_waitcnt lgkmcnt(6)
	v_mfma_f32_16x16x32_bf16 v[64:67], v[64:67], v[40:43], v[108:111]
	s_nop 2
	v_lshl_add_u64 v[108:109], v[74:75], 0, v[188:189]
	v_add_lshl_u32 v188, s0, v85, 7
	s_waitcnt lgkmcnt(0)
; #define LAS __attribute__((address_space(3)))
; #define MFMA16(a, b, c) __builtin_amdgcn_mfma_f32_16x16x32_bf16((a), (b), (c), 0, 0, 0)
; DI bf16x8 k_frag(const LAS char* vt, int t, int ks, int lane) { return k_frag_at(vt + KT_OFF, t, ks, lane); }
; DI void tile_load(TileRegs& R, const bf16* kb, const bf16* vb, int tokbase, int stride, int lane) {
; #pragma unroll
;     for (int it = 0; it < 4; ++it) { const int n = lane + 64 * it, row = n >> 3, ch = n & 7; int tok = tokbase + stride * row; tok = min(max(tok, 0), T - 1);
;         R.k[it] = *(const u32x4*)(kb + (size_t)tok * 64 + ch * 8); R.v[it] = *(const u32x4*)(vb + (size_t)tok * 64 + ch * 8); }
; }
; DI void d_compute(f32x4 (&o)[4], f32x4& ol, const TileRegs& R, const bf16x8 (&qf)[2], const f32x4 cinit, int kr, int kc0, const LAS float* rpl, LAS char* vt, int lane) {
;     tile_v_to_lds(R, vt, lane);
;     const LAS float* rr_ = rpl + kr * 31;
;     f32x4 st[2];
; #pragma unroll
;     for (int t = 0; t < 2; ++t) {
;         st[t] = MFMA16(k_frag(vt, t, 0, lane), qf[0], cinit); st[t] = MFMA16(k_frag(vt, t, 1, lane), qf[1], st[t]);
; #pragma unroll
;         for (int i = 0; i < 4; ++i) { const bool ok = (unsigned)(kc0 + 16 * t + i) <= 15u;
;             const float v = st[t][i] + rr_[16 * t + i];
;             st[t][i] = ok ? v : -1e30f; }
;     }
;     fb_update(o, ol, st[0], st[1], vt, lane);
;     asm volatile("" ::: "memory");
; }
	v_mfma_f32_16x16x32_bf16 v[128:131], v[128:131], v[40:43], v[36:39]
	v_lshl_add_u64 v[134:135], v[76:77], 0, v[188:189]
	s_mov_b64 s[0:1], 0x7800000
	s_nop 0
	v_or_b32_e32 v36, s55, v82
	v_mfma_f32_16x16x32_bf16 v[104:107], v[104:107], v[40:43], v[112:115]
	global_load_dwordx4 v[108:111], v[108:109], off
	s_nop 1
	global_load_dwordx4 v[112:115], v[132:133], off
	v_lshl_add_u64 v[132:133], v[74:75], 0, v[188:189]
	v_lshlrev_b32_e32 v188, 7, v36
	v_mfma_f32_16x16x32_bf16 v[60:63], v[16:19], v[40:43], v[60:63]
	v_lshl_add_u64 v[36:37], v[74:75], 0, v[188:189]
	v_mfma_f32_16x16x32_bf16 v[100:103], v[120:123], v[40:43], v[100:103]
	global_load_dwordx4 v[120:123], v[132:133], off
	s_nop 0
	global_load_dwordx4 v[132:135], v[134:135], off
	v_lshl_add_u64 v[40:41], v[76:77], 0, v[188:189]
	global_load_dwordx4 v[36:39], v[36:37], off
	s_nop 0
	global_load_dwordx4 v[40:43], v[40:41], off
	s_waitcnt vmcnt(16)
	ds_write_b128 v95, v[24:27]
	ds_write_b128 v95, v[20:23] offset:4608
	s_waitcnt vmcnt(14)
	ds_write_b128 v95, v[32:35] offset:1152
	ds_write_b128 v95, v[28:31] offset:5760
	s_waitcnt vmcnt(12)
	ds_write_b128 v95, v[144:147] offset:2304
	ds_write_b128 v95, v[124:127] offset:6912
	s_waitcnt vmcnt(10)
	ds_write_b128 v95, v[148:151] offset:3456
	ds_write_b128 v95, v[116:119] offset:8064
	ds_read_b128 v[24:27], v96 offset:4608
	v_lshlrev_b32_e32 v188, 7, v73
	v_lshl_add_u64 v[136:137], v[74:75], 0, v[188:189]
	v_add_u32_e32 v32, s55, v84
	v_lshl_add_u64 v[138:139], v[76:77], 0, v[188:189]
	global_load_dwordx4 v[20:23], v[136:137], off
	global_load_dwordx4 v[28:31], v[138:139], off
	v_min_u32_e32 v73, 0x7ff, v32
	ds_read_b128 v[32:35], v96 offset:4672
	s_waitcnt lgkmcnt(1)
	v_mfma_f32_16x16x32_bf16 v[24:27], v[24:27], v[4:7], v[12:15]
	v_lshlrev_b32_e32 v188, 7, v73
	v_lshl_add_u64 v[116:117], v[74:75], 0, v[188:189]
	v_lshl_add_u64 v[124:125], v[76:77], 0, v[188:189]
	v_add_u32_e32 v136, 0x360c, v71
	global_load_dwordx4 v[116:119], v[116:117], off
	s_nop 0
	global_load_dwordx4 v[124:127], v[124:125], off
	s_waitcnt lgkmcnt(0)
	v_mfma_f32_16x16x32_bf16 v[24:27], v[32:35], v[8:11], v[24:27]
	ds_read2_b32 v[140:141], v136 offset1:1
	ds_read_b128 v[32:35], v96 offset:6912
	v_add_u32_e32 v136, 0x3614, v71
	v_add_u32_e32 v137, 0x364c, v71
	v_add_u32_e32 v138, 0x3654, v71
	ds_read2_b32 v[142:143], v136 offset1:1
	ds_read2_b32 v[144:145], v137 offset1:1
	ds_read2_b32 v[146:147], v138 offset1:1
	ds_read_b128 v[136:139], v96 offset:6976
	s_waitcnt lgkmcnt(5)
	v_add_f32_e32 v24, v24, v140
	s_waitcnt lgkmcnt(4)
	v_mfma_f32_16x16x32_bf16 v[32:35], v[32:35], v[4:7], v[12:15]
	v_cndmask_b32_e64 v140, v234, v24, s[36:37]
	v_add_f32_e32 v24, v25, v141
	v_cndmask_b32_e64 v141, v234, v24, s[38:39]
	s_waitcnt lgkmcnt(3)
	v_add_f32_e32 v24, v26, v142
	v_cndmask_b32_e64 v142, v234, v24, s[40:41]
	v_add_f32_e32 v24, v27, v143
	v_cndmask_b32_e64 v143, v234, v24, s[42:43]
	s_waitcnt lgkmcnt(0)
	v_mfma_f32_16x16x32_bf16 v[24:27], v[136:139], v[8:11], v[32:35]
	v_add_u32_e32 v73, s55, v85
	s_nop 1
	v_exp_f32_e32 v32, v140
	v_exp_f32_e32 v35, v143
	s_nop 2
	v_add_f32_e32 v24, v24, v144
	v_add_f32_e32 v25, v25, v145
	v_cndmask_b32_e64 v24, v234, v24, s[44:45]
	v_cndmask_b32_e64 v25, v234, v25, s[46:47]
	v_exp_f32_e32 v33, v24
	v_exp_f32_e32 v24, v141
	v_exp_f32_e32 v34, v25
	v_exp_f32_e32 v25, v142
	v_add_f32_e32 v26, v26, v146
	v_add_f32_e32 v27, v27, v147
	v_cndmask_b32_e64 v26, v234, v26, s[48:49]
	v_cndmask_b32_e64 v27, v234, v27, s[50:51]
	v_exp_f32_e32 v136, v26
	v_exp_f32_e32 v27, v27
	v_cvt_pk_bf16_f32 v24, v32, v24
	v_cvt_pk_bf16_f32 v25, v25, v35
	v_cvt_pk_bf16_f32 v26, v33, v34
	ds_read_b64_tr_b16 v[34:35], v97 offset:2304
	ds_read_b64_tr_b16 v[32:33], v97
	v_cvt_pk_bf16_f32 v27, v136, v27
	ds_read_b64_tr_b16 v[138:139], v97 offset:2336
	ds_read_b64_tr_b16 v[136:137], v97 offset:32
	ds_read_b64_tr_b16 v[140:141], v97 offset:64
	ds_read_b64_tr_b16 v[144:145], v97 offset:96
	ds_read_b64_tr_b16 v[142:143], v97 offset:2368
	ds_read_b64_tr_b16 v[146:147], v97 offset:2400
	s_waitcnt lgkmcnt(6)
	v_mfma_f32_16x16x32_bf16 v[32:35], v[32:35], v[24:27], v[64:67]
	s_nop 2
	v_min_u32_e32 v64, 0x7ff, v73
	v_lshlrev_b32_e32 v188, 7, v64
	v_lshl_add_u64 v[74:75], v[74:75], 0, v[188:189]
	s_waitcnt lgkmcnt(4)
	v_mfma_f32_16x16x32_bf16 v[64:67], v[136:139], v[24:27], v[104:107]
	v_mov_b32_e32 v73, v189
	s_nop 1
	v_lshl_add_u64 v[104:105], v[76:77], 0, v[188:189]
	global_load_dwordx4 v[74:77], v[74:75], off
	s_nop 0
	global_load_dwordx4 v[104:107], v[104:105], off
	s_waitcnt vmcnt(14)
	ds_write_b128 v95, v[48:51]
	ds_write_b128 v95, v[44:47] offset:4608
	s_waitcnt vmcnt(12)
	ds_write_b128 v95, v[56:59] offset:1152
	ds_write_b128 v95, v[52:55] offset:5760
	s_waitcnt vmcnt(10)
	ds_write_b128 v95, v[112:115] offset:2304
	ds_write_b128 v95, v[108:111] offset:6912
	s_waitcnt vmcnt(8)
	ds_write_b128 v95, v[132:135] offset:3456
	ds_write_b128 v95, v[120:123] offset:8064
	ds_read_b128 v[44:47], v96 offset:4608
	ds_read_b128 v[48:51], v96 offset:4672
	v_add_u32_e32 v52, 0x3688, v71
	ds_read2_b32 v[56:57], v52 offset1:1
	s_waitcnt lgkmcnt(2)
	v_mfma_f32_16x16x32_bf16 v[44:47], v[44:47], v[4:7], v[12:15]
	v_add_u32_e32 v52, 0x3690, v71
	v_add_u32_e32 v53, 0x36c8, v71
	v_add_u32_e32 v54, 0x36d0, v71
	s_waitcnt lgkmcnt(1)
	v_mfma_f32_16x16x32_bf16 v[44:47], v[48:51], v[8:11], v[44:47]
	ds_read_b128 v[48:51], v96 offset:6912
	ds_read2_b32 v[58:59], v52 offset1:1
	ds_read2_b32 v[108:109], v53 offset1:1
	ds_read2_b32 v[110:111], v54 offset1:1
	ds_read_b128 v[52:55], v96 offset:6976
	s_waitcnt lgkmcnt(5)
	s_nop 1
	v_add_f32_e32 v44, v44, v56
	s_waitcnt lgkmcnt(4)
; #define LAS __attribute__((address_space(3)))
; #define MFMA16(a, b, c) __builtin_amdgcn_mfma_f32_16x16x32_bf16((a), (b), (c), 0, 0, 0)
; DI bf16x8 k_frag(const LAS char* vt, int t, int ks, int lane) { return k_frag_at(vt + KT_OFF, t, ks, lane); }
; DI void d_compute(f32x4 (&o)[4], f32x4& ol, const TileRegs& R, const bf16x8 (&qf)[2], const f32x4 cinit, int kr, int kc0, const LAS float* rpl, LAS char* vt, int lane) {
;     tile_v_to_lds(R, vt, lane);
;     const LAS float* rr_ = rpl + kr * 31;
;     f32x4 st[2];
; #pragma unroll
;     for (int t = 0; t < 2; ++t) {
;         st[t] = MFMA16(k_frag(vt, t, 0, lane), qf[0], cinit); st[t] = MFMA16(k_frag(vt, t, 1, lane), qf[1], st[t]);
; #pragma unroll
;         for (int i = 0; i < 4; ++i) { const bool ok = (unsigned)(kc0 + 16 * t + i) <= 15u;
;             const float v = st[t][i] + rr_[16 * t + i];
;             st[t][i] = ok ? v : -1e30f; }
;     }
;     fb_update(o, ol, st[0], st[1], vt, lane);
;     asm volatile("" ::: "memory");
; }
; DI void mixerD2_unit(int u, const bf16* PROJ, bf16* YC, float rmax, const float* kmax_l, LAS char* vt, int wave, int lane) {
;     ...
;     d_compute(o, ol, R0, qf, cinit, 6, kc0, rpl, vt, lane);
;     d_compute(o, ol, R1, qf, cinit, 7, kc0, rpl, vt, lane);
;     const float inv = 1.f / ol[0];
;     LAS char* sc = vt + SC_OFF; const int tok0 = 64 * rr + 16 * cb;
;     u32x2 gv[4];
;     rows16_load(sc, slab(PROJ, C_DG + h * 64, b), 64, tok0, 1, lane);
; #pragma unroll
;     for (int c = 0; c < 4; ++c) gv[c] = *(const LAS u32x2*)(sc + r * VT_PITCH + (16 * c + 4 * g) * 2);
	v_mfma_f32_16x16x32_bf16 v[48:51], v[48:51], v[4:7], v[12:15]
	v_cndmask_b32_e64 v56, v234, v44, s[36:37]
	v_add_f32_e32 v44, v45, v57
	v_cndmask_b32_e64 v57, v234, v44, s[38:39]
	s_waitcnt lgkmcnt(3)
	v_add_f32_e32 v44, v46, v58
	v_cndmask_b32_e64 v58, v234, v44, s[40:41]
	v_add_f32_e32 v44, v47, v59
	v_cndmask_b32_e64 v59, v234, v44, s[42:43]
	s_waitcnt lgkmcnt(0)
	v_mfma_f32_16x16x32_bf16 v[44:47], v[52:55], v[8:11], v[48:51]
	s_nop 2
	v_exp_f32_e32 v48, v56
	v_exp_f32_e32 v51, v59
	s_nop 2
	v_add_f32_e32 v44, v44, v108
	v_add_f32_e32 v45, v45, v109
	v_add_f32_e32 v46, v46, v110
	v_add_f32_e32 v47, v47, v111
	v_cndmask_b32_e64 v44, v234, v44, s[44:45]
	v_cndmask_b32_e64 v45, v234, v45, s[46:47]
	v_cndmask_b32_e64 v46, v234, v46, s[48:49]
	v_cndmask_b32_e64 v47, v234, v47, s[50:51]
	v_exp_f32_e32 v49, v44
	v_exp_f32_e32 v44, v57
	v_exp_f32_e32 v50, v45
	v_exp_f32_e32 v45, v58
	v_exp_f32_e32 v52, v46
	v_exp_f32_e32 v47, v47
	v_mfma_f32_16x16x32_bf16 v[60:63], v[16:19], v[24:27], v[60:63]
	v_cvt_pk_bf16_f32 v44, v48, v44
	v_cvt_pk_bf16_f32 v45, v45, v51
	v_cvt_pk_bf16_f32 v46, v49, v50
	v_cvt_pk_bf16_f32 v47, v52, v47
	ds_read_b64_tr_b16 v[50:51], v97 offset:2304
	ds_read_b64_tr_b16 v[48:49], v97
	v_mfma_f32_16x16x32_bf16 v[52:55], v[16:19], v[44:47], v[60:63]
	ds_read_b64_tr_b16 v[58:59], v97 offset:2336
	ds_read_b64_tr_b16 v[56:57], v97 offset:32
	s_nop 0
	ds_read_b64_tr_b16 v[60:61], v97 offset:64
	ds_read_b64_tr_b16 v[108:109], v97 offset:96
	ds_read_b64_tr_b16 v[62:63], v97 offset:2368
	ds_read_b64_tr_b16 v[110:111], v97 offset:2400
	s_waitcnt vmcnt(6)
	ds_write_b128 v95, v[40:43]
	ds_write_b128 v95, v[36:39] offset:4608
	s_waitcnt vmcnt(4)
	ds_write_b128 v95, v[28:31] offset:1152
	ds_write_b128 v95, v[20:23] offset:5760
	s_waitcnt vmcnt(2)
	ds_write_b128 v95, v[124:127] offset:2304
	ds_write_b128 v95, v[116:119] offset:6912
	s_waitcnt vmcnt(0)
	ds_write_b128 v95, v[104:107] offset:3456
	ds_write_b128 v95, v[74:77] offset:8064
	ds_read_b128 v[20:23], v96 offset:4608
	ds_read_b128 v[28:31], v96 offset:4672
	v_add_u32_e32 v36, 0x3704, v71
	ds_read2_b32 v[40:41], v36 offset1:1
	s_waitcnt lgkmcnt(2)
	v_mfma_f32_16x16x32_bf16 v[20:23], v[20:23], v[4:7], v[12:15]
	v_add_u32_e32 v36, 0x370c, v71
	v_add_u32_e32 v37, 0x3744, v71
	v_add_u32_e32 v38, 0x374c, v71
	v_mfma_f32_16x16x32_bf16 v[100:103], v[140:143], v[24:27], v[100:103]
	v_mfma_f32_16x16x32_bf16 v[24:27], v[144:147], v[24:27], v[128:131]
	s_waitcnt lgkmcnt(1)
	v_mfma_f32_16x16x32_bf16 v[20:23], v[28:31], v[8:11], v[20:23]
	ds_read_b128 v[28:31], v96 offset:6912
	v_mfma_f32_16x16x32_bf16 v[32:35], v[48:51], v[44:47], v[32:35]
	v_mfma_f32_16x16x32_bf16 v[48:51], v[56:59], v[44:47], v[64:67]
	s_waitcnt lgkmcnt(1)
	s_nop 3
	v_add_f32_e32 v20, v20, v40
	v_add_f32_e32 v21, v21, v41
	v_cndmask_b32_e64 v20, v234, v20, s[36:37]
	v_mfma_f32_16x16x32_bf16 v[56:59], v[60:63], v[44:47], v[100:103]
	v_cndmask_b32_e64 v21, v234, v21, s[38:39]
	v_or_b32_e32 v40, s54, v83
	v_ashrrev_i32_e32 v41, 31, v40
	v_mfma_f32_16x16x32_bf16 v[24:27], v[108:111], v[44:47], v[24:27]
	ds_read2_b32 v[42:43], v36 offset1:1
	ds_read2_b32 v[44:45], v37 offset1:1
	ds_read2_b32 v[46:47], v38 offset1:1
	ds_read_b128 v[36:39], v96 offset:6976
	s_waitcnt lgkmcnt(3)
	v_add_f32_e32 v22, v22, v42
	v_mfma_f32_16x16x32_bf16 v[4:7], v[28:31], v[4:7], v[12:15]
	v_add_u32_e32 v42, v88, v86
	s_nop 1
	v_add_f32_e32 v13, v23, v43
	s_waitcnt lgkmcnt(0)
	v_mfma_f32_16x16x32_bf16 v[4:7], v[36:39], v[8:11], v[4:7]
	v_cndmask_b32_e64 v12, v234, v22, s[40:41]
	v_cndmask_b32_e64 v13, v234, v13, s[42:43]
	v_exp_f32_e32 v10, v12
	v_exp_f32_e32 v11, v13
	s_nop 3
	v_add_f32_e32 v4, v4, v44
	v_add_f32_e32 v5, v5, v45
	v_add_f32_e32 v6, v6, v46
	v_add_f32_e32 v7, v7, v47
	v_cndmask_b32_e64 v4, v234, v4, s[44:45]
	v_cndmask_b32_e64 v5, v234, v5, s[46:47]
	v_cndmask_b32_e64 v6, v234, v6, s[48:49]
	v_cndmask_b32_e64 v7, v234, v7, s[50:51]
	v_exp_f32_e32 v8, v20
	v_exp_f32_e32 v4, v4
	v_exp_f32_e32 v9, v21
	v_exp_f32_e32 v5, v5
	v_exp_f32_e32 v14, v6
	v_exp_f32_e32 v15, v7
	v_cvt_pk_bf16_f32 v7, v10, v11
	ds_read_b64_tr_b16 v[12:13], v97 offset:2304
	ds_read_b64_tr_b16 v[10:11], v97
	v_cvt_pk_bf16_f32 v6, v8, v9
	v_cvt_pk_bf16_f32 v8, v4, v5
	v_cvt_pk_bf16_f32 v9, v14, v15
	v_lshl_add_u64 v[4:5], s[30:31], 0, v[72:73]
	v_lshlrev_b64 v[36:37], 7, v[40:41]
	s_waitcnt lgkmcnt(0)
	v_mfma_f32_16x16x32_bf16 v[10:13], v[10:13], v[6:9], v[32:35]
	s_nop 2
	v_lshl_add_u64 v[32:33], v[4:5], 0, s[0:1]
	v_or_b32_e32 v4, s54, v82
	v_ashrrev_i32_e32 v5, 31, v4
	v_mfma_f32_16x16x32_bf16 v[14:17], v[16:19], v[6:9], v[52:55]
	v_lshlrev_b64 v[34:35], 7, v[4:5]
	ds_read_b64_tr_b16 v[18:19], v97 offset:2336
	s_nop 5
	ds_read_b64_tr_b16 v[16:17], v97 offset:32
	ds_read_b64_tr_b16 v[20:21], v97 offset:64
	ds_read_b64_tr_b16 v[28:29], v97 offset:96
	ds_read_b64_tr_b16 v[22:23], v97 offset:2368
	ds_read_b64_tr_b16 v[30:31], v97 offset:2400
	v_lshl_add_u64 v[34:35], v[32:33], 0, v[34:35]
	v_lshl_add_u64 v[36:37], v[32:33], 0, v[36:37]
	global_load_dwordx4 v[32:35], v[34:35], off
	s_nop 0
	global_load_dwordx4 v[36:39], v[36:37], off
	s_waitcnt vmcnt(1)
	ds_write_b128 v42, v[32:35] offset:9216
	s_waitcnt vmcnt(0)
	ds_write_b128 v98, v[36:39] offset:9216
	v_div_scale_f32 v32, s[0:1], v14, v14, 1.0
	v_rcp_f32_e32 v33, v32
	v_add_u32_e32 v15, v87, v68
	v_add_u32_e32 v38, 0x2000, v15
	s_waitcnt lgkmcnt(6)
; #define LAS __attribute__((address_space(3)))
; DI unsigned pk2(float lo, float hi) { f32x2_t v = {lo, hi}; bf16x2_t b = __builtin_convertvector(v, bf16x2_t); return __builtin_bit_cast(unsigned, b); }
; DI float silu_f(float x) { return x * __builtin_amdgcn_rcpf(1.f + __expf(-x)); }
; DI void mixerD2_unit(int u, const bf16* PROJ, bf16* YC, float rmax, const float* kmax_l, LAS char* vt, int wave, int lane) {
;     ...
;     const float inv = 1.f / ol[0];
;     LAS char* sc = vt + SC_OFF; const int tok0 = 64 * rr + 16 * cb;
;     u32x2 gv[4];
;     rows16_load(sc, slab(PROJ, C_DG + h * 64, b), 64, tok0, 1, lane);
; #pragma unroll
;     for (int c = 0; c < 4; ++c) gv[c] = *(const LAS u32x2*)(sc + r * VT_PITCH + (16 * c + 4 * g) * 2);
; #pragma unroll
;     for (int c = 0; c < 4; ++c) { const f32x4 ov = o[c] * inv;
;         u32x2 w; w.x = pk2(ov[0] * silu_f(bflo(gv[c].x)), ov[1] * silu_f(bfhi(gv[c].x))); w.y = pk2(ov[2] * silu_f(bflo(gv[c].y)), ov[3] * silu_f(bfhi(gv[c].y)));
;         *(LAS u32x2*)(sc + r * VT_PITCH + (16 * c + 4 * g) * 2) = w; }
;     rows16_store(sc, YC + (size_t)b * T * 1024 + 768 + h * 64, 1024, tok0, 1, lane);
; __global__ void __launch_bounds__(512) fwd_kernel(Args a) {
;     ...
;                 for (int u = blockIdx.x; u < 512; u += G) { const int hd = (u >> 4) & 3; if (hd != hcur) { rmax = d_stage_rpb(a.in[14] + l * 4 * 15 * 31, hd, vt, lane); hcur = hd; }
;                     mixerD2_unit(u, PROJ, YC, rmax, KMAX + l * 1024, vt, wave, lane); } }
	v_mfma_f32_16x16x32_bf16 v[16:19], v[16:19], v[6:9], v[48:51]
	v_fma_f32 v15, -v32, v33, 1.0
	v_fmac_f32_e32 v33, v15, v33
	v_div_scale_f32 v15, vcc, 1.0, v14, 1.0
	v_mul_f32_e32 v34, v15, v33
	s_waitcnt lgkmcnt(3)
	v_mfma_f32_16x16x32_bf16 v[20:23], v[20:23], v[6:9], v[56:59]
	v_fma_f32 v35, -v32, v34, v15
	v_fmac_f32_e32 v34, v35, v33
	v_fma_f32 v15, -v32, v34, v15
	s_waitcnt lgkmcnt(2)
	v_mfma_f32_16x16x32_bf16 v[6:9], v[28:31], v[6:9], v[24:27]
	s_nop 2
	ds_read2_b64 v[24:27], v38 offset0:128 offset1:132
	ds_read2_b64 v[28:31], v38 offset0:136 offset1:140
	v_div_fmas_f32 v15, v15, v33, v34
	v_div_fixup_f32 v14, v15, v14, 1.0
	v_pk_mul_f32 v[12:13], v[12:13], v[14:15] op_sel_hi:[1,0]
	s_waitcnt lgkmcnt(1)
	v_lshlrev_b32_e32 v32, 16, v24
	v_and_b32_e32 v33, 0xffff0000, v24
	v_mul_f32_e32 v15, 0xbfb8aa3b, v32
	v_exp_f32_e32 v15, v15
	v_mul_f32_e32 v24, 0xbfb8aa3b, v33
	v_exp_f32_e32 v34, v24
	v_and_b32_e32 v35, 0xffff0000, v25
	v_pk_mul_f32 v[10:11], v[10:11], v[14:15] op_sel_hi:[1,0]
	v_add_f32_e32 v15, 1.0, v15
	v_rcp_f32_e32 v24, v15
	v_add_f32_e32 v15, 1.0, v34
	v_lshlrev_b32_e32 v34, 16, v25
	v_mul_f32_e32 v25, 0xbfb8aa3b, v34
	v_exp_f32_e32 v36, v25
	v_mul_f32_e32 v25, 0xbfb8aa3b, v35
	v_exp_f32_e32 v37, v25
	v_rcp_f32_e32 v25, v15
	v_add_f32_e32 v15, 1.0, v36
	v_rcp_f32_e32 v36, v15
	v_add_f32_e32 v15, 1.0, v37
	v_rcp_f32_e32 v37, v15
	v_pk_mul_f32 v[24:25], v[24:25], v[32:33]
	s_lshl_b64 s[0:1], s[26:27], 22
	v_pk_mul_f32 v[10:11], v[10:11], v[24:25]
	v_pk_mul_f32 v[24:25], v[36:37], v[34:35]
	v_cvt_pk_bf16_f32 v10, v10, v11
	v_pk_mul_f32 v[12:13], v[12:13], v[24:25]
	s_add_u32 s0, s8, s0
	v_cvt_pk_bf16_f32 v11, v12, v13
	v_pk_mul_f32 v[12:13], v[14:15], v[18:19] op_sel_hi:[0,1]
	v_lshlrev_b32_e32 v18, 16, v26
	v_and_b32_e32 v19, 0xffff0000, v26
	v_mul_f32_e32 v15, 0xbfb8aa3b, v18
	v_exp_f32_e32 v15, v15
	v_mul_f32_e32 v24, 0xbfb8aa3b, v19
	v_exp_f32_e32 v25, v24
	v_lshlrev_b32_e32 v26, 16, v27
	v_pk_mul_f32 v[16:17], v[14:15], v[16:17] op_sel_hi:[0,1]
	v_add_f32_e32 v15, 1.0, v15
	v_rcp_f32_e32 v24, v15
	v_add_f32_e32 v15, 1.0, v25
	v_and_b32_e32 v27, 0xffff0000, v27
	v_mul_f32_e32 v25, 0xbfb8aa3b, v26
	v_exp_f32_e32 v32, v25
	v_mul_f32_e32 v25, 0xbfb8aa3b, v27
	v_exp_f32_e32 v33, v25
	v_rcp_f32_e32 v25, v15
	v_add_f32_e32 v15, 1.0, v32
	v_rcp_f32_e32 v32, v15
	v_add_f32_e32 v15, 1.0, v33
	v_rcp_f32_e32 v33, v15
	v_pk_mul_f32 v[18:19], v[24:25], v[18:19]
	s_addc_u32 s1, s9, s1
	v_pk_mul_f32 v[16:17], v[16:17], v[18:19]
	v_pk_mul_f32 v[18:19], v[32:33], v[26:27]
	v_cvt_pk_bf16_f32 v16, v16, v17
	v_pk_mul_f32 v[12:13], v[12:13], v[18:19]
	s_lshl_b32 s26, s53, 7
	v_cvt_pk_bf16_f32 v17, v12, v13
	s_waitcnt lgkmcnt(0)
	v_lshlrev_b32_e32 v12, 16, v28
	ds_write2_b64 v38, v[10:11], v[16:17] offset0:128 offset1:132
	v_pk_mul_f32 v[10:11], v[14:15], v[22:23] op_sel_hi:[0,1]
	v_and_b32_e32 v13, 0xffff0000, v28
	v_mul_f32_e32 v15, 0xbfb8aa3b, v12
	v_exp_f32_e32 v15, v15
	v_mul_f32_e32 v16, 0xbfb8aa3b, v13
	v_exp_f32_e32 v19, v16
	s_add_u32 s0, s0, s26
	v_pk_mul_f32 v[16:17], v[14:15], v[20:21] op_sel_hi:[0,1]
	v_add_f32_e32 v15, 1.0, v15
	v_lshlrev_b32_e32 v20, 16, v29
	v_rcp_f32_e32 v18, v15
	v_add_f32_e32 v15, 1.0, v19
	v_and_b32_e32 v21, 0xffff0000, v29
	v_mul_f32_e32 v19, 0xbfb8aa3b, v20
	v_exp_f32_e32 v22, v19
	v_mul_f32_e32 v19, 0xbfb8aa3b, v21
	v_exp_f32_e32 v23, v19
	v_rcp_f32_e32 v19, v15
	v_add_f32_e32 v15, 1.0, v22
	v_rcp_f32_e32 v22, v15
	v_add_f32_e32 v15, 1.0, v23
	v_rcp_f32_e32 v23, v15
	v_pk_mul_f32 v[12:13], v[18:19], v[12:13]
	v_pk_mul_f32 v[8:9], v[14:15], v[8:9] op_sel_hi:[0,1]
	v_pk_mul_f32 v[12:13], v[16:17], v[12:13]
	v_pk_mul_f32 v[16:17], v[22:23], v[20:21]
	v_cvt_pk_bf16_f32 v12, v12, v13
	v_pk_mul_f32 v[10:11], v[10:11], v[16:17]
	v_and_b32_e32 v17, 0xffff0000, v31
	v_cvt_pk_bf16_f32 v13, v10, v11
	v_lshlrev_b32_e32 v10, 16, v30
	v_and_b32_e32 v11, 0xffff0000, v30
	v_mul_f32_e32 v15, 0xbfb8aa3b, v10
	v_mul_f32_e32 v16, 0xbfb8aa3b, v11
	v_exp_f32_e32 v15, v15
	v_exp_f32_e32 v16, v16
	v_mul_f32_e32 v19, 0xbfb8aa3b, v17
	v_exp_f32_e32 v19, v19
	v_pk_mul_f32 v[6:7], v[14:15], v[6:7] op_sel_hi:[0,1]
	v_add_f32_e32 v14, 1.0, v15
	v_add_f32_e32 v15, 1.0, v16
	v_lshlrev_b32_e32 v16, 16, v31
	v_mul_f32_e32 v18, 0xbfb8aa3b, v16
	v_exp_f32_e32 v18, v18
	v_rcp_f32_e32 v14, v14
	v_rcp_f32_e32 v15, v15
	v_add_f32_e32 v19, 1.0, v19
	v_add_f32_e32 v18, 1.0, v18
	v_rcp_f32_e32 v18, v18
	v_rcp_f32_e32 v19, v19
	v_pk_mul_f32 v[10:11], v[14:15], v[10:11]
	s_addc_u32 s1, s1, 0
	v_pk_mul_f32 v[6:7], v[6:7], v[10:11]
	v_pk_mul_f32 v[10:11], v[18:19], v[16:17]
	v_cvt_pk_bf16_f32 v6, v6, v7
	v_pk_mul_f32 v[8:9], v[8:9], v[10:11]
	v_lshl_add_u64 v[14:15], s[0:1], 0, v[72:73]
	v_cvt_pk_bf16_f32 v7, v8, v9
	ds_write2_b64 v38, v[12:13], v[6:7] offset0:136 offset1:140
	ds_read_b128 v[6:9], v42 offset:9216
	ds_read_b128 v[10:13], v98 offset:9216
	v_lshlrev_b64 v[4:5], 11, v[4:5]
	v_lshl_add_u64 v[4:5], v[14:15], 0, v[4:5]
	s_add_i32 s52, s52, 1
	s_waitcnt lgkmcnt(1)
	global_store_dwordx4 v[4:5], v[6:9], off offset:1536
	v_lshlrev_b64 v[4:5], 11, v[40:41]
	v_lshl_add_u64 v[4:5], v[14:15], 0, v[4:5]
	s_bitcmp1_b32 s52, 0
	s_waitcnt lgkmcnt(0)
	global_store_dwordx4 v[4:5], v[10:13], off offset:1536
	s_cbranch_scc0 .LBB0_368

; #define LAS __attribute__((address_space(3)))
; DI float ex2(float x) { return __builtin_amdgcn_exp2f(x); }
; DI float a_bound(const bf16x8 (&qf)[2], const float* kmax_l, int b, int h) { return sqrtf(q_norm2(qf) * (kmax_l[b * 128 + 8 + 2 * h] + kmax_l[b * 128 + 9 + 2 * h])) * 1.01f + 0.05f; }
; #define A_LOAD(R, t_) do { int tb_, sd_, md_; a_desc((t_), a0, rho, tb_, sd_, md_); tile_load(R, kb, vb, tb_, sd_, lane); } while (0)
; #define A_STAGE(S, R, t_) do { int tb_, sd_, md_; a_desc((t_), a0, rho, tb_, sd_, md_); a_stage(S, R, vt, (t_) & 1, qf, cinit, tb_, sd_, md_, tq, nslope2, lane); } while (0)
; #define LAUNDER() int tp = TID0(); const int tid = tp, lane = tp & 63, wave = __builtin_amdgcn_readfirstlane(tp >> 6); (void)tid; (void)lane; (void)wave
; DI void mixerA2_unit(int u, const bf16* PROJ, bf16* YC, const float* LPA, const float* kmax_l, LAS char* vt, int wave, int lane) {
;     const int b = u >> 6, h = (u >> 4) & 3, rho = u & 15, a0 = 16 * wave, r = lane & 15, g = lane >> 4;
;     const bf16* kb = slab(PROJ, C_AK + h * 64, b); const bf16* vb = slab(PROJ, C_AV + h * 64, b);
;     const int tq = 16 * (a0 + r) + rho;
;     bf16x8 qf[2];
; #pragma unroll
;     for (int ks = 0; ks < 2; ++ks) qf[ks] = *(const bf16x8*)(slab(PROJ, C_AQ + h * 64, b) + (size_t)tq * 64 + 32 * ks + 8 * g);
;     const float nslope2 = -ex2(-(float)(2 * h + 1)) * LOG2E;
;     const float bound = a_bound(qf, kmax_l, b, h);
;     const f32x4 cinit = {-bound, -bound, -bound, -bound};
;     f32x4 o[4], ol = {0.f, 0.f, 0.f, 0.f};
; #pragma unroll
;     for (int c = 0; c < 4; ++c) o[c] = ol;
;     TileRegs R0, R1, R2;
;     ...
;     A_LOAD(R0, 0); A_LOAD(R1, 1); A_LOAD(R2, 2);
;     f32x4 sA[2], sB[2];
;     ...
;     A_STAGE(sA, R0, 0); A_LOAD(R0, 3);
; __global__ void __launch_bounds__(512) fwd_kernel(Args a) {
;     ...
;         if (IN(pb + 3) && EN_A) { LAUNDER(); LAS char* vt = (LAS char*)lds + wave * 16384;
;             for (int u = blockIdx.x; u < 512; u += G) { mixerA2_unit(u, PROJ, YC, LPA, KMAX + l * 1024, vt, wave, lane); } }
.Lsw_a2:
	v_readlane_b32 s0, v253, 0
	v_mbcnt_lo_u32_b32 v4, -1, 0
	v_mbcnt_hi_u32_b32 v4, -1, v4
	s_waitcnt lgkmcnt(0)
	s_nop 0
	v_add_u32_e32 v5, s0, v4
	v_readlane_b32 s0, v254, 31
	v_readlane_b32 s1, v254, 32
	s_andn2_b64 vcc, exec, s[0:1]
	v_readfirstlane_b32 s0, v5
	s_cbranch_vccnz .LBB0_423
	v_writelane_b32 v255, s26, 35
	s_ashr_i32 s2, s0, 6
	s_lshl_b32 s0, s2, 14
	v_writelane_b32 v255, s27, 36
	s_add_i32 s4, s0, 0
	v_readlane_b32 s0, v255, 27
	v_readlane_b32 s1, v255, 28
	s_lshl_b32 s34, s0, 10
	s_lshl_b64 s[0:1], s[34:35], 2
	v_readlane_b32 s20, v253, 42
	v_readlane_b32 s21, v253, 43
	s_add_u32 s60, s20, s0
	s_addc_u32 s61, s21, s1
	v_and_b32_e32 v7, 15, v4
	v_bfe_u32 v8, v4, 4, 2
	s_lshl_b32 s62, s2, 8
	v_lshl_or_b32 v149, v7, 4, s62
	v_lshlrev_b32_e32 v167, 6, v8
	v_lshlrev_b32_e32 v148, 3, v8
	v_sub_u32_e32 v8, v167, v149
	v_mov_b32_e32 v14, s4
	s_movk_i32 s0, 0x90
	v_mad_u32_u24 v169, v7, s0, v14
	v_add_u32_e32 v7, 0x400, v8
	v_cmp_gt_u32_e64 s[36:37], s14, v7
	v_add_u32_e32 v7, 16, v8
	v_cvt_f32_i32_e32 v171, v7
	v_add_u32_e32 v7, 32, v8
	v_and_b32_e32 v9, 64, v224
	v_add_u32_e32 v15, 0x410, v8
	v_cvt_f32_i32_e32 v172, v7
	v_add_u32_e32 v7, 48, v8
	s_add_i32 s63, s62, 0xffffff00
	s_add_i32 s64, s62, 0xffffff80
	v_xor_b32_e32 v6, 16, v224
	v_add_u32_e32 v9, 64, v9
	v_cmp_gt_u32_e64 s[38:39], s14, v15
	v_add_u32_e32 v15, 0x420, v8
	v_cvt_f32_i32_e32 v173, v7
	v_add_u32_e32 v7, 0x100, v8
	s_cmpk_lt_u32 s63, 0x800
	v_cmp_lt_i32_e32 vcc, v6, v9
	v_cmp_gt_u32_e64 s[40:41], s14, v15
	v_add_u32_e32 v15, 0x430, v8
	v_cvt_f32_i32_e32 v174, v7
	v_add_u32_e32 v7, 0x110, v8
	s_cselect_b64 s[54:55], -1, 0
	s_cmpk_lt_u32 s64, 0x800
	v_cndmask_b32_e32 v6, v224, v6, vcc
	v_cmp_gt_u32_e64 s[42:43], s14, v15
	v_add_u32_e32 v15, 0x500, v8
	v_cvt_f32_i32_e32 v175, v7
	v_add_u32_e32 v7, 0x120, v8
	s_cselect_b64 s[90:91], -1, 0
	s_add_i32 s65, s62, 0x100
	v_lshlrev_b32_e32 v160, 2, v6
	v_xor_b32_e32 v6, 32, v224
	v_cmp_gt_u32_e64 s[44:45], s14, v15
	v_add_u32_e32 v15, 0x510, v8
	v_cvt_f32_i32_e32 v176, v7
	v_add_u32_e32 v7, 0x130, v8
	s_cmpk_lt_u32 s62, 0x800
	v_and_b32_e32 v5, 63, v4
	v_cmp_lt_i32_e32 vcc, v6, v9
	v_bfe_u32 v9, v4, 3, 3
	v_lshlrev_b32_e32 v13, 4, v4
	v_cvt_f32_i32_e32 v170, v8
	v_cmp_gt_u32_e64 s[46:47], s14, v15
	v_add_u32_e32 v15, 0x520, v8
	v_add_u32_e32 v8, 0x530, v8
	v_cvt_f32_i32_e32 v177, v7
	s_cselect_b64 s[20:21], -1, 0
	s_add_i32 s68, s62, 0x180
	v_cndmask_b32_e32 v6, v224, v6, vcc
	v_lshlrev_b32_e32 v5, 3, v5
	v_or_b32_e32 v10, 8, v9
	v_and_b32_e32 v13, 0x70, v13
	v_cmp_gt_u32_e64 s[50:51], s14, v8
	v_bfe_u32 v7, v4, 2, 4
	s_cmpk_lt_u32 s65, 0x800
	v_and_b32_e32 v8, 7, v4
	v_lshlrev_b32_e32 v161, 2, v6
	v_and_b32_e32 v6, 56, v5
	v_or_b32_e32 v11, 16, v9
	v_or_b32_e32 v12, 24, v9
	v_add_u32_e32 v13, s4, v13
	v_mul_u32_u24_e32 v166, 0x90, v9
	v_and_b32_e32 v168, 48, v4
	v_mad_u32_u24 v7, v7, s0, v14
	v_and_b32_e32 v5, 24, v5
	s_mov_b64 s[56:57], s[96:97]
	s_cselect_b64 s[96:97], -1, 0
	s_cmpk_lt_u32 s68, 0x800
	v_lshlrev_b32_e32 v4, 3, v8
	v_lshl_add_u32 v182, v8, 4, s4
	v_mul_u32_u24_e32 v8, 0x90, v10
	v_lshlrev_b32_e32 v162, 4, v9
	v_lshlrev_b32_e32 v163, 4, v10
	v_lshlrev_b32_e32 v164, 4, v11
	v_lshlrev_b32_e32 v165, 4, v12
	v_cmp_gt_u32_e64 s[48:49], s14, v15
	v_lshlrev_b32_e32 v178, 2, v9
	v_lshlrev_b32_e32 v179, 2, v10
	v_lshlrev_b32_e32 v180, 2, v11
	v_lshlrev_b32_e32 v181, 2, v12
	s_cselect_b64 s[26:27], -1, 0
	v_lshlrev_b32_e32 v150, 1, v6
	v_add_u32_e32 v183, v13, v166
	v_add_u32_e32 v184, v7, v5
	v_lshlrev_b32_e32 v152, 1, v4
	v_add_u32_e32 v185, v182, v8
	v_readlane_b32 s69, v255, 40
	s_lshl_b32 s69, s69, 1
	s_movk_i32 s58, 0x7bc
	s_movk_i32 s67, 0x7fc
	s_movk_i32 s59, 0x7b8
	s_movk_i32 s52, 0x7b4
.LBB0_421:
	s_ashr_i32 s94, s69, 6
	s_bfe_u32 s2, s69, 0x20004
	s_and_b32 s5, s69, 15
	s_ashr_i32 s95, s94, 31
	s_lshl_b32 s0, s2, 21
	s_add_u32 s4, s10, s0
	s_addc_u32 s16, s11, 0
	s_lshl_b64 s[0:1], s[94:95], 18
	v_or_b32_e32 v154, s5, v149
	s_add_u32 s30, s4, s0
	v_ashrrev_i32_e32 v155, 31, v154
	s_addc_u32 s31, s16, s1
	v_lshlrev_b64 v[4:5], 7, v[154:155]
	v_lshl_add_u64 v[4:5], s[30:31], 0, v[4:5]
	v_lshlrev_b32_e32 v188, 1, v148
	v_lshl_add_u64 v[4:5], v[4:5], 0, v[188:189]
	global_load_dwordx4 v[8:11], v[4:5], off
	s_nop 0
	global_load_dwordx4 v[4:7], v[4:5], off offset:64
	s_lshl_b32 s0, s2, 1
	s_or_b32 s1, s0, 1
	v_cvt_f32_ubyte0_e32 v12, s1
	v_exp_f32_e64 v18, -v12
	s_lshl_b32 s1, s94, 7
	s_or_b32 s0, s0, s1
	s_ashr_i32 s1, s0, 31
	s_lshl_b64 s[0:1], s[0:1], 2
	s_add_u32 s0, s60, s0
	s_addc_u32 s1, s61, s1
	v_mov_b32_e32 v151, v189
	v_mul_f32_e32 v153, 0xbfb8aa3b, v18
	s_or_b32 s4, s5, 0x600
	s_or_b32 s33, s5, s64
	s_lshl_b32 s34, s2, 2
	s_waitcnt vmcnt(0)
	v_and_b32_e32 v14, 0xffff0000, v8
	v_and_b32_e32 v15, 0xffff0000, v4
	v_lshlrev_b32_e32 v13, 16, v4
	v_lshlrev_b32_e32 v12, 16, v8
	v_pk_mul_f32 v[14:15], v[14:15], v[14:15]
	v_and_b32_e32 v17, 0xffff0000, v5
	v_and_b32_e32 v16, 0xffff0000, v9
	v_pk_fma_f32 v[12:13], v[12:13], v[12:13], v[14:15]
	v_lshlrev_b32_e32 v15, 16, v5
	v_lshlrev_b32_e32 v14, 16, v9
	v_pk_mul_f32 v[16:17], v[16:17], v[16:17]
	s_nop 0
	v_pk_fma_f32 v[14:15], v[14:15], v[14:15], v[16:17]
	v_and_b32_e32 v17, 0xffff0000, v6
	v_and_b32_e32 v16, 0xffff0000, v10
	v_pk_add_f32 v[12:13], v[12:13], v[14:15]
	v_lshlrev_b32_e32 v15, 16, v6
	v_lshlrev_b32_e32 v14, 16, v10
	v_pk_mul_f32 v[16:17], v[16:17], v[16:17]
	s_nop 0
	v_pk_fma_f32 v[14:15], v[14:15], v[14:15], v[16:17]
	v_and_b32_e32 v17, 0xffff0000, v7
	v_and_b32_e32 v16, 0xffff0000, v11
	v_pk_add_f32 v[12:13], v[14:15], v[12:13]
	v_lshlrev_b32_e32 v15, 16, v7
	v_lshlrev_b32_e32 v14, 16, v11
	v_pk_mul_f32 v[16:17], v[16:17], v[16:17]
	s_nop 0
	v_pk_fma_f32 v[14:15], v[14:15], v[14:15], v[16:17]
	global_load_dwordx2 v[16:17], v189, s[0:1] offset:32
	v_pk_add_f32 v[12:13], v[14:15], v[12:13]
	s_waitcnt vmcnt(0)
; DI float q_norm2(const bf16x8 (&qf)[2]) { float a = sumsq8(qf[0]) + sumsq8(qf[1]); a += __shfl_xor(a, 16); a += __shfl_xor(a, 32); return a; }
; DI void a_desc(int ti, int a0, int rho, int& tokbase, int& stride, int& maxd) {
;     if (ti < 4) { stride = 16; tokbase = rho + 512 * ti; maxd = 1024; }
;     else if (ti < 10) { stride = 4; const int m0 = 4 * a0 + (rho >> 2) - 64 + 32 * (ti - 4); tokbase = 4 * m0 + (rho & 3); maxd = 256; }
;     else { stride = 1; tokbase = 16 * a0 + rho - 64 + 32 * (ti - 10); maxd = 64; }
; }
; template <bool EDGE>
; DI void a_scores(f32x4 (&st)[2], const LAS char* kt, const bf16x8 (&qf)[2], const f32x4 cinit, int tokbase, int stride, int maxd, int tq, float nslope2, int lane) {
;     const int g = lane >> 4;
;     const int base0 = tokbase + stride * 4 * g - tq;
; #pragma unroll
;     for (int t = 0; t < 2; ++t) {
;         st[t] = MFMA16(k_frag_at(kt, t, 0, lane), qf[0], cinit); st[t] = MFMA16(k_frag_at(kt, t, 1, lane), qf[1], st[t]);
; #pragma unroll
;         for (int i = 0; i < 4; ++i) { const int d = base0 + stride * (16 * t + i);
;             bool ok = (unsigned)(d + maxd) <= (unsigned)(2 * maxd);
;             if (EDGE) ok = ok && ((unsigned)(d + tq) < (unsigned)T);
;             const float v = __builtin_fmaf(__builtin_fabsf((float)d), nslope2, st[t][i]);
;             st[t][i] = ok ? v : -1e30f; }
;     }
; }
; DI void a_stage(f32x4 (&st)[2], const TileRegs& R, LAS char* vt, int vpar, const bf16x8 (&qf)[2], const f32x4 cinit, int tokbase, int stride, int maxd, int tq, float nslope2, int lane) {
; #pragma unroll
;     for (int it = 0; it < 4; ++it) { const int n = lane + 64 * it, row = n >> 3, ch = n & 7;
;         *(LAS u32x4*)(vt + vpar * A_V1 + row * VT_PITCH + ch * 16) = R.v[it]; *(LAS u32x4*)(vt + A_K + row * VT_PITCH + ch * 16) = R.k[it]; }
;     a_scores<true>(st, vt + A_K, qf, cinit, tokbase, stride, maxd, tq, nslope2, lane);
; }
; DI void mixerA2_unit(int u, const bf16* PROJ, bf16* YC, const float* LPA, const float* kmax_l, LAS char* vt, int wave, int lane) {
;     ...
;     const float bound = a_bound(qf, kmax_l, b, h);
;     const f32x4 cinit = {-bound, -bound, -bound, -bound};
;     f32x4 o[4], ol = {0.f, 0.f, 0.f, 0.f};
; #pragma unroll
;     for (int c = 0; c < 4; ++c) o[c] = ol;
;     TileRegs R0, R1, R2;
;     ...
;     A_LOAD(R0, 0); A_LOAD(R1, 1); A_LOAD(R2, 2);
;     f32x4 sA[2], sB[2];
	v_mov_b32_e32 v14, v17
	v_add_f32_e32 v12, v12, v13
	ds_bpermute_b32 v13, v160, v12
	s_waitcnt lgkmcnt(0)
	v_add_f32_e32 v13, v12, v13
	ds_bpermute_b32 v15, v161, v13
	v_mov_b32_e32 v12, v16
	v_lshl_add_u64 v[16:17], s[30:31], 0, v[150:151]
	v_add_u32_e32 v151, v169, v168
	s_waitcnt lgkmcnt(0)
	v_pk_add_f32 v[12:13], v[12:13], v[14:15]
	s_nop 0
	v_mul_f32_e32 v12, v12, v13
	v_cmp_gt_f32_e32 vcc, s92, v12
	v_mul_f32_e32 v13, 0x4f800000, v12
	s_nop 0
	v_cndmask_b32_e32 v12, v12, v13, vcc
	v_sqrt_f32_e32 v13, v12
	s_nop 0
	v_add_u32_e32 v14, -1, v13
	v_fma_f32 v15, -v14, v13, v12
	v_cmp_ge_f32_e64 s[0:1], 0, v15
	v_add_u32_e32 v15, 1, v13
	s_nop 0
	v_cndmask_b32_e64 v14, v13, v14, s[0:1]
	v_fma_f32 v13, -v15, v13, v12
	v_cmp_lt_f32_e64 s[0:1], 0, v13
	s_nop 1
	v_cndmask_b32_e64 v13, v14, v15, s[0:1]
	s_mov_b64 s[0:1], 0x800000
	v_lshl_add_u64 v[156:157], v[16:17], 0, s[0:1]
	s_mov_b64 s[0:1], 0x1000000
	v_lshl_add_u64 v[158:159], v[16:17], 0, s[0:1]
	v_or_b32_e32 v16, s5, v162
	v_lshlrev_b32_e32 v188, 7, v16
	v_lshl_add_u64 v[16:17], v[156:157], 0, v[188:189]
	global_load_dwordx4 v[52:55], v[16:17], off
	v_lshl_add_u64 v[16:17], v[158:159], 0, v[188:189]
	global_load_dwordx4 v[56:59], v[16:17], off
	v_or_b32_e32 v16, s5, v163
	v_lshlrev_b32_e32 v188, 7, v16
	v_lshl_add_u64 v[16:17], v[156:157], 0, v[188:189]
	global_load_dwordx4 v[60:63], v[16:17], off
	v_lshl_add_u64 v[16:17], v[158:159], 0, v[188:189]
	global_load_dwordx4 v[64:67], v[16:17], off
	v_or_b32_e32 v16, s5, v164
	v_lshlrev_b32_e32 v188, 7, v16
	v_lshl_add_u64 v[16:17], v[156:157], 0, v[188:189]
	global_load_dwordx4 v[68:71], v[16:17], off
	v_lshl_add_u64 v[16:17], v[158:159], 0, v[188:189]
	global_load_dwordx4 v[72:75], v[16:17], off
	v_or_b32_e32 v16, s5, v165
	v_lshlrev_b32_e32 v188, 7, v16
	v_lshl_add_u64 v[16:17], v[156:157], 0, v[188:189]
	global_load_dwordx4 v[76:79], v[16:17], off
	v_lshl_add_u64 v[16:17], v[158:159], 0, v[188:189]
	global_load_dwordx4 v[80:83], v[16:17], off
	s_or_b32 s0, s5, 0x200
	v_or_b32_e32 v16, s0, v162
	v_lshlrev_b32_e32 v188, 7, v16
	v_lshl_add_u64 v[16:17], v[156:157], 0, v[188:189]
	v_lshl_add_u64 v[20:21], v[158:159], 0, v[188:189]
	global_load_dwordx4 v[16:19], v[16:17], off
	s_or_b32 s1, s5, 0x400
	global_load_dwordx4 v[84:87], v[20:21], off
	v_or_b32_e32 v20, s0, v163
	v_lshlrev_b32_e32 v188, 7, v20
	v_lshl_add_u64 v[20:21], v[156:157], 0, v[188:189]
	global_load_dwordx4 v[88:91], v[20:21], off
	v_lshl_add_u64 v[20:21], v[158:159], 0, v[188:189]
	global_load_dwordx4 v[92:95], v[20:21], off
	v_or_b32_e32 v20, s0, v164
	v_lshlrev_b32_e32 v188, 7, v20
	v_lshl_add_u64 v[20:21], v[156:157], 0, v[188:189]
	global_load_dwordx4 v[96:99], v[20:21], off
	v_lshl_add_u64 v[20:21], v[158:159], 0, v[188:189]
	global_load_dwordx4 v[100:103], v[20:21], off
	v_or_b32_e32 v20, s0, v165
	v_lshlrev_b32_e32 v188, 7, v20
	v_lshl_add_u64 v[20:21], v[156:157], 0, v[188:189]
	global_load_dwordx4 v[104:107], v[20:21], off
	v_lshl_add_u64 v[20:21], v[158:159], 0, v[188:189]
	global_load_dwordx4 v[108:111], v[20:21], off
	v_or_b32_e32 v20, s1, v162
	v_lshlrev_b32_e32 v188, 7, v20
	v_or_b32_e32 v28, s1, v163
	v_lshl_add_u64 v[20:21], v[156:157], 0, v[188:189]
	v_lshl_add_u64 v[24:25], v[158:159], 0, v[188:189]
	v_lshlrev_b32_e32 v188, 7, v28
	v_or_b32_e32 v36, s1, v164
	v_lshl_add_u64 v[28:29], v[156:157], 0, v[188:189]
	v_lshl_add_u64 v[32:33], v[158:159], 0, v[188:189]
	v_lshlrev_b32_e32 v188, 7, v36
	v_or_b32_e32 v44, s1, v165
	v_lshl_add_u64 v[36:37], v[156:157], 0, v[188:189]
	v_lshl_add_u64 v[40:41], v[158:159], 0, v[188:189]
	v_lshlrev_b32_e32 v188, 7, v44
	v_lshl_add_u64 v[44:45], v[156:157], 0, v[188:189]
	v_lshl_add_u64 v[48:49], v[158:159], 0, v[188:189]
	global_load_dwordx4 v[20:23], v[20:21], off
	v_mul_f32_e32 v14, 0x37800000, v13
	global_load_dwordx4 v[24:27], v[24:25], off
	v_cndmask_b32_e32 v13, v13, v14, vcc
	global_load_dwordx4 v[28:31], v[28:29], off
	v_cmp_class_f32_e32 vcc, v12, v226
	global_load_dwordx4 v[32:35], v[32:33], off
	s_nop 0
	global_load_dwordx4 v[36:39], v[36:37], off
	v_cndmask_b32_e32 v12, v13, v12, vcc
	global_load_dwordx4 v[40:43], v[40:41], off
	v_fmamk_f32 v12, v12, 0x3f8147ae, v227
	global_load_dwordx4 v[44:47], v[44:45], off
	v_xor_b32_e32 v12, 0x80000000, v12
	global_load_dwordx4 v[48:51], v[48:49], off
	s_waitcnt vmcnt(22)
	ds_write_b128 v183, v[56:59]
	ds_write_b128 v183, v[52:55] offset:9216
	s_waitcnt vmcnt(20)
	ds_write_b128 v183, v[64:67] offset:1152
	ds_write_b128 v183, v[60:63] offset:10368
	s_waitcnt vmcnt(18)
	ds_write_b128 v183, v[72:75] offset:2304
	ds_write_b128 v183, v[68:71] offset:11520
	s_waitcnt vmcnt(16)
	ds_write_b128 v183, v[80:83] offset:3456
	ds_write_b128 v183, v[76:79] offset:12672
	ds_read_b128 v[52:55], v151 offset:9216
	ds_read_b128 v[56:59], v151 offset:9280
	v_mov_b32_e32 v13, v12
	v_mov_b32_e32 v14, v12
	v_mov_b32_e32 v15, v12
	v_or_b32_e32 v60, s4, v163
	v_or_b32_e32 v68, s4, v164
	s_waitcnt lgkmcnt(1)
	v_mfma_f32_16x16x32_bf16 v[52:55], v[52:55], v[8:11], v[12:15]
	v_or_b32_e32 v76, s4, v165
	s_waitcnt lgkmcnt(0)
	v_mfma_f32_16x16x32_bf16 v[52:55], v[56:59], v[4:7], v[52:55]
	ds_read_b128 v[56:59], v151 offset:11584
	s_nop 6
	v_fma_f32 v52, |v170|, v153, v52
	v_cndmask_b32_e64 v116, v234, v52, s[36:37]
	v_fma_f32 v52, |v171|, v153, v53
	v_cndmask_b32_e64 v117, v234, v52, s[38:39]
	v_fma_f32 v52, |v172|, v153, v54
	v_cndmask_b32_e64 v118, v234, v52, s[40:41]
	v_fma_f32 v52, |v173|, v153, v55
	v_cndmask_b32_e64 v119, v234, v52, s[42:43]
	ds_read_b128 v[52:55], v151 offset:11520
	s_waitcnt lgkmcnt(0)
; #define LAS __attribute__((address_space(3)))
; #define MFMA16(a, b, c) __builtin_amdgcn_mfma_f32_16x16x32_bf16((a), (b), (c), 0, 0, 0)
; #define A_LOAD(R, t_) do { int tb_, sd_, md_; a_desc((t_), a0, rho, tb_, sd_, md_); tile_load(R, kb, vb, tb_, sd_, lane); } while (0)
; #define A_STAGE(S, R, t_) do { int tb_, sd_, md_; a_desc((t_), a0, rho, tb_, sd_, md_); a_stage(S, R, vt, (t_) & 1, qf, cinit, tb_, sd_, md_, tq, nslope2, lane); } while (0)
; template <bool EDGE>
; DI void a_scores(f32x4 (&st)[2], const LAS char* kt, const bf16x8 (&qf)[2], const f32x4 cinit, int tokbase, int stride, int maxd, int tq, float nslope2, int lane) {
;     const int g = lane >> 4;
;     const int base0 = tokbase + stride * 4 * g - tq;
; #pragma unroll
;     for (int t = 0; t < 2; ++t) {
;         st[t] = MFMA16(k_frag_at(kt, t, 0, lane), qf[0], cinit); st[t] = MFMA16(k_frag_at(kt, t, 1, lane), qf[1], st[t]);
; #pragma unroll
;         for (int i = 0; i < 4; ++i) { const int d = base0 + stride * (16 * t + i);
;             bool ok = (unsigned)(d + maxd) <= (unsigned)(2 * maxd);
;             if (EDGE) ok = ok && ((unsigned)(d + tq) < (unsigned)T);
;             const float v = __builtin_fmaf(__builtin_fabsf((float)d), nslope2, st[t][i]);
;             st[t][i] = ok ? v : -1e30f; }
;     }
; }
; DI void a_stage(f32x4 (&st)[2], const TileRegs& R, LAS char* vt, int vpar, const bf16x8 (&qf)[2], const f32x4 cinit, int tokbase, int stride, int maxd, int tq, float nslope2, int lane) {
; #pragma unroll
;     for (int it = 0; it < 4; ++it) { const int n = lane + 64 * it, row = n >> 3, ch = n & 7;
;         *(LAS u32x4*)(vt + vpar * A_V1 + row * VT_PITCH + ch * 16) = R.v[it]; *(LAS u32x4*)(vt + A_K + row * VT_PITCH + ch * 16) = R.k[it]; }
;     a_scores<true>(st, vt + A_K, qf, cinit, tokbase, stride, maxd, tq, nslope2, lane);
; }
; DI void mixerA2_unit(int u, const bf16* PROJ, bf16* YC, const float* LPA, const float* kmax_l, LAS char* vt, int wave, int lane) {
;     ...
;     A_LOAD(R0, 0); A_LOAD(R1, 1); A_LOAD(R2, 2);
;     f32x4 sA[2], sB[2];
;     ...
;     A_STAGE(sA, R0, 0); A_LOAD(R0, 3);
;     A_STAGE(sB, R1, 1); A_LOAD(R1, 4);
;     fb_update(o, ol, sA[0], sA[1], vt, lane);
	v_mfma_f32_16x16x32_bf16 v[52:55], v[52:55], v[8:11], v[12:15]
	v_mfma_f32_16x16x32_bf16 v[52:55], v[56:59], v[4:7], v[52:55]
	s_nop 7
	v_fma_f32 v52, |v174|, v153, v52
	v_cndmask_b32_e64 v120, v234, v52, s[44:45]
	v_fma_f32 v52, |v175|, v153, v53
	v_cndmask_b32_e64 v121, v234, v52, s[46:47]
	v_fma_f32 v52, |v176|, v153, v54
	v_cndmask_b32_e64 v122, v234, v52, s[48:49]
	v_fma_f32 v52, |v177|, v153, v55
	v_cndmask_b32_e64 v123, v234, v52, s[50:51]
	v_or_b32_e32 v52, s4, v162
	v_lshlrev_b32_e32 v188, 7, v52
	v_lshl_add_u64 v[52:53], v[156:157], 0, v[188:189]
	v_lshl_add_u64 v[56:57], v[158:159], 0, v[188:189]
	v_lshlrev_b32_e32 v188, 7, v60
	v_lshl_add_u64 v[60:61], v[156:157], 0, v[188:189]
	v_lshl_add_u64 v[64:65], v[158:159], 0, v[188:189]
	v_lshlrev_b32_e32 v188, 7, v68
	v_lshl_add_u64 v[68:69], v[156:157], 0, v[188:189]
	v_lshl_add_u64 v[72:73], v[158:159], 0, v[188:189]
	v_lshlrev_b32_e32 v188, 7, v76
	v_lshl_add_u64 v[76:77], v[156:157], 0, v[188:189]
	v_lshl_add_u64 v[80:81], v[158:159], 0, v[188:189]
	global_load_dwordx4 v[52:55], v[52:53], off
	s_nop 0
	global_load_dwordx4 v[56:59], v[56:57], off
	s_nop 0
	global_load_dwordx4 v[60:63], v[60:61], off
	s_nop 0
	global_load_dwordx4 v[64:67], v[64:65], off
	s_nop 0
	global_load_dwordx4 v[68:71], v[68:69], off
	s_nop 0
	global_load_dwordx4 v[72:75], v[72:73], off
	s_nop 0
	global_load_dwordx4 v[76:79], v[76:77], off
	s_nop 0
	global_load_dwordx4 v[80:83], v[80:81], off
	s_waitcnt vmcnt(22)
	ds_write_b128 v183, v[84:87] offset:4608
	ds_write_b128 v183, v[16:19] offset:9216
	s_waitcnt vmcnt(20)
	ds_write_b128 v183, v[92:95] offset:5760
	ds_write_b128 v183, v[88:91] offset:10368
	s_waitcnt vmcnt(18)
	ds_write_b128 v183, v[100:103] offset:6912
	ds_write_b128 v183, v[96:99] offset:11520
	s_waitcnt vmcnt(16)
	ds_write_b128 v183, v[108:111] offset:8064
	ds_write_b128 v183, v[104:107] offset:12672
	v_or_b32_e32 v16, s0, v167
	v_sub_u32_e32 v88, v16, v154
	ds_read_b128 v[16:19], v151 offset:9216
	ds_read_b128 v[84:87], v151 offset:9280
	s_waitcnt lgkmcnt(1)
	v_mfma_f32_16x16x32_bf16 v[16:19], v[16:19], v[8:11], v[12:15]
	s_or_b32 s0, s5, s63
	s_waitcnt lgkmcnt(0)
	v_mfma_f32_16x16x32_bf16 v[16:19], v[84:87], v[4:7], v[16:19]
	v_add_u32_e32 v84, 0x400, v88
	v_cmp_gt_u32_e32 vcc, s14, v84
	v_cvt_f32_i32_e32 v84, v88
	s_nop 4
	v_fma_f32 v16, |v84|, v153, v16
	v_cndmask_b32_e32 v128, v234, v16, vcc
	v_add_u32_e32 v16, 16, v88
	v_cvt_f32_i32_e32 v16, v16
	v_add_u32_e32 v84, 0x410, v88
	v_cmp_gt_u32_e32 vcc, s14, v84
	ds_read_b128 v[84:87], v151 offset:11584
	v_fma_f32 v16, |v16|, v153, v17
	v_cndmask_b32_e32 v129, v234, v16, vcc
	v_add_u32_e32 v16, 32, v88
	v_cvt_f32_i32_e32 v16, v16
	v_add_u32_e32 v17, 0x420, v88
	v_cmp_gt_u32_e32 vcc, s14, v17
	v_add_u32_e32 v17, 0x430, v88
	v_fma_f32 v16, |v16|, v153, v18
	v_cndmask_b32_e32 v130, v234, v16, vcc
	v_add_u32_e32 v16, 48, v88
	v_cvt_f32_i32_e32 v16, v16
	v_cmp_gt_u32_e32 vcc, s14, v17
	v_exp_f32_e32 v128, v128
	v_exp_f32_e32 v129, v129
	v_fma_f32 v16, |v16|, v153, v19
	v_cndmask_b32_e32 v131, v234, v16, vcc
	ds_read_b128 v[16:19], v151 offset:11520
	s_waitcnt lgkmcnt(0)
	v_mfma_f32_16x16x32_bf16 v[16:19], v[16:19], v[8:11], v[12:15]
	v_exp_f32_e32 v130, v130
	v_exp_f32_e32 v131, v131
	v_cvt_pk_bf16_f32 v198, v128, v129
	v_mfma_f32_16x16x32_bf16 v[16:19], v[84:87], v[4:7], v[16:19]
	v_add_u32_e32 v84, 0x100, v88
	v_cvt_f32_i32_e32 v84, v84
	v_add_u32_e32 v85, 0x500, v88
	v_cmp_gt_u32_e32 vcc, s14, v85
	v_cvt_pk_bf16_f32 v199, v130, v131
	s_nop 2
	v_fma_f32 v16, |v84|, v153, v16
	v_cndmask_b32_e32 v136, v234, v16, vcc
	v_add_u32_e32 v16, 0x110, v88
	v_cvt_f32_i32_e32 v16, v16
	v_add_u32_e32 v84, 0x510, v88
	v_cmp_gt_u32_e32 vcc, s14, v84
	v_exp_f32_e32 v136, v136
	v_fma_f32 v16, |v16|, v153, v17
	v_cndmask_b32_e32 v137, v234, v16, vcc
	v_add_u32_e32 v16, 0x120, v88
	v_cvt_f32_i32_e32 v16, v16
	v_add_u32_e32 v17, 0x520, v88
	v_cmp_gt_u32_e32 vcc, s14, v17
	v_add_u32_e32 v17, 0x530, v88
	v_fma_f32 v16, |v16|, v153, v18
	v_cndmask_b32_e32 v138, v234, v16, vcc
	v_add_u32_e32 v16, 0x130, v88
	v_cvt_f32_i32_e32 v16, v16
	v_cmp_gt_u32_e32 vcc, s14, v17
	v_exp_f32_e32 v18, v117
	v_exp_f32_e32 v117, v122
	v_fma_f32 v16, |v16|, v153, v19
	v_cndmask_b32_e32 v139, v234, v16, vcc
	v_add_u32_e32 v16, s0, v178
	v_med3_i32 v16, v16, 0, v233
	v_lshlrev_b32_e32 v188, 7, v16
	v_lshl_add_u64 v[16:17], v[156:157], 0, v[188:189]
	global_load_dwordx4 v[84:87], v[16:17], off
	v_lshl_add_u64 v[16:17], v[158:159], 0, v[188:189]
	global_load_dwordx4 v[88:91], v[16:17], off
	v_add_u32_e32 v16, s0, v179
	v_med3_i32 v16, v16, 0, v233
	v_lshlrev_b32_e32 v188, 7, v16
	v_lshl_add_u64 v[16:17], v[156:157], 0, v[188:189]
	global_load_dwordx4 v[92:95], v[16:17], off
	v_lshl_add_u64 v[16:17], v[158:159], 0, v[188:189]
	global_load_dwordx4 v[96:99], v[16:17], off
	v_add_u32_e32 v16, s0, v180
	v_med3_i32 v16, v16, 0, v233
	v_lshlrev_b32_e32 v188, 7, v16
	v_lshl_add_u64 v[16:17], v[156:157], 0, v[188:189]
	global_load_dwordx4 v[100:103], v[16:17], off
	v_lshl_add_u64 v[16:17], v[158:159], 0, v[188:189]
	global_load_dwordx4 v[104:107], v[16:17], off
	v_add_u32_e32 v16, s0, v181
	v_med3_i32 v16, v16, 0, v233
	v_lshlrev_b32_e32 v188, 7, v16
	v_lshl_add_u64 v[16:17], v[156:157], 0, v[188:189]
	global_load_dwordx4 v[108:111], v[16:17], off
	v_lshl_add_u64 v[16:17], v[158:159], 0, v[188:189]
	global_load_dwordx4 v[112:115], v[16:17], off
	v_exp_f32_e32 v16, v116
	v_exp_f32_e32 v17, v120
	v_exp_f32_e32 v19, v121
	v_exp_f32_e32 v116, v118
	v_exp_f32_e32 v118, v119
	v_exp_f32_e32 v119, v123
	ds_read_b64_tr_b16 v[122:123], v184 offset:2304
	ds_read_b64_tr_b16 v[120:121], v184
	ds_read_b64_tr_b16 v[124:125], v184 offset:32
	ds_read_b64_tr_b16 v[126:127], v184 offset:2336
	ds_read_b64_tr_b16 v[132:133], v184 offset:64
	ds_read_b64_tr_b16 v[134:135], v184 offset:2368
	ds_read_b64_tr_b16 v[144:145], v184 offset:96
	ds_read_b64_tr_b16 v[146:147], v184 offset:2400
	s_waitcnt vmcnt(22)
; #define LAS __attribute__((address_space(3)))
; #define MFMA16(a, b, c) __builtin_amdgcn_mfma_f32_16x16x32_bf16((a), (b), (c), 0, 0, 0)
; DI float ex2(float x) { return __builtin_amdgcn_exp2f(x); }
; DI void fb_update(f32x4 (&o)[4], f32x4& ol, const f32x4 st0, const f32x4 st1, const LAS char* vt, int lane) {
;     f32x4 p0, p1;
; #pragma unroll
;     for (int i = 0; i < 4; ++i) { p0[i] = ex2(st0[i]); p1[i] = ex2(st1[i]); }
;     const bf16x8 pf = pack8(p0, p1);
;     const bf16x8 ones = {0x3F80, 0x3F80, 0x3F80, 0x3F80, 0x3F80, 0x3F80, 0x3F80, 0x3F80};
;     ol = MFMA16(ones, pf, ol);
;     const int g = lane >> 4, q = (lane & 15) >> 2, p = lane & 3;
;     const LAS char* v0 = vt + (4 * g + q) * VT_PITCH + 8 * p;
;     const LAS char* v1 = v0 + 16 * VT_PITCH;
; #pragma unroll
;     for (int c = 0; c < 4; ++c) { const bf16x8 vf = cat8(vtr(v0 + 32 * c), vtr(v1 + 32 * c)); o[c] = MFMA16(vf, pf, o[c]); }
; }
; template <bool EDGE>
; DI void a_scores(f32x4 (&st)[2], const LAS char* kt, const bf16x8 (&qf)[2], const f32x4 cinit, int tokbase, int stride, int maxd, int tq, float nslope2, int lane) {
;     const int g = lane >> 4;
;     const int base0 = tokbase + stride * 4 * g - tq;
; #pragma unroll
;     for (int t = 0; t < 2; ++t) {
;         st[t] = MFMA16(k_frag_at(kt, t, 0, lane), qf[0], cinit); st[t] = MFMA16(k_frag_at(kt, t, 1, lane), qf[1], st[t]);
; #pragma unroll
;         for (int i = 0; i < 4; ++i) { const int d = base0 + stride * (16 * t + i);
;             bool ok = (unsigned)(d + maxd) <= (unsigned)(2 * maxd);
;             if (EDGE) ok = ok && ((unsigned)(d + tq) < (unsigned)T);
;             const float v = __builtin_fmaf(__builtin_fabsf((float)d), nslope2, st[t][i]);
;             st[t][i] = ok ? v : -1e30f; }
;     }
; }
; DI void a_stage(f32x4 (&st)[2], const TileRegs& R, LAS char* vt, int vpar, const bf16x8 (&qf)[2], const f32x4 cinit, int tokbase, int stride, int maxd, int tq, float nslope2, int lane) {
; #pragma unroll
;     for (int it = 0; it < 4; ++it) { const int n = lane + 64 * it, row = n >> 3, ch = n & 7;
;         *(LAS u32x4*)(vt + vpar * A_V1 + row * VT_PITCH + ch * 16) = R.v[it]; *(LAS u32x4*)(vt + A_K + row * VT_PITCH + ch * 16) = R.k[it]; }
;     a_scores<true>(st, vt + A_K, qf, cinit, tokbase, stride, maxd, tq, nslope2, lane);
; }
	ds_write_b128 v183, v[24:27]
	ds_write_b128 v183, v[20:23] offset:9216
	s_waitcnt vmcnt(20)
	ds_write_b128 v183, v[32:35] offset:1152
	ds_write_b128 v183, v[28:31] offset:10368
	s_waitcnt vmcnt(18)
	ds_write_b128 v183, v[40:43] offset:2304
	ds_write_b128 v183, v[36:39] offset:11520
	s_waitcnt vmcnt(16)
	ds_write_b128 v183, v[48:51] offset:3456
	ds_write_b128 v183, v[44:47] offset:12672
	v_or_b32_e32 v20, s1, v167
	v_sub_u32_e32 v28, v20, v154
	ds_read_b128 v[20:23], v151 offset:9216
	ds_read_b128 v[24:27], v151 offset:9280
	s_waitcnt lgkmcnt(1)
	v_mfma_f32_16x16x32_bf16 v[20:23], v[20:23], v[8:11], v[12:15]
	v_cvt_pk_bf16_f32 v140, v16, v18
	v_cvt_pk_bf16_f32 v142, v17, v19
	v_mov_b64_e32 v[16:17], s[84:85]
	s_waitcnt lgkmcnt(0)
	v_mfma_f32_16x16x32_bf16 v[20:23], v[24:27], v[4:7], v[20:23]
	v_add_u32_e32 v24, 0x400, v28
	v_mov_b64_e32 v[18:19], s[86:87]
	v_cmp_gt_u32_e32 vcc, s14, v24
	v_cvt_f32_i32_e32 v24, v28
	v_cvt_pk_bf16_f32 v141, v116, v118
	v_cvt_pk_bf16_f32 v143, v117, v119
	v_add_u32_e32 v36, s33, v180
	s_nop 0
	v_fma_f32 v20, |v24|, v153, v20
	v_mfma_f32_16x16x32_bf16 v[116:119], v[16:19], v[140:143], 0
	v_add_u32_e32 v24, 0x410, v28
	v_med3_i32 v36, v36, 0, v233
	v_add_u32_e32 v44, s33, v181
	v_mfma_f32_16x16x32_bf16 v[120:123], v[120:123], v[140:143], 0
	v_exp_f32_e32 v137, v137
	v_exp_f32_e32 v138, v138
	v_exp_f32_e32 v139, v139
	v_mfma_f32_16x16x32_bf16 v[124:127], v[124:127], v[140:143], 0
	v_med3_i32 v44, v44, 0, v233
	v_cvt_pk_bf16_f32 v200, v136, v137
	v_cvt_pk_bf16_f32 v201, v138, v139
	v_mfma_f32_16x16x32_bf16 v[132:135], v[132:135], v[140:143], 0
	v_mfma_f32_16x16x32_bf16 v[140:143], v[144:147], v[140:143], 0
	v_cndmask_b32_e32 v144, v234, v20, vcc
	v_add_u32_e32 v20, 16, v28
	v_cvt_f32_i32_e32 v20, v20
	v_cmp_gt_u32_e32 vcc, s14, v24
	ds_read_b128 v[24:27], v151 offset:11584
	v_mfma_f32_16x16x32_bf16 v[116:119], v[16:19], v[198:201], v[116:119]
	v_fma_f32 v20, |v20|, v153, v21
	v_cndmask_b32_e32 v145, v234, v20, vcc
	v_add_u32_e32 v20, 32, v28
	v_cvt_f32_i32_e32 v20, v20
	v_add_u32_e32 v21, 0x420, v28
	v_cmp_gt_u32_e32 vcc, s14, v21
	v_add_u32_e32 v21, 0x430, v28
	v_fma_f32 v20, |v20|, v153, v22
	v_cndmask_b32_e32 v146, v234, v20, vcc
	v_add_u32_e32 v20, 48, v28
	v_cvt_f32_i32_e32 v20, v20
	v_cmp_gt_u32_e32 vcc, s14, v21
	v_fma_f32 v20, |v20|, v153, v23
	s_nop 0
	v_cndmask_b32_e32 v147, v234, v20, vcc
	ds_read_b128 v[20:23], v151 offset:11520
	s_waitcnt lgkmcnt(0)
	v_mfma_f32_16x16x32_bf16 v[20:23], v[20:23], v[8:11], v[12:15]
	v_mfma_f32_16x16x32_bf16 v[20:23], v[24:27], v[4:7], v[20:23]
	v_add_u32_e32 v24, 0x100, v28
	v_cvt_f32_i32_e32 v24, v24
	v_add_u32_e32 v25, 0x500, v28
	v_cmp_gt_u32_e32 vcc, s14, v25
	s_nop 3
	v_fma_f32 v20, |v24|, v153, v20
	v_cndmask_b32_e32 v155, v234, v20, vcc
	v_add_u32_e32 v20, 0x110, v28
	v_cvt_f32_i32_e32 v20, v20
	v_add_u32_e32 v24, 0x510, v28
	v_cmp_gt_u32_e32 vcc, s14, v24
	v_fma_f32 v20, |v20|, v153, v21
	s_nop 0
	v_cndmask_b32_e32 v186, v234, v20, vcc
	v_add_u32_e32 v20, 0x120, v28
	v_cvt_f32_i32_e32 v20, v20
	v_add_u32_e32 v21, 0x520, v28
	v_cmp_gt_u32_e32 vcc, s14, v21
	v_add_u32_e32 v21, 0x530, v28
	v_fma_f32 v20, |v20|, v153, v22
	v_cndmask_b32_e32 v187, v234, v20, vcc
	v_add_u32_e32 v20, 0x130, v28
	v_cvt_f32_i32_e32 v20, v20
	v_cmp_gt_u32_e32 vcc, s14, v21
	v_add_u32_e32 v28, s33, v179
	v_med3_i32 v28, v28, 0, v233
	v_fma_f32 v20, |v20|, v153, v23
	v_cndmask_b32_e32 v191, v234, v20, vcc
	v_add_u32_e32 v20, s33, v178
	v_med3_i32 v20, v20, 0, v233
	v_lshlrev_b32_e32 v188, 7, v20
	v_lshl_add_u64 v[20:21], v[156:157], 0, v[188:189]
	v_lshl_add_u64 v[24:25], v[158:159], 0, v[188:189]
	v_lshlrev_b32_e32 v188, 7, v28
	v_lshl_add_u64 v[28:29], v[156:157], 0, v[188:189]
	v_lshl_add_u64 v[32:33], v[158:159], 0, v[188:189]
	v_lshlrev_b32_e32 v188, 7, v36
	v_lshl_add_u64 v[36:37], v[156:157], 0, v[188:189]
	v_lshl_add_u64 v[40:41], v[158:159], 0, v[188:189]
	v_lshlrev_b32_e32 v188, 7, v44
	v_lshl_add_u64 v[44:45], v[156:157], 0, v[188:189]
	v_lshl_add_u64 v[48:49], v[158:159], 0, v[188:189]
	global_load_dwordx4 v[20:23], v[20:21], off
	s_nop 0
	global_load_dwordx4 v[24:27], v[24:25], off
	s_nop 0
	global_load_dwordx4 v[28:31], v[28:29], off
	s_nop 0
	global_load_dwordx4 v[32:35], v[32:33], off
	s_nop 0
	global_load_dwordx4 v[36:39], v[36:37], off
	s_nop 0
	global_load_dwordx4 v[40:43], v[40:41], off
	s_nop 0
	global_load_dwordx4 v[44:47], v[44:45], off
	s_nop 0
	global_load_dwordx4 v[48:51], v[48:49], off
	ds_read_b64_tr_b16 v[130:131], v184 offset:6912
	ds_read_b64_tr_b16 v[128:129], v184 offset:4608
	ds_read_b64_tr_b16 v[136:137], v184 offset:4640
	ds_read_b64_tr_b16 v[138:139], v184 offset:6944
	s_waitcnt lgkmcnt(2)
	v_mfma_f32_16x16x32_bf16 v[120:123], v[128:131], v[198:201], v[120:123]
	s_waitcnt lgkmcnt(0)
	v_mfma_f32_16x16x32_bf16 v[128:131], v[136:139], v[198:201], v[124:127]
	s_nop 2
	ds_read_b64_tr_b16 v[124:125], v184 offset:4672
	ds_read_b64_tr_b16 v[126:127], v184 offset:6976
	s_waitcnt lgkmcnt(0)
	v_mfma_f32_16x16x32_bf16 v[136:139], v[124:127], v[198:201], v[132:135]
	ds_read_b64_tr_b16 v[124:125], v184 offset:4704
	ds_read_b64_tr_b16 v[126:127], v184 offset:7008
	s_waitcnt vmcnt(22)
	ds_write_b128 v183, v[56:59] offset:4608
	ds_write_b128 v183, v[52:55] offset:9216
	s_waitcnt vmcnt(20)
	ds_write_b128 v183, v[64:67] offset:5760
	ds_write_b128 v183, v[60:63] offset:10368
	s_waitcnt vmcnt(18)
	ds_write_b128 v183, v[72:75] offset:6912
	ds_write_b128 v183, v[68:71] offset:11520
	s_waitcnt vmcnt(16)
	ds_write_b128 v183, v[80:83] offset:8064
	ds_write_b128 v183, v[76:79] offset:12672
	v_or_b32_e32 v52, s4, v167
	v_sub_u32_e32 v60, v52, v154
	ds_read_b128 v[52:55], v151 offset:9216
	ds_read_b128 v[56:59], v151 offset:9280
	s_waitcnt lgkmcnt(1)
; DI void tile_load(TileRegs& R, const bf16* kb, const bf16* vb, int tokbase, int stride, int lane) {
; #pragma unroll
;     for (int it = 0; it < 4; ++it) { const int n = lane + 64 * it, row = n >> 3, ch = n & 7; int tok = tokbase + stride * row; tok = min(max(tok, 0), T - 1);
;         R.k[it] = *(const u32x4*)(kb + (size_t)tok * 64 + ch * 8); R.v[it] = *(const u32x4*)(vb + (size_t)tok * 64 + ch * 8); }
; }
; DI void tile_v_to_lds(const TileRegs& R, LAS char* vt, int lane) {
; #pragma unroll
;     for (int it = 0; it < 4; ++it) { const int n = lane + 64 * it, row = n >> 3, ch = n & 7;
;         *(LAS u32x4*)(vt + row * VT_PITCH + ch * 16) = R.v[it]; *(LAS u32x4*)(vt + KT_OFF + row * VT_PITCH + ch * 16) = R.k[it]; }
; }
; DI bf16x8 k_frag(const LAS char* vt, int t, int ks, int lane) { return k_frag_at(vt + KT_OFF, t, ks, lane); }
; DI void fb_update(f32x4 (&o)[4], f32x4& ol, const f32x4 st0, const f32x4 st1, const LAS char* vt, int lane) {
;     f32x4 p0, p1;
; #pragma unroll
;     for (int i = 0; i < 4; ++i) { p0[i] = ex2(st0[i]); p1[i] = ex2(st1[i]); }
;     const bf16x8 pf = pack8(p0, p1);
;     const bf16x8 ones = {0x3F80, 0x3F80, 0x3F80, 0x3F80, 0x3F80, 0x3F80, 0x3F80, 0x3F80};
;     ol = MFMA16(ones, pf, ol);
;     const int g = lane >> 4, q = (lane & 15) >> 2, p = lane & 3;
;     const LAS char* v0 = vt + (4 * g + q) * VT_PITCH + 8 * p;
;     const LAS char* v1 = v0 + 16 * VT_PITCH;
; #pragma unroll
;     for (int c = 0; c < 4; ++c) { const bf16x8 vf = cat8(vtr(v0 + 32 * c), vtr(v1 + 32 * c)); o[c] = MFMA16(vf, pf, o[c]); }
; }
; DI float q_norm2(const bf16x8 (&qf)[2]) { float a = sumsq8(qf[0]) + sumsq8(qf[1]); a += __shfl_xor(a, 16); a += __shfl_xor(a, 32); return a; }
; DI void a_desc(int ti, int a0, int rho, int& tokbase, int& stride, int& maxd) {
;     if (ti < 4) { stride = 16; tokbase = rho + 512 * ti; maxd = 1024; }
;     else if (ti < 10) { stride = 4; const int m0 = 4 * a0 + (rho >> 2) - 64 + 32 * (ti - 4); tokbase = 4 * m0 + (rho & 3); maxd = 256; }
;     else { stride = 1; tokbase = 16 * a0 + rho - 64 + 32 * (ti - 10); maxd = 64; }
; }
; template <bool EDGE>
; DI void a_scores(f32x4 (&st)[2], const LAS char* kt, const bf16x8 (&qf)[2], const f32x4 cinit, int tokbase, int stride, int maxd, int tq, float nslope2, int lane) {
;     const int g = lane >> 4;
;     const int base0 = tokbase + stride * 4 * g - tq;
; #pragma unroll
	v_mfma_f32_16x16x32_bf16 v[52:55], v[52:55], v[8:11], v[12:15]
	s_or_b32 s4, s5, s62
	v_add_u32_e32 v68, s4, v180
	v_exp_f32_e32 v132, v146
	s_waitcnt lgkmcnt(0)
	v_mfma_f32_16x16x32_bf16 v[52:55], v[56:59], v[4:7], v[52:55]
	v_add_u32_e32 v56, 0x400, v60
	v_cmp_gt_u32_e32 vcc, s14, v56
	v_cvt_f32_i32_e32 v56, v60
	v_mfma_f32_16x16x32_bf16 v[140:143], v[124:127], v[198:201], v[140:143]
	v_exp_f32_e32 v124, v144
	v_exp_f32_e32 v125, v155
	s_nop 1
	v_fma_f32 v52, |v56|, v153, v52
	v_cndmask_b32_e32 v193, v234, v52, vcc
	v_add_u32_e32 v52, 16, v60
	v_cvt_f32_i32_e32 v52, v52
	v_add_u32_e32 v56, 0x410, v60
	v_cmp_gt_u32_e32 vcc, s14, v56
	ds_read_b128 v[56:59], v151 offset:11584
	v_fma_f32 v52, |v52|, v153, v53
	v_cndmask_b32_e32 v198, v234, v52, vcc
	v_add_u32_e32 v52, 32, v60
	v_cvt_f32_i32_e32 v52, v52
	v_add_u32_e32 v53, 0x420, v60
	v_cmp_gt_u32_e32 vcc, s14, v53
	v_add_u32_e32 v53, 0x430, v60
	v_fma_f32 v52, |v52|, v153, v54
	v_cndmask_b32_e32 v199, v234, v52, vcc
	v_add_u32_e32 v52, 48, v60
	v_cvt_f32_i32_e32 v52, v52
	v_cmp_gt_u32_e32 vcc, s14, v53
	v_exp_f32_e32 v126, v145
	v_exp_f32_e32 v127, v186
	v_fma_f32 v52, |v52|, v153, v55
	v_cndmask_b32_e32 v200, v234, v52, vcc
	ds_read_b128 v[52:55], v151 offset:11520
	s_waitcnt lgkmcnt(0)
	v_mfma_f32_16x16x32_bf16 v[52:55], v[52:55], v[8:11], v[12:15]
	v_exp_f32_e32 v133, v187
	v_exp_f32_e32 v134, v147
	v_exp_f32_e32 v135, v191
	v_mfma_f32_16x16x32_bf16 v[52:55], v[56:59], v[4:7], v[52:55]
	v_add_u32_e32 v56, 0x100, v60
	v_cvt_f32_i32_e32 v56, v56
	v_add_u32_e32 v57, 0x500, v60
	v_cmp_gt_u32_e32 vcc, s14, v57
	v_med3_i32 v68, v68, 0, v233
	s_nop 2
	v_fma_f32 v52, |v56|, v153, v52
	v_cndmask_b32_e32 v201, v234, v52, vcc
	v_add_u32_e32 v52, 0x110, v60
	v_cvt_f32_i32_e32 v52, v52
	v_add_u32_e32 v56, 0x510, v60
	v_cmp_gt_u32_e32 vcc, s14, v56
	v_add_u32_e32 v76, s4, v181
	v_fma_f32 v52, |v52|, v153, v53
	v_cndmask_b32_e32 v202, v234, v52, vcc
	v_add_u32_e32 v52, 0x120, v60
	v_cvt_f32_i32_e32 v52, v52
	v_add_u32_e32 v53, 0x520, v60
	v_cmp_gt_u32_e32 vcc, s14, v53
	v_add_u32_e32 v53, 0x530, v60
	v_fma_f32 v52, |v52|, v153, v54
	v_cndmask_b32_e32 v203, v234, v52, vcc
	v_add_u32_e32 v52, 0x130, v60
	v_cvt_f32_i32_e32 v52, v52
	v_cmp_gt_u32_e32 vcc, s14, v53
	v_add_u32_e32 v60, s4, v179
	v_med3_i32 v60, v60, 0, v233
	v_fma_f32 v52, |v52|, v153, v55
	v_cndmask_b32_e32 v204, v234, v52, vcc
	v_add_u32_e32 v52, s4, v178
	v_med3_i32 v52, v52, 0, v233
	v_lshlrev_b32_e32 v188, 7, v52
	v_lshl_add_u64 v[52:53], v[156:157], 0, v[188:189]
	v_lshl_add_u64 v[56:57], v[158:159], 0, v[188:189]
	v_lshlrev_b32_e32 v188, 7, v60
	v_lshl_add_u64 v[60:61], v[156:157], 0, v[188:189]
	v_lshl_add_u64 v[64:65], v[158:159], 0, v[188:189]
	v_lshlrev_b32_e32 v188, 7, v68
	v_med3_i32 v76, v76, 0, v233
	v_lshl_add_u64 v[68:69], v[156:157], 0, v[188:189]
	v_lshl_add_u64 v[72:73], v[158:159], 0, v[188:189]
	v_lshlrev_b32_e32 v188, 7, v76
	v_lshl_add_u64 v[76:77], v[156:157], 0, v[188:189]
	v_lshl_add_u64 v[80:81], v[158:159], 0, v[188:189]
	v_cvt_pk_bf16_f32 v144, v124, v126
	v_cvt_pk_bf16_f32 v145, v132, v134
	v_cvt_pk_bf16_f32 v146, v125, v127
	v_cvt_pk_bf16_f32 v147, v133, v135
	global_load_dwordx4 v[52:55], v[52:53], off
	s_or_b32 s16, s4, 0x80
	global_load_dwordx4 v[56:59], v[56:57], off
	v_mfma_f32_16x16x32_bf16 v[132:135], v[16:19], v[144:147], v[116:119]
	global_load_dwordx4 v[60:63], v[60:61], off
	s_nop 0
	global_load_dwordx4 v[64:67], v[64:65], off
	s_nop 0
	global_load_dwordx4 v[68:71], v[68:69], off
	s_nop 0
	global_load_dwordx4 v[72:75], v[72:73], off
	s_nop 0
	global_load_dwordx4 v[76:79], v[76:77], off
	s_nop 0
	global_load_dwordx4 v[80:83], v[80:81], off
	ds_read_b64_tr_b16 v[118:119], v184 offset:2304
	ds_read_b64_tr_b16 v[116:117], v184
	ds_read_b64_tr_b16 v[206:207], v184 offset:32
	s_waitcnt lgkmcnt(1)
	v_mfma_f32_16x16x32_bf16 v[124:127], v[116:119], v[144:147], v[120:123]
	ds_read_b64_tr_b16 v[208:209], v184 offset:2336
	ds_read_b64_tr_b16 v[116:117], v184 offset:64
	ds_read_b64_tr_b16 v[118:119], v184 offset:2368
	s_waitcnt lgkmcnt(0)
	v_mfma_f32_16x16x32_bf16 v[120:123], v[116:119], v[144:147], v[136:139]
	ds_read_b64_tr_b16 v[116:117], v184 offset:96
	ds_read_b64_tr_b16 v[118:119], v184 offset:2400
	s_waitcnt vmcnt(22)
	ds_write_b128 v183, v[88:91]
	ds_write_b128 v183, v[84:87] offset:9216
	s_waitcnt vmcnt(20)
	ds_write_b128 v183, v[96:99] offset:1152
	ds_write_b128 v183, v[92:95] offset:10368
	s_waitcnt vmcnt(18)
	ds_write_b128 v183, v[104:107] offset:2304
	ds_write_b128 v183, v[100:103] offset:11520
	s_waitcnt vmcnt(16)
	ds_write_b128 v183, v[112:115] offset:3456
	ds_write_b128 v183, v[108:111] offset:12672
	ds_read_b128 v[84:87], v151 offset:9216
	ds_read_b128 v[88:91], v151 offset:9280
	s_waitcnt lgkmcnt(1)
	v_mfma_f32_16x16x32_bf16 v[84:87], v[84:87], v[8:11], v[12:15]
	v_or_b32_e32 v92, s0, v168
	v_sub_u32_e32 v93, v92, v154
	v_cmp_gt_u32_e64 s[0:1], s67, v92
	s_waitcnt lgkmcnt(0)
	v_mfma_f32_16x16x32_bf16 v[84:87], v[88:91], v[4:7], v[84:87]
	v_add_u32_e32 v88, 0x100, v93
	v_cmp_gt_u32_e32 vcc, s22, v88
	v_cvt_f32_i32_e32 v88, v93
	s_and_b64 vcc, s[54:55], vcc
	v_mfma_f32_16x16x32_bf16 v[128:131], v[206:209], v[144:147], v[128:131]
	v_exp_f32_e32 v136, v193
	s_nop 1
	v_fma_f32 v84, |v88|, v153, v84
	v_add_u32_e32 v88, 0x104, v93
	v_mfma_f32_16x16x32_bf16 v[116:119], v[116:119], v[144:147], v[140:143]
	v_cndmask_b32_e32 v144, v234, v84, vcc
	v_add_u32_e32 v84, 4, v93
	v_cvt_f32_i32_e32 v84, v84
	v_cmp_gt_u32_e32 vcc, s22, v88
	s_and_b64 vcc, vcc, s[0:1]
	v_cmp_gt_u32_e64 s[0:1], s23, v92
	v_fma_f32 v84, |v84|, v153, v85
	v_cndmask_b32_e32 v145, v234, v84, vcc
	v_add_u32_e32 v84, 8, v93
	v_cvt_f32_i32_e32 v84, v84
	v_add_u32_e32 v85, 0x108, v93
	v_cmp_gt_u32_e32 vcc, s22, v85
	s_and_b64 vcc, vcc, s[0:1]
	v_fma_f32 v84, |v84|, v153, v86
	v_cndmask_b32_e32 v146, v234, v84, vcc
	v_add_u32_e32 v84, 12, v93
	v_cvt_f32_i32_e32 v84, v84
	v_add_u32_e32 v85, 0x10c, v93
	v_cmp_gt_u32_e32 vcc, s22, v85
	v_cmp_gt_u32_e64 s[0:1], s17, v92
	s_and_b64 vcc, vcc, s[0:1]
	v_fma_f32 v84, |v84|, v153, v87
	v_cndmask_b32_e32 v147, v234, v84, vcc
	ds_read_b128 v[84:87], v151 offset:11520
	ds_read_b128 v[88:91], v151 offset:11584
	s_waitcnt lgkmcnt(1)
; DI void tile_load(TileRegs& R, const bf16* kb, const bf16* vb, int tokbase, int stride, int lane) {
; #pragma unroll
;     for (int it = 0; it < 4; ++it) { const int n = lane + 64 * it, row = n >> 3, ch = n & 7; int tok = tokbase + stride * row; tok = min(max(tok, 0), T - 1);
;         R.k[it] = *(const u32x4*)(kb + (size_t)tok * 64 + ch * 8); R.v[it] = *(const u32x4*)(vb + (size_t)tok * 64 + ch * 8); }
; }
; DI void tile_v_to_lds(const TileRegs& R, LAS char* vt, int lane) {
; #pragma unroll
;     for (int it = 0; it < 4; ++it) { const int n = lane + 64 * it, row = n >> 3, ch = n & 7;
;         *(LAS u32x4*)(vt + row * VT_PITCH + ch * 16) = R.v[it]; *(LAS u32x4*)(vt + KT_OFF + row * VT_PITCH + ch * 16) = R.k[it]; }
; }
; DI bf16x8 k_frag(const LAS char* vt, int t, int ks, int lane) { return k_frag_at(vt + KT_OFF, t, ks, lane); }
; DI void fb_update(f32x4 (&o)[4], f32x4& ol, const f32x4 st0, const f32x4 st1, const LAS char* vt, int lane) {
;     f32x4 p0, p1;
; #pragma unroll
;     for (int i = 0; i < 4; ++i) { p0[i] = ex2(st0[i]); p1[i] = ex2(st1[i]); }
;     const bf16x8 pf = pack8(p0, p1);
;     const bf16x8 ones = {0x3F80, 0x3F80, 0x3F80, 0x3F80, 0x3F80, 0x3F80, 0x3F80, 0x3F80};
;     ol = MFMA16(ones, pf, ol);
;     const int g = lane >> 4, q = (lane & 15) >> 2, p = lane & 3;
;     const LAS char* v0 = vt + (4 * g + q) * VT_PITCH + 8 * p;
;     const LAS char* v1 = v0 + 16 * VT_PITCH;
; #pragma unroll
;     for (int c = 0; c < 4; ++c) { const bf16x8 vf = cat8(vtr(v0 + 32 * c), vtr(v1 + 32 * c)); o[c] = MFMA16(vf, pf, o[c]); }
; }
; DI float q_norm2(const bf16x8 (&qf)[2]) { float a = sumsq8(qf[0]) + sumsq8(qf[1]); a += __shfl_xor(a, 16); a += __shfl_xor(a, 32); return a; }
; DI void a_desc(int ti, int a0, int rho, int& tokbase, int& stride, int& maxd) {
;     if (ti < 4) { stride = 16; tokbase = rho + 512 * ti; maxd = 1024; }
;     else if (ti < 10) { stride = 4; const int m0 = 4 * a0 + (rho >> 2) - 64 + 32 * (ti - 4); tokbase = 4 * m0 + (rho & 3); maxd = 256; }
;     else { stride = 1; tokbase = 16 * a0 + rho - 64 + 32 * (ti - 10); maxd = 64; }
; }
; template <bool EDGE>
; DI void a_scores(f32x4 (&st)[2], const LAS char* kt, const bf16x8 (&qf)[2], const f32x4 cinit, int tokbase, int stride, int maxd, int tq, float nslope2, int lane) {
;     const int g = lane >> 4;
;     const int base0 = tokbase + stride * 4 * g - tq;
; #pragma unroll
	v_mfma_f32_16x16x32_bf16 v[84:87], v[84:87], v[8:11], v[12:15]
	v_cmp_gt_u32_e64 s[0:1], s58, v92
	v_exp_f32_e32 v138, v201
	v_exp_f32_e32 v137, v198
	s_waitcnt lgkmcnt(0)
	v_mfma_f32_16x16x32_bf16 v[84:87], v[88:91], v[4:7], v[84:87]
	v_add_u32_e32 v88, 64, v93
	v_cvt_f32_i32_e32 v88, v88
	v_add_u32_e32 v89, 0x140, v93
	v_cmp_gt_u32_e32 vcc, s22, v89
	s_and_b64 vcc, s[54:55], vcc
	s_nop 2
	v_fma_f32 v84, |v88|, v153, v84
	v_cndmask_b32_e32 v155, v234, v84, vcc
	v_add_u32_e32 v84, 0x44, v93
	v_cvt_f32_i32_e32 v84, v84
	v_add_u32_e32 v88, 0x144, v93
	v_cmp_gt_u32_e32 vcc, s22, v88
	s_and_b64 vcc, vcc, s[0:1]
	v_fma_f32 v84, |v84|, v153, v85
	v_cndmask_b32_e32 v186, v234, v84, vcc
	v_add_u32_e32 v84, 0x48, v93
	v_cvt_f32_i32_e32 v84, v84
	v_add_u32_e32 v85, 0x148, v93
	v_cmp_gt_u32_e32 vcc, s22, v85
	v_cmp_gt_u32_e64 s[0:1], s59, v92
	s_and_b64 vcc, vcc, s[0:1]
	v_fma_f32 v84, |v84|, v153, v86
	v_cndmask_b32_e32 v187, v234, v84, vcc
	v_add_u32_e32 v84, 0x4c, v93
	v_cvt_f32_i32_e32 v84, v84
	v_add_u32_e32 v85, 0x14c, v93
	v_cmp_gt_u32_e32 vcc, s22, v85
	v_cmp_gt_u32_e64 s[0:1], s52, v92
	s_and_b64 vcc, vcc, s[0:1]
	v_fma_f32 v84, |v84|, v153, v87
	v_cndmask_b32_e32 v191, v234, v84, vcc
	v_add_u32_e32 v84, s16, v178
	v_med3_i32 v84, v84, 0, v233
	v_lshlrev_b32_e32 v188, 7, v84
	v_lshl_add_u64 v[84:85], v[156:157], 0, v[188:189]
	global_load_dwordx4 v[108:111], v[84:85], off
	v_lshl_add_u64 v[84:85], v[158:159], 0, v[188:189]
	global_load_dwordx4 v[112:115], v[84:85], off
	v_add_u32_e32 v84, s16, v179
	v_med3_i32 v84, v84, 0, v233
	v_lshlrev_b32_e32 v188, 7, v84
	v_lshl_add_u64 v[84:85], v[156:157], 0, v[188:189]
	global_load_dwordx4 v[100:103], v[84:85], off
	v_lshl_add_u64 v[84:85], v[158:159], 0, v[188:189]
	global_load_dwordx4 v[104:107], v[84:85], off
	v_add_u32_e32 v84, s16, v180
	v_med3_i32 v84, v84, 0, v233
	v_lshlrev_b32_e32 v188, 7, v84
	v_lshl_add_u64 v[84:85], v[156:157], 0, v[188:189]
	global_load_dwordx4 v[92:95], v[84:85], off
	v_lshl_add_u64 v[84:85], v[158:159], 0, v[188:189]
	global_load_dwordx4 v[96:99], v[84:85], off
	v_add_u32_e32 v84, s16, v181
	v_exp_f32_e32 v139, v202
	v_exp_f32_e32 v140, v199
	v_exp_f32_e32 v141, v203
	v_exp_f32_e32 v142, v200
	v_exp_f32_e32 v143, v204
	v_med3_i32 v84, v84, 0, v233
	v_lshlrev_b32_e32 v188, 7, v84
	v_lshl_add_u64 v[84:85], v[156:157], 0, v[188:189]
	v_lshl_add_u64 v[88:89], v[158:159], 0, v[188:189]
	global_load_dwordx4 v[84:87], v[84:85], off
	v_cvt_pk_bf16_f32 v136, v136, v137
	global_load_dwordx4 v[88:91], v[88:89], off
	v_cvt_pk_bf16_f32 v137, v140, v142
	v_cvt_pk_bf16_f32 v138, v138, v139
	v_cvt_pk_bf16_f32 v139, v141, v143
	ds_read_b64_tr_b16 v[142:143], v184 offset:6912
	ds_read_b64_tr_b16 v[140:141], v184 offset:4608
	ds_read_b64_tr_b16 v[198:199], v184 offset:4640
	s_waitcnt lgkmcnt(1)
	v_mfma_f32_16x16x32_bf16 v[124:127], v[140:143], v[136:139], v[124:127]
	ds_read_b64_tr_b16 v[200:201], v184 offset:6944
	ds_read_b64_tr_b16 v[140:141], v184 offset:4672
	ds_read_b64_tr_b16 v[142:143], v184 offset:6976
	s_waitcnt lgkmcnt(0)
	v_mfma_f32_16x16x32_bf16 v[140:143], v[140:143], v[136:139], v[120:123]
	s_nop 2
	ds_read_b64_tr_b16 v[120:121], v184 offset:4704
	ds_read_b64_tr_b16 v[122:123], v184 offset:7008
	s_waitcnt vmcnt(22)
	ds_write_b128 v183, v[24:27] offset:4608
	ds_write_b128 v183, v[20:23] offset:9216
	s_waitcnt vmcnt(20)
	ds_write_b128 v183, v[32:35] offset:5760
	ds_write_b128 v183, v[28:31] offset:10368
	s_waitcnt vmcnt(18)
	ds_write_b128 v183, v[40:43] offset:6912
	ds_write_b128 v183, v[36:39] offset:11520
	s_waitcnt vmcnt(16)
	ds_write_b128 v183, v[48:51] offset:8064
	ds_write_b128 v183, v[44:47] offset:12672
	ds_read_b128 v[20:23], v151 offset:9216
	ds_read_b128 v[24:27], v151 offset:9280
	s_waitcnt lgkmcnt(1)
	v_mfma_f32_16x16x32_bf16 v[20:23], v[20:23], v[8:11], v[12:15]
	v_or_b32_e32 v28, s33, v168
	v_sub_u32_e32 v29, v28, v154
	v_cmp_gt_u32_e64 s[0:1], s67, v28
	s_waitcnt lgkmcnt(0)
	v_mfma_f32_16x16x32_bf16 v[20:23], v[24:27], v[4:7], v[20:23]
	v_add_u32_e32 v24, 0x100, v29
	v_cmp_gt_u32_e32 vcc, s22, v24
	v_cvt_f32_i32_e32 v24, v29
	s_and_b64 vcc, s[90:91], vcc
	v_mfma_f32_16x16x32_bf16 v[128:131], v[198:201], v[136:139], v[128:131]
	s_or_b32 s33, s5, s65
	s_nop 1
	v_fma_f32 v20, |v24|, v153, v20
	v_cndmask_b32_e32 v193, v234, v20, vcc
	v_add_u32_e32 v20, 4, v29
	v_cvt_f32_i32_e32 v20, v20
	v_add_u32_e32 v24, 0x104, v29
	v_cmp_gt_u32_e32 vcc, s22, v24
	s_and_b64 vcc, vcc, s[0:1]
	v_fma_f32 v20, |v20|, v153, v21
	v_cndmask_b32_e32 v198, v234, v20, vcc
	v_add_u32_e32 v20, 8, v29
	v_cvt_f32_i32_e32 v20, v20
	v_add_u32_e32 v21, 0x108, v29
	v_cmp_gt_u32_e32 vcc, s22, v21
	v_cmp_gt_u32_e64 s[0:1], s23, v28
	s_and_b64 vcc, vcc, s[0:1]
	v_fma_f32 v20, |v20|, v153, v22
	v_cndmask_b32_e32 v199, v234, v20, vcc
	v_add_u32_e32 v20, 12, v29
	v_cvt_f32_i32_e32 v20, v20
	v_add_u32_e32 v21, 0x10c, v29
	v_cmp_gt_u32_e32 vcc, s22, v21
	v_cmp_gt_u32_e64 s[0:1], s17, v28
	s_and_b64 vcc, vcc, s[0:1]
	v_fma_f32 v20, |v20|, v153, v23
	v_cndmask_b32_e32 v200, v234, v20, vcc
	ds_read_b128 v[20:23], v151 offset:11520
	ds_read_b128 v[24:27], v151 offset:11584
	s_waitcnt lgkmcnt(1)
	v_mfma_f32_16x16x32_bf16 v[20:23], v[20:23], v[8:11], v[12:15]
	v_add_u32_e32 v32, s33, v181
	v_med3_i32 v32, v32, 0, v233
	s_or_b32 s5, s5, s68
	s_waitcnt lgkmcnt(0)
; DI void tile_load(TileRegs& R, const bf16* kb, const bf16* vb, int tokbase, int stride, int lane) {
; #pragma unroll
;     for (int it = 0; it < 4; ++it) { const int n = lane + 64 * it, row = n >> 3, ch = n & 7; int tok = tokbase + stride * row; tok = min(max(tok, 0), T - 1);
;         R.k[it] = *(const u32x4*)(kb + (size_t)tok * 64 + ch * 8); R.v[it] = *(const u32x4*)(vb + (size_t)tok * 64 + ch * 8); }
; }
; DI void tile_v_to_lds(const TileRegs& R, LAS char* vt, int lane) {
; #pragma unroll
;     for (int it = 0; it < 4; ++it) { const int n = lane + 64 * it, row = n >> 3, ch = n & 7;
;         *(LAS u32x4*)(vt + row * VT_PITCH + ch * 16) = R.v[it]; *(LAS u32x4*)(vt + KT_OFF + row * VT_PITCH + ch * 16) = R.k[it]; }
; }
; DI bf16x8 k_frag(const LAS char* vt, int t, int ks, int lane) { return k_frag_at(vt + KT_OFF, t, ks, lane); }
; DI void fb_update(f32x4 (&o)[4], f32x4& ol, const f32x4 st0, const f32x4 st1, const LAS char* vt, int lane) {
;     f32x4 p0, p1;
; #pragma unroll
;     for (int i = 0; i < 4; ++i) { p0[i] = ex2(st0[i]); p1[i] = ex2(st1[i]); }
;     const bf16x8 pf = pack8(p0, p1);
;     const bf16x8 ones = {0x3F80, 0x3F80, 0x3F80, 0x3F80, 0x3F80, 0x3F80, 0x3F80, 0x3F80};
;     ol = MFMA16(ones, pf, ol);
;     const int g = lane >> 4, q = (lane & 15) >> 2, p = lane & 3;
;     const LAS char* v0 = vt + (4 * g + q) * VT_PITCH + 8 * p;
;     const LAS char* v1 = v0 + 16 * VT_PITCH;
; #pragma unroll
;     for (int c = 0; c < 4; ++c) { const bf16x8 vf = cat8(vtr(v0 + 32 * c), vtr(v1 + 32 * c)); o[c] = MFMA16(vf, pf, o[c]); }
; }
; DI float q_norm2(const bf16x8 (&qf)[2]) { float a = sumsq8(qf[0]) + sumsq8(qf[1]); a += __shfl_xor(a, 16); a += __shfl_xor(a, 32); return a; }
; DI void a_desc(int ti, int a0, int rho, int& tokbase, int& stride, int& maxd) {
;     if (ti < 4) { stride = 16; tokbase = rho + 512 * ti; maxd = 1024; }
;     else if (ti < 10) { stride = 4; const int m0 = 4 * a0 + (rho >> 2) - 64 + 32 * (ti - 4); tokbase = 4 * m0 + (rho & 3); maxd = 256; }
;     else { stride = 1; tokbase = 16 * a0 + rho - 64 + 32 * (ti - 10); maxd = 64; }
; }
; template <bool EDGE>
; DI void a_scores(f32x4 (&st)[2], const LAS char* kt, const bf16x8 (&qf)[2], const f32x4 cinit, int tokbase, int stride, int maxd, int tq, float nslope2, int lane) {
;     const int g = lane >> 4;
;     const int base0 = tokbase + stride * 4 * g - tq;
; #pragma unroll
	v_mfma_f32_16x16x32_bf16 v[20:23], v[24:27], v[4:7], v[20:23]
	v_add_u32_e32 v24, 64, v29
	v_cvt_f32_i32_e32 v24, v24
	v_add_u32_e32 v25, 0x140, v29
	v_cmp_gt_u32_e32 vcc, s22, v25
	s_and_b64 vcc, s[90:91], vcc
	s_nop 2
	v_fma_f32 v20, |v24|, v153, v20
	v_cndmask_b32_e32 v201, v234, v20, vcc
	v_add_u32_e32 v20, 0x44, v29
	v_cvt_f32_i32_e32 v20, v20
	v_add_u32_e32 v24, 0x144, v29
	v_cmp_gt_u32_e32 vcc, s22, v24
	v_add_u32_e32 v24, 0x44, v28
	v_cmp_gt_u32_e64 s[0:1], s24, v24
	s_and_b64 vcc, vcc, s[0:1]
	v_fma_f32 v20, |v20|, v153, v21
	v_cndmask_b32_e32 v202, v234, v20, vcc
	v_add_u32_e32 v20, 0x48, v29
	v_cvt_f32_i32_e32 v20, v20
	v_add_u32_e32 v21, 0x148, v29
	v_cmp_gt_u32_e32 vcc, s22, v21
	v_add_u32_e32 v21, 0x48, v28
	v_cmp_gt_u32_e64 s[0:1], s24, v21
	s_and_b64 vcc, vcc, s[0:1]
	v_fma_f32 v20, |v20|, v153, v22
	v_cndmask_b32_e32 v203, v234, v20, vcc
	v_add_u32_e32 v20, 0x4c, v29
	v_cvt_f32_i32_e32 v20, v20
	v_add_u32_e32 v21, 0x14c, v29
	v_cmp_gt_u32_e32 vcc, s22, v21
	v_add_u32_e32 v21, 0x4c, v28
	v_cmp_gt_u32_e64 s[0:1], s24, v21
	s_and_b64 vcc, vcc, s[0:1]
	v_fma_f32 v20, |v20|, v153, v23
	v_cndmask_b32_e32 v204, v234, v20, vcc
	v_add_u32_e32 v20, s33, v178
	v_med3_i32 v20, v20, 0, v233
	v_lshlrev_b32_e32 v188, 7, v20
	v_lshl_add_u64 v[20:21], v[156:157], 0, v[188:189]
	global_load_dwordx4 v[44:47], v[20:21], off
	v_lshl_add_u64 v[20:21], v[158:159], 0, v[188:189]
	global_load_dwordx4 v[48:51], v[20:21], off
	v_add_u32_e32 v20, s33, v179
	v_med3_i32 v20, v20, 0, v233
	v_lshlrev_b32_e32 v188, 7, v20
	v_lshl_add_u64 v[20:21], v[156:157], 0, v[188:189]
	v_lshl_add_u64 v[24:25], v[158:159], 0, v[188:189]
	v_mfma_f32_16x16x32_bf16 v[132:135], v[16:19], v[136:139], v[132:135]
	global_load_dwordx4 v[20:23], v[20:21], off
	s_nop 0
	global_load_dwordx4 v[36:39], v[24:25], off
	v_mfma_f32_16x16x32_bf16 v[116:119], v[120:123], v[136:139], v[116:119]
	v_add_u32_e32 v24, s33, v180
	v_exp_f32_e32 v120, v144
	v_exp_f32_e32 v121, v155
	v_exp_f32_e32 v122, v145
	v_exp_f32_e32 v123, v186
	v_exp_f32_e32 v136, v146
	v_exp_f32_e32 v137, v187
	v_exp_f32_e32 v138, v147
	v_exp_f32_e32 v139, v191
	v_med3_i32 v24, v24, 0, v233
	v_lshlrev_b32_e32 v188, 7, v24
	v_lshl_add_u64 v[24:25], v[156:157], 0, v[188:189]
	v_lshl_add_u64 v[28:29], v[158:159], 0, v[188:189]
	v_lshlrev_b32_e32 v188, 7, v32
	v_lshl_add_u64 v[32:33], v[156:157], 0, v[188:189]
	v_lshl_add_u64 v[40:41], v[158:159], 0, v[188:189]
	v_cvt_pk_bf16_f32 v144, v120, v122
	v_cvt_pk_bf16_f32 v145, v136, v138
	v_cvt_pk_bf16_f32 v146, v121, v123
	v_cvt_pk_bf16_f32 v147, v137, v139
	global_load_dwordx4 v[24:27], v[24:25], off
	s_nop 0
	global_load_dwordx4 v[28:31], v[28:29], off
	v_mfma_f32_16x16x32_bf16 v[136:139], v[16:19], v[144:147], v[132:135]
	global_load_dwordx4 v[32:35], v[32:33], off
	s_nop 0
	global_load_dwordx4 v[40:43], v[40:41], off
	ds_read_b64_tr_b16 v[122:123], v184 offset:2304
	ds_read_b64_tr_b16 v[120:121], v184
	ds_read_b64_tr_b16 v[132:133], v184 offset:32
	ds_read_b64_tr_b16 v[134:135], v184 offset:2336
	s_waitcnt lgkmcnt(2)
	v_mfma_f32_16x16x32_bf16 v[120:123], v[120:123], v[144:147], v[124:127]
	s_waitcnt lgkmcnt(0)
	v_mfma_f32_16x16x32_bf16 v[124:127], v[132:135], v[144:147], v[128:131]
	s_nop 2
	ds_read_b64_tr_b16 v[128:129], v184 offset:64
	ds_read_b64_tr_b16 v[130:131], v184 offset:2368
	ds_read_b64_tr_b16 v[132:133], v184 offset:96
	ds_read_b64_tr_b16 v[134:135], v184 offset:2400
	s_waitcnt vmcnt(22)
	ds_write_b128 v183, v[56:59]
	ds_write_b128 v183, v[52:55] offset:9216
	s_waitcnt vmcnt(20)
	ds_write_b128 v183, v[64:67] offset:1152
	ds_write_b128 v183, v[60:63] offset:10368
	s_waitcnt vmcnt(18)
	ds_write_b128 v183, v[72:75] offset:2304
	ds_write_b128 v183, v[68:71] offset:11520
	s_waitcnt vmcnt(16)
	ds_write_b128 v183, v[80:83] offset:3456
	ds_write_b128 v183, v[76:79] offset:12672
	ds_read_b128 v[52:55], v151 offset:9216
	ds_read_b128 v[56:59], v151 offset:9280
	s_waitcnt lgkmcnt(1)
	v_mfma_f32_16x16x32_bf16 v[52:55], v[52:55], v[8:11], v[12:15]
	v_or_b32_e32 v60, s4, v168
	v_sub_u32_e32 v61, v60, v154
	v_cmp_gt_u32_e64 s[0:1], s67, v60
	s_waitcnt lgkmcnt(0)
	v_mfma_f32_16x16x32_bf16 v[52:55], v[56:59], v[4:7], v[52:55]
	v_add_u32_e32 v56, 0x100, v61
	v_cmp_gt_u32_e32 vcc, s22, v56
	v_cvt_f32_i32_e32 v56, v61
	s_and_b64 vcc, s[20:21], vcc
	v_mfma_f32_16x16x32_bf16 v[128:131], v[128:131], v[144:147], v[140:143]
	v_add_u32_e32 v68, s5, v180
	s_nop 1
	v_fma_f32 v52, |v56|, v153, v52
	v_add_u32_e32 v56, 0x104, v61
	v_mfma_f32_16x16x32_bf16 v[132:135], v[132:135], v[144:147], v[116:119]
	v_cndmask_b32_e32 v144, v234, v52, vcc
	v_add_u32_e32 v52, 4, v61
	v_cvt_f32_i32_e32 v52, v52
	v_cmp_gt_u32_e32 vcc, s22, v56
	s_and_b64 vcc, vcc, s[0:1]
	v_cmp_gt_u32_e64 s[0:1], s23, v60
	v_fma_f32 v52, |v52|, v153, v53
	v_cndmask_b32_e32 v145, v234, v52, vcc
	v_add_u32_e32 v52, 8, v61
	v_cvt_f32_i32_e32 v52, v52
	v_add_u32_e32 v53, 0x108, v61
	v_cmp_gt_u32_e32 vcc, s22, v53
	s_and_b64 vcc, vcc, s[0:1]
	v_fma_f32 v52, |v52|, v153, v54
	v_cndmask_b32_e32 v146, v234, v52, vcc
	v_add_u32_e32 v52, 12, v61
	v_cvt_f32_i32_e32 v52, v52
	v_add_u32_e32 v53, 0x10c, v61
	v_cmp_gt_u32_e32 vcc, s22, v53
	v_cmp_gt_u32_e64 s[0:1], s17, v60
	s_and_b64 vcc, vcc, s[0:1]
	v_fma_f32 v52, |v52|, v153, v55
	v_cndmask_b32_e32 v147, v234, v52, vcc
	ds_read_b128 v[52:55], v151 offset:11520
	ds_read_b128 v[56:59], v151 offset:11584
	s_waitcnt lgkmcnt(1)
	v_mfma_f32_16x16x32_bf16 v[52:55], v[52:55], v[8:11], v[12:15]
	v_cmp_gt_u32_e64 s[0:1], s58, v60
	v_med3_i32 v68, v68, 0, v233
	v_add_u32_e32 v76, s5, v181
	s_waitcnt lgkmcnt(0)
; DI void tile_load(TileRegs& R, const bf16* kb, const bf16* vb, int tokbase, int stride, int lane) {
; #pragma unroll
;     for (int it = 0; it < 4; ++it) { const int n = lane + 64 * it, row = n >> 3, ch = n & 7; int tok = tokbase + stride * row; tok = min(max(tok, 0), T - 1);
;         R.k[it] = *(const u32x4*)(kb + (size_t)tok * 64 + ch * 8); R.v[it] = *(const u32x4*)(vb + (size_t)tok * 64 + ch * 8); }
; }
; DI void tile_v_to_lds(const TileRegs& R, LAS char* vt, int lane) {
; #pragma unroll
;     for (int it = 0; it < 4; ++it) { const int n = lane + 64 * it, row = n >> 3, ch = n & 7;
;         *(LAS u32x4*)(vt + row * VT_PITCH + ch * 16) = R.v[it]; *(LAS u32x4*)(vt + KT_OFF + row * VT_PITCH + ch * 16) = R.k[it]; }
; }
; DI bf16x8 k_frag(const LAS char* vt, int t, int ks, int lane) { return k_frag_at(vt + KT_OFF, t, ks, lane); }
; DI void fb_update(f32x4 (&o)[4], f32x4& ol, const f32x4 st0, const f32x4 st1, const LAS char* vt, int lane) {
;     f32x4 p0, p1;
; #pragma unroll
;     for (int i = 0; i < 4; ++i) { p0[i] = ex2(st0[i]); p1[i] = ex2(st1[i]); }
;     const bf16x8 pf = pack8(p0, p1);
;     const bf16x8 ones = {0x3F80, 0x3F80, 0x3F80, 0x3F80, 0x3F80, 0x3F80, 0x3F80, 0x3F80};
;     ol = MFMA16(ones, pf, ol);
;     const int g = lane >> 4, q = (lane & 15) >> 2, p = lane & 3;
;     const LAS char* v0 = vt + (4 * g + q) * VT_PITCH + 8 * p;
;     const LAS char* v1 = v0 + 16 * VT_PITCH;
; #pragma unroll
;     for (int c = 0; c < 4; ++c) { const bf16x8 vf = cat8(vtr(v0 + 32 * c), vtr(v1 + 32 * c)); o[c] = MFMA16(vf, pf, o[c]); }
; }
; DI float q_norm2(const bf16x8 (&qf)[2]) { float a = sumsq8(qf[0]) + sumsq8(qf[1]); a += __shfl_xor(a, 16); a += __shfl_xor(a, 32); return a; }
; DI void a_desc(int ti, int a0, int rho, int& tokbase, int& stride, int& maxd) {
;     if (ti < 4) { stride = 16; tokbase = rho + 512 * ti; maxd = 1024; }
;     else if (ti < 10) { stride = 4; const int m0 = 4 * a0 + (rho >> 2) - 64 + 32 * (ti - 4); tokbase = 4 * m0 + (rho & 3); maxd = 256; }
;     else { stride = 1; tokbase = 16 * a0 + rho - 64 + 32 * (ti - 10); maxd = 64; }
; }
; template <bool EDGE>
; DI void a_scores(f32x4 (&st)[2], const LAS char* kt, const bf16x8 (&qf)[2], const f32x4 cinit, int tokbase, int stride, int maxd, int tq, float nslope2, int lane) {
;     const int g = lane >> 4;
;     const int base0 = tokbase + stride * 4 * g - tq;
; #pragma unroll
	v_mfma_f32_16x16x32_bf16 v[52:55], v[56:59], v[4:7], v[52:55]
	v_add_u32_e32 v56, 64, v61
	v_cvt_f32_i32_e32 v56, v56
	v_add_u32_e32 v57, 0x140, v61
	v_cmp_gt_u32_e32 vcc, s22, v57
	s_and_b64 vcc, s[20:21], vcc
	s_nop 2
	v_fma_f32 v52, |v56|, v153, v52
	v_cndmask_b32_e32 v155, v234, v52, vcc
	v_add_u32_e32 v52, 0x44, v61
	v_cvt_f32_i32_e32 v52, v52
	v_add_u32_e32 v56, 0x144, v61
	v_cmp_gt_u32_e32 vcc, s22, v56
	s_and_b64 vcc, vcc, s[0:1]
	v_fma_f32 v52, |v52|, v153, v53
	v_cndmask_b32_e32 v186, v234, v52, vcc
	v_add_u32_e32 v52, 0x48, v61
	v_cvt_f32_i32_e32 v52, v52
	v_add_u32_e32 v53, 0x148, v61
	v_cmp_gt_u32_e32 vcc, s22, v53
	v_cmp_gt_u32_e64 s[0:1], s59, v60
	s_and_b64 vcc, vcc, s[0:1]
	v_fma_f32 v52, |v52|, v153, v54
	v_cndmask_b32_e32 v187, v234, v52, vcc
	v_add_u32_e32 v52, 0x4c, v61
	v_cvt_f32_i32_e32 v52, v52
	v_add_u32_e32 v53, 0x14c, v61
	v_cmp_gt_u32_e32 vcc, s22, v53
	v_cmp_gt_u32_e64 s[0:1], s52, v60
	s_and_b64 vcc, vcc, s[0:1]
	v_fma_f32 v52, |v52|, v153, v55
	v_cndmask_b32_e32 v191, v234, v52, vcc
	v_add_u32_e32 v52, s5, v178
	v_med3_i32 v52, v52, 0, v233
	v_add_u32_e32 v60, s5, v179
	v_lshlrev_b32_e32 v188, 7, v52
	v_med3_i32 v60, v60, 0, v233
	v_lshl_add_u64 v[52:53], v[156:157], 0, v[188:189]
	v_lshl_add_u64 v[56:57], v[158:159], 0, v[188:189]
	v_lshlrev_b32_e32 v188, 7, v60
	v_lshl_add_u64 v[60:61], v[156:157], 0, v[188:189]
	v_lshl_add_u64 v[64:65], v[158:159], 0, v[188:189]
	v_lshlrev_b32_e32 v188, 7, v68
	v_med3_i32 v76, v76, 0, v233
	v_lshl_add_u64 v[68:69], v[156:157], 0, v[188:189]
	v_lshl_add_u64 v[72:73], v[158:159], 0, v[188:189]
	v_lshlrev_b32_e32 v188, 7, v76
	v_lshl_add_u64 v[76:77], v[156:157], 0, v[188:189]
	v_exp_f32_e32 v116, v193
	v_exp_f32_e32 v117, v201
	v_exp_f32_e32 v118, v198
	v_exp_f32_e32 v119, v202
	v_exp_f32_e32 v141, v199
	v_exp_f32_e32 v143, v203
	v_exp_f32_e32 v142, v200
	v_exp_f32_e32 v156, v204
	v_lshl_add_u64 v[80:81], v[158:159], 0, v[188:189]
	v_cvt_pk_bf16_f32 v140, v116, v118
	v_cvt_pk_bf16_f32 v141, v141, v142
	v_cvt_pk_bf16_f32 v142, v117, v119
	v_cvt_pk_bf16_f32 v143, v143, v156
	global_load_dwordx4 v[52:55], v[52:53], off
	s_nop 0
	global_load_dwordx4 v[56:59], v[56:57], off
	v_mfma_f32_16x16x32_bf16 v[116:119], v[16:19], v[140:143], v[136:139]
	global_load_dwordx4 v[60:63], v[60:61], off
	s_nop 0
	global_load_dwordx4 v[64:67], v[64:65], off
	s_nop 0
	global_load_dwordx4 v[68:71], v[68:69], off
	s_nop 0
	global_load_dwordx4 v[72:75], v[72:73], off
	s_nop 0
	global_load_dwordx4 v[76:79], v[76:77], off
	s_nop 0
	global_load_dwordx4 v[80:83], v[80:81], off
	ds_read_b64_tr_b16 v[138:139], v184 offset:6912
	ds_read_b64_tr_b16 v[136:137], v184 offset:4608
	ds_read_b64_tr_b16 v[156:157], v184 offset:4640
	ds_read_b64_tr_b16 v[158:159], v184 offset:6944
	s_waitcnt lgkmcnt(2)
	v_mfma_f32_16x16x32_bf16 v[136:139], v[136:139], v[140:143], v[120:123]
	s_waitcnt lgkmcnt(0)
	v_mfma_f32_16x16x32_bf16 v[120:123], v[156:159], v[140:143], v[124:127]
	s_nop 2
	ds_read_b64_tr_b16 v[124:125], v184 offset:4672
	ds_read_b64_tr_b16 v[126:127], v184 offset:6976
	s_waitcnt lgkmcnt(0)
	v_mfma_f32_16x16x32_bf16 v[124:127], v[124:127], v[140:143], v[128:131]
	s_nop 2
	ds_read_b64_tr_b16 v[128:129], v184 offset:4704
	ds_read_b64_tr_b16 v[130:131], v184 offset:7008
	s_waitcnt vmcnt(22)
	ds_write_b128 v183, v[112:115] offset:4608
	ds_write_b128 v183, v[108:111] offset:9216
	s_waitcnt vmcnt(20)
	ds_write_b128 v183, v[104:107] offset:5760
	ds_write_b128 v183, v[100:103] offset:10368
	s_waitcnt vmcnt(18)
	ds_write_b128 v183, v[96:99] offset:6912
	ds_write_b128 v183, v[92:95] offset:11520
	s_waitcnt vmcnt(16)
	ds_write_b128 v183, v[88:91] offset:8064
	ds_write_b128 v183, v[84:87] offset:12672
	ds_read_b128 v[84:87], v151 offset:9216
	ds_read_b128 v[88:91], v151 offset:9280
	s_waitcnt lgkmcnt(1)
	v_mfma_f32_16x16x32_bf16 v[84:87], v[84:87], v[8:11], v[12:15]
	v_or_b32_e32 v99, s16, v168
	v_sub_u32_e32 v100, v99, v154
	v_cmp_gt_u32_e64 s[0:1], s67, v99
	s_waitcnt lgkmcnt(0)
	v_mfma_f32_16x16x32_bf16 v[84:87], v[88:91], v[4:7], v[84:87]
	v_add_u32_e32 v88, 0x100, v100
	v_cmp_gt_u32_e32 vcc, s22, v88
	v_cvt_f32_i32_e32 v88, v100
	s_and_b64 vcc, s[20:21], vcc
	v_mfma_f32_16x16x32_bf16 v[128:131], v[128:131], v[140:143], v[132:135]
	s_nop 2
	v_fma_f32 v84, |v88|, v153, v84
	v_cndmask_b32_e32 v92, v234, v84, vcc
	v_add_u32_e32 v84, 4, v100
	v_cvt_f32_i32_e32 v84, v84
	v_add_u32_e32 v88, 0x104, v100
	v_cmp_gt_u32_e32 vcc, s22, v88
	s_and_b64 vcc, vcc, s[0:1]
	v_fma_f32 v84, |v84|, v153, v85
	v_cndmask_b32_e32 v93, v234, v84, vcc
	v_add_u32_e32 v84, 8, v100
	v_cvt_f32_i32_e32 v84, v84
	v_add_u32_e32 v85, 0x108, v100
	v_cmp_gt_u32_e32 vcc, s22, v85
	v_cmp_gt_u32_e64 s[0:1], s23, v99
	s_and_b64 vcc, vcc, s[0:1]
	v_fma_f32 v84, |v84|, v153, v86
	v_cndmask_b32_e32 v94, v234, v84, vcc
	v_add_u32_e32 v84, 12, v100
	v_cvt_f32_i32_e32 v84, v84
	v_add_u32_e32 v85, 0x10c, v100
	v_cmp_gt_u32_e32 vcc, s22, v85
	v_cmp_gt_u32_e64 s[0:1], s17, v99
	s_and_b64 vcc, vcc, s[0:1]
	v_fma_f32 v84, |v84|, v153, v87
	v_cndmask_b32_e32 v95, v234, v84, vcc
	ds_read_b128 v[84:87], v151 offset:11520
	ds_read_b128 v[88:91], v151 offset:11584
	s_waitcnt lgkmcnt(1)
	v_mfma_f32_16x16x32_bf16 v[84:87], v[84:87], v[8:11], v[12:15]
	s_waitcnt lgkmcnt(0)
; DI void tile_load(TileRegs& R, const bf16* kb, const bf16* vb, int tokbase, int stride, int lane) {
; #pragma unroll
;     for (int it = 0; it < 4; ++it) { const int n = lane + 64 * it, row = n >> 3, ch = n & 7; int tok = tokbase + stride * row; tok = min(max(tok, 0), T - 1);
;         R.k[it] = *(const u32x4*)(kb + (size_t)tok * 64 + ch * 8); R.v[it] = *(const u32x4*)(vb + (size_t)tok * 64 + ch * 8); }
; }
; DI void tile_v_to_lds(const TileRegs& R, LAS char* vt, int lane) {
; #pragma unroll
;     for (int it = 0; it < 4; ++it) { const int n = lane + 64 * it, row = n >> 3, ch = n & 7;
;         *(LAS u32x4*)(vt + row * VT_PITCH + ch * 16) = R.v[it]; *(LAS u32x4*)(vt + KT_OFF + row * VT_PITCH + ch * 16) = R.k[it]; }
; }
; DI bf16x8 k_frag(const LAS char* vt, int t, int ks, int lane) { return k_frag_at(vt + KT_OFF, t, ks, lane); }
; DI void fb_update(f32x4 (&o)[4], f32x4& ol, const f32x4 st0, const f32x4 st1, const LAS char* vt, int lane) {
;     f32x4 p0, p1;
; #pragma unroll
;     for (int i = 0; i < 4; ++i) { p0[i] = ex2(st0[i]); p1[i] = ex2(st1[i]); }
;     const bf16x8 pf = pack8(p0, p1);
;     const bf16x8 ones = {0x3F80, 0x3F80, 0x3F80, 0x3F80, 0x3F80, 0x3F80, 0x3F80, 0x3F80};
;     ol = MFMA16(ones, pf, ol);
;     const int g = lane >> 4, q = (lane & 15) >> 2, p = lane & 3;
;     const LAS char* v0 = vt + (4 * g + q) * VT_PITCH + 8 * p;
;     const LAS char* v1 = v0 + 16 * VT_PITCH;
; #pragma unroll
;     for (int c = 0; c < 4; ++c) { const bf16x8 vf = cat8(vtr(v0 + 32 * c), vtr(v1 + 32 * c)); o[c] = MFMA16(vf, pf, o[c]); }
; }
; DI float q_norm2(const bf16x8 (&qf)[2]) { float a = sumsq8(qf[0]) + sumsq8(qf[1]); a += __shfl_xor(a, 16); a += __shfl_xor(a, 32); return a; }
; DI void a_desc(int ti, int a0, int rho, int& tokbase, int& stride, int& maxd) {
;     if (ti < 4) { stride = 16; tokbase = rho + 512 * ti; maxd = 1024; }
;     else if (ti < 10) { stride = 4; const int m0 = 4 * a0 + (rho >> 2) - 64 + 32 * (ti - 4); tokbase = 4 * m0 + (rho & 3); maxd = 256; }
;     else { stride = 1; tokbase = 16 * a0 + rho - 64 + 32 * (ti - 10); maxd = 64; }
; }
; template <bool EDGE>
; DI void a_scores(f32x4 (&st)[2], const LAS char* kt, const bf16x8 (&qf)[2], const f32x4 cinit, int tokbase, int stride, int maxd, int tq, float nslope2, int lane) {
;     const int g = lane >> 4;
;     const int base0 = tokbase + stride * 4 * g - tq;
; #pragma unroll
	v_mfma_f32_16x16x32_bf16 v[84:87], v[88:91], v[4:7], v[84:87]
	v_add_u32_e32 v88, 64, v100
	v_cvt_f32_i32_e32 v88, v88
	v_add_u32_e32 v89, 0x140, v100
	v_cmp_gt_u32_e32 vcc, s22, v89
	s_and_b64 vcc, s[20:21], vcc
	s_nop 2
	v_fma_f32 v84, |v88|, v153, v84
	v_cndmask_b32_e32 v96, v234, v84, vcc
	v_add_u32_e32 v84, 0x44, v100
	v_cvt_f32_i32_e32 v84, v84
	v_add_u32_e32 v88, 0x144, v100
	v_cmp_gt_u32_e32 vcc, s22, v88
	v_add_u32_e32 v88, 0x44, v99
	v_cmp_gt_u32_e64 s[0:1], s24, v88
	s_and_b64 vcc, vcc, s[0:1]
	v_fma_f32 v84, |v84|, v153, v85
	v_cndmask_b32_e32 v97, v234, v84, vcc
	v_add_u32_e32 v84, 0x48, v100
	v_cvt_f32_i32_e32 v84, v84
	v_add_u32_e32 v85, 0x148, v100
	v_cmp_gt_u32_e32 vcc, s22, v85
	v_add_u32_e32 v85, 0x48, v99
	v_cmp_gt_u32_e64 s[0:1], s24, v85
	s_and_b64 vcc, vcc, s[0:1]
	v_fma_f32 v84, |v84|, v153, v86
	v_cndmask_b32_e32 v98, v234, v84, vcc
	v_add_u32_e32 v84, 0x4c, v100
	v_add_u32_e32 v85, 0x14c, v100
	v_exp_f32_e32 v91, v187
	v_exp_f32_e32 v100, v191
	v_cvt_f32_i32_e32 v84, v84
	v_cmp_gt_u32_e32 vcc, s22, v85
	v_add_u32_e32 v85, 0x4c, v99
	v_cvt_pk_bf16_f32 v91, v91, v100
	ds_read_b64_tr_b16 v[102:103], v184 offset:2304
	ds_read_b64_tr_b16 v[100:101], v184
	ds_read_b64_tr_b16 v[104:105], v184 offset:32
	ds_read_b64_tr_b16 v[106:107], v184 offset:2336
	ds_read_b64_tr_b16 v[108:109], v184 offset:64
	ds_read_b64_tr_b16 v[110:111], v184 offset:2368
	ds_read_b64_tr_b16 v[112:113], v184 offset:96
	ds_read_b64_tr_b16 v[114:115], v184 offset:2400
	s_waitcnt vmcnt(14)
	ds_write_b128 v183, v[48:51]
	ds_write_b128 v183, v[44:47] offset:9216
	s_waitcnt vmcnt(12)
	ds_write_b128 v183, v[36:39] offset:1152
	ds_write_b128 v183, v[20:23] offset:10368
	s_waitcnt vmcnt(10)
	ds_write_b128 v183, v[28:31] offset:2304
	ds_write_b128 v183, v[24:27] offset:11520
	s_waitcnt vmcnt(8)
	ds_write_b128 v183, v[40:43] offset:3456
	ds_write_b128 v183, v[32:35] offset:12672
	ds_read_b128 v[20:23], v151 offset:9216
	ds_read_b128 v[24:27], v151 offset:9280
	s_waitcnt lgkmcnt(1)
	v_mfma_f32_16x16x32_bf16 v[20:23], v[20:23], v[8:11], v[12:15]
	v_or_b32_e32 v28, s33, v168
	v_cmp_gt_u32_e64 s[0:1], s24, v85
	v_sub_u32_e32 v29, v28, v154
	s_and_b64 vcc, vcc, s[0:1]
	v_fma_f32 v84, |v84|, v153, v87
	s_waitcnt lgkmcnt(0)
	v_mfma_f32_16x16x32_bf16 v[20:23], v[24:27], v[4:7], v[20:23]
	v_add_u32_e32 v24, 0x100, v29
	v_cndmask_b32_e32 v99, v234, v84, vcc
	v_cmp_gt_u32_e32 vcc, s22, v24
	v_cvt_f32_i32_e32 v24, v29
	s_and_b64 vcc, s[96:97], vcc
	v_cmp_gt_u32_e64 s[0:1], s67, v28
	v_exp_f32_e32 v84, v144
	s_nop 0
	v_fma_f32 v20, |v24|, v153, v20
	v_cndmask_b32_e32 v48, v234, v20, vcc
	v_add_u32_e32 v20, 4, v29
	v_cvt_f32_i32_e32 v20, v20
	v_add_u32_e32 v24, 0x104, v29
	v_cmp_gt_u32_e32 vcc, s22, v24
	s_and_b64 vcc, vcc, s[0:1]
	v_fma_f32 v20, |v20|, v153, v21
	v_cndmask_b32_e32 v49, v234, v20, vcc
	v_add_u32_e32 v20, 8, v29
	v_cvt_f32_i32_e32 v20, v20
	v_add_u32_e32 v21, 0x108, v29
	v_cmp_gt_u32_e32 vcc, s22, v21
	v_cmp_gt_u32_e64 s[0:1], s23, v28
	s_and_b64 vcc, vcc, s[0:1]
	v_fma_f32 v20, |v20|, v153, v22
	v_cndmask_b32_e32 v50, v234, v20, vcc
	v_add_u32_e32 v20, 12, v29
	v_cvt_f32_i32_e32 v20, v20
	v_add_u32_e32 v21, 0x10c, v29
	v_cmp_gt_u32_e32 vcc, s22, v21
	v_cmp_gt_u32_e64 s[0:1], s17, v28
	s_and_b64 vcc, vcc, s[0:1]
	v_fma_f32 v20, |v20|, v153, v23
	v_cndmask_b32_e32 v51, v234, v20, vcc
	ds_read_b128 v[20:23], v151 offset:11520
	ds_read_b128 v[24:27], v151 offset:11584
	s_waitcnt lgkmcnt(1)
	v_mfma_f32_16x16x32_bf16 v[20:23], v[20:23], v[8:11], v[12:15]
	v_exp_f32_e32 v85, v155
	v_exp_f32_e32 v86, v145
	v_exp_f32_e32 v87, v186
	s_waitcnt lgkmcnt(0)
	v_mfma_f32_16x16x32_bf16 v[20:23], v[24:27], v[4:7], v[20:23]
	v_add_u32_e32 v24, 64, v29
	v_exp_f32_e32 v89, v146
	v_exp_f32_e32 v90, v147
	v_cvt_f32_i32_e32 v24, v24
	v_add_u32_e32 v25, 0x140, v29
	v_cmp_gt_u32_e32 vcc, s22, v25
	v_cvt_pk_bf16_f32 v88, v84, v86
	v_cvt_pk_bf16_f32 v89, v89, v90
	v_cvt_pk_bf16_f32 v90, v85, v87
	s_and_b64 vcc, s[96:97], vcc
	v_fma_f32 v20, |v24|, v153, v20
	v_mfma_f32_16x16x32_bf16 v[84:87], v[16:19], v[88:91], v[116:119]
	v_add_u32_e32 v24, 0x144, v29
	v_cmp_gt_u32_e64 s[0:1], s58, v28
	v_exp_f32_e32 v25, v98
	v_mfma_f32_16x16x32_bf16 v[100:103], v[100:103], v[88:91], v[136:139]
	v_exp_f32_e32 v26, v95
	v_exp_f32_e32 v27, v99
	v_mfma_f32_16x16x32_bf16 v[104:107], v[104:107], v[88:91], v[120:123]
	v_mfma_f32_16x16x32_bf16 v[108:111], v[108:111], v[88:91], v[124:127]
	v_mfma_f32_16x16x32_bf16 v[88:91], v[112:115], v[88:91], v[128:131]
	v_cndmask_b32_e32 v112, v234, v20, vcc
	v_add_u32_e32 v20, 0x44, v29
	v_cvt_f32_i32_e32 v20, v20
	v_cmp_gt_u32_e32 vcc, s22, v24
	s_and_b64 vcc, vcc, s[0:1]
	v_cmp_gt_u32_e64 s[0:1], s59, v28
	v_fma_f32 v20, |v20|, v153, v21
	v_cndmask_b32_e32 v113, v234, v20, vcc
	v_add_u32_e32 v20, 0x48, v29
	v_cvt_f32_i32_e32 v20, v20
	v_add_u32_e32 v21, 0x148, v29
	v_cmp_gt_u32_e32 vcc, s22, v21
	s_and_b64 vcc, vcc, s[0:1]
	v_fma_f32 v20, |v20|, v153, v22
	v_cndmask_b32_e32 v114, v234, v20, vcc
	v_add_u32_e32 v20, 0x4c, v29
	v_cvt_f32_i32_e32 v20, v20
	v_add_u32_e32 v21, 0x14c, v29
	v_cmp_gt_u32_e64 s[0:1], s52, v28
	ds_read_b64_tr_b16 v[30:31], v184 offset:6912
	ds_read_b64_tr_b16 v[28:29], v184 offset:4608
	ds_read_b64_tr_b16 v[32:33], v184 offset:4640
	ds_read_b64_tr_b16 v[34:35], v184 offset:6944
	v_cmp_gt_u32_e32 vcc, s22, v21
	s_and_b64 vcc, vcc, s[0:1]
	v_fma_f32 v20, |v20|, v153, v23
	v_cndmask_b32_e32 v115, v234, v20, vcc
	v_exp_f32_e32 v20, v92
	v_exp_f32_e32 v22, v96
	v_exp_f32_e32 v21, v93
	v_exp_f32_e32 v23, v97
	v_exp_f32_e32 v24, v94
	ds_read_b64_tr_b16 v[36:37], v184 offset:4672
	ds_read_b64_tr_b16 v[38:39], v184 offset:6976
	ds_read_b64_tr_b16 v[40:41], v184 offset:4704
	ds_read_b64_tr_b16 v[42:43], v184 offset:7008
	v_cvt_pk_bf16_f32 v20, v20, v21
	v_cvt_pk_bf16_f32 v21, v24, v26
	v_cvt_pk_bf16_f32 v22, v22, v23
	v_cvt_pk_bf16_f32 v23, v25, v27
	s_waitcnt vmcnt(6)
; DI void fb_update(f32x4 (&o)[4], f32x4& ol, const f32x4 st0, const f32x4 st1, const LAS char* vt, int lane) {
;     f32x4 p0, p1;
; #pragma unroll
;     for (int i = 0; i < 4; ++i) { p0[i] = ex2(st0[i]); p1[i] = ex2(st1[i]); }
;     const bf16x8 pf = pack8(p0, p1);
;     const bf16x8 ones = {0x3F80, 0x3F80, 0x3F80, 0x3F80, 0x3F80, 0x3F80, 0x3F80, 0x3F80};
;     ol = MFMA16(ones, pf, ol);
;     const int g = lane >> 4, q = (lane & 15) >> 2, p = lane & 3;
;     const LAS char* v0 = vt + (4 * g + q) * VT_PITCH + 8 * p;
;     const LAS char* v1 = v0 + 16 * VT_PITCH;
; #pragma unroll
;     for (int c = 0; c < 4; ++c) { const bf16x8 vf = cat8(vtr(v0 + 32 * c), vtr(v1 + 32 * c)); o[c] = MFMA16(vf, pf, o[c]); }
; }
; DI float q_norm2(const bf16x8 (&qf)[2]) { float a = sumsq8(qf[0]) + sumsq8(qf[1]); a += __shfl_xor(a, 16); a += __shfl_xor(a, 32); return a; }
; DI void a_desc(int ti, int a0, int rho, int& tokbase, int& stride, int& maxd) {
;     if (ti < 4) { stride = 16; tokbase = rho + 512 * ti; maxd = 1024; }
;     else if (ti < 10) { stride = 4; const int m0 = 4 * a0 + (rho >> 2) - 64 + 32 * (ti - 4); tokbase = 4 * m0 + (rho & 3); maxd = 256; }
;     else { stride = 1; tokbase = 16 * a0 + rho - 64 + 32 * (ti - 10); maxd = 64; }
; }
; template <bool EDGE>
; DI void a_scores(f32x4 (&st)[2], const LAS char* kt, const bf16x8 (&qf)[2], const f32x4 cinit, int tokbase, int stride, int maxd, int tq, float nslope2, int lane) {
;     const int g = lane >> 4;
;     const int base0 = tokbase + stride * 4 * g - tq;
; #pragma unroll
;     for (int t = 0; t < 2; ++t) {
;         st[t] = MFMA16(k_frag_at(kt, t, 0, lane), qf[0], cinit); st[t] = MFMA16(k_frag_at(kt, t, 1, lane), qf[1], st[t]);
; #pragma unroll
;         for (int i = 0; i < 4; ++i) { const int d = base0 + stride * (16 * t + i);
;             bool ok = (unsigned)(d + maxd) <= (unsigned)(2 * maxd);
;             if (EDGE) ok = ok && ((unsigned)(d + tq) < (unsigned)T);
;             const float v = __builtin_fmaf(__builtin_fabsf((float)d), nslope2, st[t][i]);
;             st[t][i] = ok ? v : -1e30f; }
;     }
; }
; DI void a_stage(f32x4 (&st)[2], const TileRegs& R, LAS char* vt, int vpar, const bf16x8 (&qf)[2], const f32x4 cinit, int tokbase, int stride, int maxd, int tq, float nslope2, int lane) {
; #pragma unroll
;     for (int it = 0; it < 4; ++it) { const int n = lane + 64 * it, row = n >> 3, ch = n & 7;
	ds_write_b128 v183, v[56:59] offset:4608
	ds_write_b128 v183, v[52:55] offset:9216
	s_waitcnt vmcnt(4)
	ds_write_b128 v183, v[64:67] offset:5760
	ds_write_b128 v183, v[60:63] offset:10368
	s_waitcnt vmcnt(2)
	ds_write_b128 v183, v[72:75] offset:6912
	ds_write_b128 v183, v[68:71] offset:11520
	s_waitcnt vmcnt(0)
	ds_write_b128 v183, v[80:83] offset:8064
	ds_write_b128 v183, v[76:79] offset:12672
	v_mfma_f32_16x16x32_bf16 v[24:27], v[16:19], v[20:23], v[84:87]
	ds_read_b128 v[44:47], v151 offset:9280
	v_or_b32_e32 v52, s5, v168
	v_sub_u32_e32 v53, v52, v154
	s_waitcnt lgkmcnt(14)
	v_mfma_f32_16x16x32_bf16 v[28:31], v[28:31], v[20:23], v[100:103]
	v_cmp_gt_u32_e64 s[0:1], s67, v52
	s_waitcnt lgkmcnt(13)
	v_mfma_f32_16x16x32_bf16 v[32:35], v[32:35], v[20:23], v[104:107]
	s_waitcnt lgkmcnt(11)
	v_mfma_f32_16x16x32_bf16 v[36:39], v[36:39], v[20:23], v[108:111]
	s_waitcnt lgkmcnt(9)
	v_mfma_f32_16x16x32_bf16 v[20:23], v[40:43], v[20:23], v[88:91]
	ds_read_b128 v[40:43], v151 offset:9216
	s_waitcnt lgkmcnt(0)
	v_mfma_f32_16x16x32_bf16 v[40:43], v[40:43], v[8:11], v[12:15]
	v_mfma_f32_16x16x32_bf16 v[40:43], v[44:47], v[4:7], v[40:43]
	v_add_u32_e32 v44, 0x100, v53
	v_cmp_gt_u32_e32 vcc, s22, v44
	v_cvt_f32_i32_e32 v44, v53
	s_and_b64 vcc, s[26:27], vcc
	v_add_u32_e32 v45, 0x104, v53
	s_nop 2
	v_fma_f32 v40, |v44|, v153, v40
	v_cndmask_b32_e32 v44, v234, v40, vcc
	v_add_u32_e32 v40, 4, v53
	v_cvt_f32_i32_e32 v40, v40
	v_cmp_gt_u32_e32 vcc, s22, v45
	s_and_b64 vcc, vcc, s[0:1]
	v_cmp_gt_u32_e64 s[0:1], s23, v52
	v_fma_f32 v40, |v40|, v153, v41
	v_cndmask_b32_e32 v45, v234, v40, vcc
	v_add_u32_e32 v40, 8, v53
	v_cvt_f32_i32_e32 v40, v40
	v_add_u32_e32 v41, 0x108, v53
	v_cmp_gt_u32_e32 vcc, s22, v41
	s_and_b64 vcc, vcc, s[0:1]
	v_fma_f32 v40, |v40|, v153, v42
	v_cndmask_b32_e32 v46, v234, v40, vcc
	v_add_u32_e32 v40, 12, v53
	v_cvt_f32_i32_e32 v40, v40
	v_add_u32_e32 v41, 0x10c, v53
	v_cmp_gt_u32_e32 vcc, s22, v41
	v_cmp_gt_u32_e64 s[0:1], s17, v52
	s_and_b64 vcc, vcc, s[0:1]
	v_fma_f32 v40, |v40|, v153, v43
	v_cndmask_b32_e32 v47, v234, v40, vcc
	ds_read_b128 v[40:43], v151 offset:11520
	s_waitcnt lgkmcnt(0)
	v_mfma_f32_16x16x32_bf16 v[8:11], v[40:43], v[8:11], v[12:15]
	s_nop 2
	ds_read_b128 v[12:15], v151 offset:11584
	s_waitcnt lgkmcnt(0)
	v_mfma_f32_16x16x32_bf16 v[4:7], v[12:15], v[4:7], v[8:11]
	s_nop 2
	v_add_u32_e32 v8, 64, v53
	v_cvt_f32_i32_e32 v8, v8
	v_add_u32_e32 v9, 0x140, v53
	v_cmp_gt_u32_e32 vcc, s22, v9
	s_and_b64 vcc, s[26:27], vcc
	v_fma_f32 v4, |v8|, v153, v4
	v_cndmask_b32_e32 v40, v234, v4, vcc
	v_add_u32_e32 v4, 0x44, v53
	v_cvt_f32_i32_e32 v4, v4
	v_add_u32_e32 v8, 0x144, v53
	v_cmp_gt_u32_e32 vcc, s22, v8
	v_add_u32_e32 v8, 0x44, v52
	v_cmp_gt_u32_e64 s[0:1], s24, v8
	s_and_b64 vcc, vcc, s[0:1]
	v_fma_f32 v4, |v4|, v153, v5
	v_cndmask_b32_e32 v41, v234, v4, vcc
	v_add_u32_e32 v4, 0x48, v53
	v_cvt_f32_i32_e32 v4, v4
	v_add_u32_e32 v5, 0x148, v53
	v_cmp_gt_u32_e32 vcc, s22, v5
	v_add_u32_e32 v5, 0x48, v52
	v_cmp_gt_u32_e64 s[0:1], s24, v5
	s_and_b64 vcc, vcc, s[0:1]
	v_fma_f32 v4, |v4|, v153, v6
	v_cndmask_b32_e32 v42, v234, v4, vcc
	v_add_u32_e32 v4, 0x4c, v53
	v_cvt_f32_i32_e32 v4, v4
	v_add_u32_e32 v5, 0x14c, v53
	v_cmp_gt_u32_e32 vcc, s22, v5
	v_add_u32_e32 v5, 0x4c, v52
	v_cmp_gt_u32_e64 s[0:1], s24, v5
	s_and_b64 vcc, vcc, s[0:1]
	v_fma_f32 v4, |v4|, v153, v7
	v_cndmask_b32_e32 v43, v234, v4, vcc
	v_exp_f32_e32 v4, v48
	v_exp_f32_e32 v6, v112
	v_exp_f32_e32 v5, v49
	v_exp_f32_e32 v7, v113
	v_exp_f32_e32 v8, v50
	v_exp_f32_e32 v9, v114
	v_exp_f32_e32 v10, v51
	v_exp_f32_e32 v11, v115
	v_cvt_pk_bf16_f32 v4, v4, v5
	v_cvt_pk_bf16_f32 v6, v6, v7
	v_cvt_pk_bf16_f32 v5, v8, v10
	v_cvt_pk_bf16_f32 v7, v9, v11
	s_lshl_b64 s[0:1], s[94:95], 22
	s_add_u32 s0, s8, s0
	v_mfma_f32_16x16x32_bf16 v[8:11], v[16:19], v[4:7], v[24:27]
	ds_read_b64_tr_b16 v[14:15], v184 offset:2304
	ds_read_b64_tr_b16 v[12:13], v184
	s_nop 0
	ds_read_b64_tr_b16 v[24:25], v184 offset:32
	ds_read_b64_tr_b16 v[26:27], v184 offset:2336
	s_addc_u32 s1, s9, s1
	s_waitcnt lgkmcnt(2)
	v_mfma_f32_16x16x32_bf16 v[12:15], v[12:15], v[4:7], v[28:31]
	s_nop 2
	ds_read_b64_tr_b16 v[28:29], v184 offset:64
	ds_read_b64_tr_b16 v[30:31], v184 offset:2368
	s_lshl_b32 s2, s2, 7
	s_add_u32 s0, s0, s2
	s_waitcnt lgkmcnt(2)
	v_mfma_f32_16x16x32_bf16 v[24:27], v[24:27], v[4:7], v[32:35]
	s_nop 2
	ds_read_b64_tr_b16 v[32:33], v184 offset:96
	ds_read_b64_tr_b16 v[34:35], v184 offset:2400
	s_addc_u32 s1, s1, 0
	v_mov_b32_e32 v153, v189
	s_waitcnt lgkmcnt(2)
	v_mfma_f32_16x16x32_bf16 v[28:31], v[28:31], v[4:7], v[36:39]
	s_add_i32 s69, s69, 1
	s_bitcmp1_b32 s69, 0
	s_waitcnt lgkmcnt(0)
	v_mfma_f32_16x16x32_bf16 v[4:7], v[32:35], v[4:7], v[20:23]
	v_exp_f32_e32 v32, v46
	v_exp_f32_e32 v33, v42
	v_exp_f32_e32 v34, v47
	v_exp_f32_e32 v20, v44
	v_exp_f32_e32 v22, v40
	v_exp_f32_e32 v21, v45
	v_exp_f32_e32 v23, v41
	v_exp_f32_e32 v35, v43
	v_or_b32_e32 v40, s4, v163
	v_cvt_pk_bf16_f32 v20, v20, v21
	v_cvt_pk_bf16_f32 v21, v32, v34
	v_cvt_pk_bf16_f32 v22, v22, v23
	v_cvt_pk_bf16_f32 v23, v33, v35
	v_ashrrev_i32_e32 v41, 31, v40
	s_nop 0
	v_mfma_f32_16x16x32_bf16 v[32:35], v[16:19], v[20:23], v[8:11]
	s_nop 2
	ds_read_b64_tr_b16 v[8:9], v184 offset:4608
	ds_read_b64_tr_b16 v[10:11], v184 offset:6912
	s_nop 2
	v_add_u32_e32 v34, v169, v148
	s_waitcnt lgkmcnt(0)
	v_mfma_f32_16x16x32_bf16 v[16:19], v[8:11], v[20:23], v[12:15]
	ds_read_b64_tr_b16 v[8:9], v184 offset:4640
	ds_read_b64_tr_b16 v[10:11], v184 offset:6944
	s_waitcnt lgkmcnt(0)
	v_mfma_f32_16x16x32_bf16 v[12:15], v[8:11], v[20:23], v[24:27]
	ds_read_b64_tr_b16 v[8:9], v184 offset:4672
	ds_read_b64_tr_b16 v[10:11], v184 offset:6976
	s_nop 0
	ds_read_b64_tr_b16 v[24:25], v184 offset:4704
	ds_read_b64_tr_b16 v[26:27], v184 offset:7008
	s_waitcnt lgkmcnt(2)
; #define LAS __attribute__((address_space(3)))
; DI void mixerA2_unit(int u, const bf16* PROJ, bf16* YC, const float* LPA, const float* kmax_l, LAS char* vt, int wave, int lane) {
;     ...
;     const float inv = 1.f / (ol[0] + LPA[(size_t)(b * T + tq) * 4 + h]);
;     LAS char* sc = vt + SC_OFF; const int tok0 = 16 * a0 + rho;
;     bf16* ybase = YC + (size_t)b * T * 1024 + h * 64;
;     u32x2 pv[4], gv[4];
;     rows16_load(sc, ybase, 1024, tok0, 16, lane);
; #pragma unroll
;     for (int c = 0; c < 4; ++c) pv[c] = *(const LAS u32x2*)(sc + r * VT_PITCH + (16 * c + 4 * g) * 2);
;     rows16_load(sc, slab(PROJ, C_AG + h * 64, b), 64, tok0, 16, lane);
; #pragma unroll
;     for (int c = 0; c < 4; ++c) gv[c] = *(const LAS u32x2*)(sc + r * VT_PITCH + (16 * c + 4 * g) * 2);
	v_mfma_f32_16x16x32_bf16 v[8:11], v[8:11], v[20:23], v[28:31]
	s_nop 2
	v_add_u32_e32 v29, v182, v166
	s_waitcnt lgkmcnt(0)
	v_mfma_f32_16x16x32_bf16 v[4:7], v[24:27], v[20:23], v[4:7]
	v_lshl_add_u32 v20, s94, 11, v154
	v_ashrrev_i32_e32 v21, 31, v20
	v_lshl_add_u64 v[20:21], v[20:21], 4, s[56:57]
	v_lshl_add_u64 v[20:21], v[20:21], 0, s[34:35]
	global_load_dword v20, v[20:21], off
	v_lshl_add_u64 v[26:27], s[0:1], 0, v[152:153]
	s_mov_b64 s[0:1], 0x1800000
	s_waitcnt vmcnt(0)
	v_add_f32_e32 v28, v32, v20
	v_or_b32_e32 v32, s4, v162
	v_ashrrev_i32_e32 v33, 31, v32
	v_lshlrev_b64 v[20:21], 11, v[32:33]
	v_lshl_add_u64 v[20:21], v[26:27], 0, v[20:21]
	global_load_dwordx4 v[22:25], v[20:21], off
	v_lshlrev_b64 v[32:33], 7, v[32:33]
	s_waitcnt vmcnt(0)
	ds_write_b128 v29, v[22:25] offset:9216
	v_lshlrev_b64 v[22:23], 11, v[40:41]
	v_lshl_add_u64 v[22:23], v[26:27], 0, v[22:23]
	global_load_dwordx4 v[24:27], v[22:23], off
	s_waitcnt vmcnt(0)
	ds_write_b128 v185, v[24:27] offset:9216
	v_lshl_add_u64 v[24:25], s[30:31], 0, v[152:153]
	v_lshl_add_u64 v[24:25], v[24:25], 0, s[0:1]
	v_lshl_add_u64 v[32:33], v[24:25], 0, v[32:33]
	ds_read_b64 v[42:43], v34 offset:9216
	ds_read_b64 v[44:45], v34 offset:9248
	ds_read_b64 v[30:31], v34 offset:9280
	ds_read_b64 v[26:27], v34 offset:9312
	global_load_dwordx4 v[36:39], v[32:33], off
	v_lshlrev_b64 v[32:33], 7, v[40:41]
	v_lshl_add_u64 v[24:25], v[24:25], 0, v[32:33]
	v_div_scale_f32 v35, s[0:1], v28, v28, 1.0
	v_rcp_f32_e32 v40, v35
	s_waitcnt vmcnt(0)
	ds_write_b128 v29, v[36:39] offset:9216
	global_load_dwordx4 v[36:39], v[24:25], off
	v_fma_f32 v41, -v35, v40, 1.0
	v_fmac_f32_e32 v40, v41, v40
	v_div_scale_f32 v41, vcc, 1.0, v28, 1.0
	v_mul_f32_e32 v46, v41, v40
	v_fma_f32 v47, -v35, v46, v41
	v_fmac_f32_e32 v46, v47, v40
	v_fma_f32 v35, -v35, v46, v41
	v_div_fmas_f32 v35, v35, v40, v46
	s_waitcnt lgkmcnt(4)
	v_lshlrev_b32_e32 v40, 16, v42
	v_and_b32_e32 v41, 0xffff0000, v42
	v_pk_add_f32 v[16:17], v[16:17], v[40:41]
	v_lshlrev_b32_e32 v40, 16, v43
	v_and_b32_e32 v41, 0xffff0000, v43
	v_pk_add_f32 v[18:19], v[18:19], v[40:41]
	v_div_fixup_f32 v28, v35, v28, 1.0
	v_pk_mul_f32 v[16:17], v[28:29], v[16:17] op_sel_hi:[0,1]
	v_pk_mul_f32 v[18:19], v[28:29], v[18:19] op_sel_hi:[0,1]
	s_waitcnt vmcnt(0)
	ds_write_b128 v185, v[36:39] offset:9216
	ds_read_b64 v[36:37], v34 offset:9216
	ds_read_b64 v[38:39], v34 offset:9248
	ds_read_b64 v[32:33], v34 offset:9280
	ds_read_b64 v[24:25], v34 offset:9312
	s_waitcnt lgkmcnt(3)
	v_lshlrev_b32_e32 v40, 16, v36
	v_mul_f32_e32 v35, 0xbfb8aa3b, v40
	v_exp_f32_e32 v35, v35
	v_and_b32_e32 v41, 0xffff0000, v36
	v_lshlrev_b32_e32 v36, 16, v37
	v_and_b32_e32 v37, 0xffff0000, v37
	v_add_f32_e32 v35, 1.0, v35
	v_rcp_f32_e32 v42, v35
	v_mul_f32_e32 v35, 0xbfb8aa3b, v41
	v_exp_f32_e32 v35, v35
	s_nop 0
	v_add_f32_e32 v35, 1.0, v35
	v_rcp_f32_e32 v43, v35
	s_nop 0
	v_pk_mul_f32 v[40:41], v[42:43], v[40:41]
	s_nop 0
	v_pk_mul_f32 v[16:17], v[16:17], v[40:41]
	s_nop 0
	v_cvt_pk_bf16_f32 v16, v16, v17
	v_mul_f32_e32 v17, 0xbfb8aa3b, v36
	v_exp_f32_e32 v17, v17
	s_nop 0
	v_add_f32_e32 v17, 1.0, v17
	v_rcp_f32_e32 v40, v17
	v_mul_f32_e32 v17, 0xbfb8aa3b, v37
	v_exp_f32_e32 v17, v17
	s_nop 0
	v_add_f32_e32 v17, 1.0, v17
	v_rcp_f32_e32 v41, v17
	s_nop 0
	v_pk_mul_f32 v[36:37], v[40:41], v[36:37]
	s_nop 0
	v_pk_mul_f32 v[18:19], v[18:19], v[36:37]
	s_nop 0
	v_cvt_pk_bf16_f32 v17, v18, v19
	v_lshlrev_b32_e32 v18, 16, v44
	v_and_b32_e32 v19, 0xffff0000, v44
	v_pk_add_f32 v[12:13], v[12:13], v[18:19]
	v_lshlrev_b32_e32 v18, 16, v45
	v_and_b32_e32 v19, 0xffff0000, v45
	v_pk_add_f32 v[14:15], v[14:15], v[18:19]
	s_waitcnt lgkmcnt(2)
; #define LAS __attribute__((address_space(3)))
; DI unsigned pk2(float lo, float hi) { f32x2_t v = {lo, hi}; bf16x2_t b = __builtin_convertvector(v, bf16x2_t); return __builtin_bit_cast(unsigned, b); }
; DI float silu_f(float x) { return x * __builtin_amdgcn_rcpf(1.f + __expf(-x)); }
; DI void mixerA2_unit(int u, const bf16* PROJ, bf16* YC, const float* LPA, const float* kmax_l, LAS char* vt, int wave, int lane) {
;     ...
; #pragma unroll
;     for (int c = 0; c < 4; ++c) {
;         f32x4 ov = o[c]; ov[0] += bflo(pv[c].x); ov[1] += bfhi(pv[c].x); ov[2] += bflo(pv[c].y); ov[3] += bfhi(pv[c].y); ov = ov * inv;
;         u32x2 w; w.x = pk2(ov[0] * silu_f(bflo(gv[c].x)), ov[1] * silu_f(bfhi(gv[c].x))); w.y = pk2(ov[2] * silu_f(bflo(gv[c].y)), ov[3] * silu_f(bfhi(gv[c].y)));
;         *(LAS u32x2*)(sc + r * VT_PITCH + (16 * c + 4 * g) * 2) = w; }
;     rows16_store(sc, ybase, 1024, tok0, 16, lane);
	v_lshlrev_b32_e32 v18, 16, v38
	v_mul_f32_e32 v35, 0xbfb8aa3b, v18
	v_exp_f32_e32 v35, v35
	v_and_b32_e32 v19, 0xffff0000, v38
	v_pk_mul_f32 v[12:13], v[28:29], v[12:13] op_sel_hi:[0,1]
	v_pk_mul_f32 v[14:15], v[28:29], v[14:15] op_sel_hi:[0,1]
	v_add_f32_e32 v35, 1.0, v35
	v_rcp_f32_e32 v36, v35
	v_mul_f32_e32 v35, 0xbfb8aa3b, v19
	v_exp_f32_e32 v35, v35
	s_nop 0
	v_add_f32_e32 v35, 1.0, v35
	v_rcp_f32_e32 v37, v35
	s_nop 0
	v_pk_mul_f32 v[18:19], v[36:37], v[18:19]
	s_nop 0
	v_pk_mul_f32 v[12:13], v[12:13], v[18:19]
	v_lshlrev_b32_e32 v18, 16, v39
	v_cvt_pk_bf16_f32 v12, v12, v13
	v_mul_f32_e32 v13, 0xbfb8aa3b, v18
	v_exp_f32_e32 v13, v13
	v_and_b32_e32 v19, 0xffff0000, v39
	v_add_f32_e32 v13, 1.0, v13
	v_rcp_f32_e32 v36, v13
	v_mul_f32_e32 v13, 0xbfb8aa3b, v19
	v_exp_f32_e32 v13, v13
	s_nop 0
	v_add_f32_e32 v13, 1.0, v13
	v_rcp_f32_e32 v37, v13
	s_nop 0
	v_pk_mul_f32 v[18:19], v[36:37], v[18:19]
	s_nop 0
	v_pk_mul_f32 v[14:15], v[14:15], v[18:19]
	s_nop 0
	v_cvt_pk_bf16_f32 v13, v14, v15
	v_add_u32_e32 v14, 0x2000, v34
	ds_write2_b64 v14, v[16:17], v[12:13] offset0:128 offset1:132
	v_lshlrev_b32_e32 v12, 16, v30
	v_and_b32_e32 v13, 0xffff0000, v30
	v_pk_add_f32 v[8:9], v[8:9], v[12:13]
	v_lshlrev_b32_e32 v12, 16, v31
	v_and_b32_e32 v13, 0xffff0000, v31
	v_pk_add_f32 v[10:11], v[10:11], v[12:13]
	s_waitcnt lgkmcnt(2)
	v_lshlrev_b32_e32 v12, 16, v32
	v_mul_f32_e32 v15, 0xbfb8aa3b, v12
	v_exp_f32_e32 v15, v15
	v_and_b32_e32 v13, 0xffff0000, v32
	v_pk_mul_f32 v[8:9], v[28:29], v[8:9] op_sel_hi:[0,1]
	v_pk_mul_f32 v[10:11], v[28:29], v[10:11] op_sel_hi:[0,1]
	v_add_f32_e32 v15, 1.0, v15
	v_rcp_f32_e32 v16, v15
	v_mul_f32_e32 v15, 0xbfb8aa3b, v13
	v_exp_f32_e32 v15, v15
	s_nop 0
	v_add_f32_e32 v15, 1.0, v15
	v_rcp_f32_e32 v17, v15
	s_nop 0
	v_pk_mul_f32 v[12:13], v[16:17], v[12:13]
	s_nop 0
	v_pk_mul_f32 v[8:9], v[8:9], v[12:13]
	v_lshlrev_b32_e32 v12, 16, v33
	v_cvt_pk_bf16_f32 v8, v8, v9
	v_mul_f32_e32 v9, 0xbfb8aa3b, v12
	v_exp_f32_e32 v9, v9
	v_and_b32_e32 v13, 0xffff0000, v33
	v_add_f32_e32 v9, 1.0, v9
	v_rcp_f32_e32 v16, v9
	v_mul_f32_e32 v9, 0xbfb8aa3b, v13
	v_exp_f32_e32 v9, v9
	s_nop 0
	v_add_f32_e32 v9, 1.0, v9
	v_rcp_f32_e32 v17, v9
	s_nop 0
	v_pk_mul_f32 v[12:13], v[16:17], v[12:13]
	s_nop 0
	v_pk_mul_f32 v[10:11], v[10:11], v[12:13]
	s_nop 0
	v_cvt_pk_bf16_f32 v9, v10, v11
	v_lshlrev_b32_e32 v10, 16, v26
	v_and_b32_e32 v11, 0xffff0000, v26
	v_pk_add_f32 v[10:11], v[4:5], v[10:11]
	v_lshlrev_b32_e32 v4, 16, v27
	v_and_b32_e32 v5, 0xffff0000, v27
	v_pk_add_f32 v[4:5], v[6:7], v[4:5]
	v_pk_mul_f32 v[6:7], v[28:29], v[10:11] op_sel_hi:[0,1]
	s_waitcnt lgkmcnt(1)
	v_lshlrev_b32_e32 v10, 16, v24
	v_and_b32_e32 v11, 0xffff0000, v24
	v_mul_f32_e32 v12, 0xbfb8aa3b, v10
	v_mul_f32_e32 v13, 0xbfb8aa3b, v11
	v_exp_f32_e32 v12, v12
	v_exp_f32_e32 v13, v13
	v_pk_mul_f32 v[4:5], v[28:29], v[4:5] op_sel_hi:[0,1]
	v_add_f32_e32 v12, 1.0, v12
	v_add_f32_e32 v13, 1.0, v13
	v_rcp_f32_e32 v12, v12
	v_rcp_f32_e32 v13, v13
	s_nop 0
	v_pk_mul_f32 v[10:11], v[12:13], v[10:11]
	s_nop 0
	v_pk_mul_f32 v[6:7], v[6:7], v[10:11]
	v_lshlrev_b32_e32 v10, 16, v25
	v_cvt_pk_bf16_f32 v6, v6, v7
	v_mul_f32_e32 v7, 0xbfb8aa3b, v10
	v_exp_f32_e32 v7, v7
	v_and_b32_e32 v11, 0xffff0000, v25
	v_add_f32_e32 v7, 1.0, v7
	v_rcp_f32_e32 v12, v7
	v_mul_f32_e32 v7, 0xbfb8aa3b, v11
	v_exp_f32_e32 v7, v7
	s_nop 0
	v_add_f32_e32 v7, 1.0, v7
	v_rcp_f32_e32 v13, v7
	s_nop 0
	v_pk_mul_f32 v[10:11], v[12:13], v[10:11]
	s_nop 0
	v_pk_mul_f32 v[4:5], v[4:5], v[10:11]
	s_nop 0
	v_cvt_pk_bf16_f32 v7, v4, v5
	ds_write2_b64 v14, v[8:9], v[6:7] offset0:136 offset1:140
	ds_read_b128 v[4:7], v29 offset:9216
	s_waitcnt lgkmcnt(0)
	global_store_dwordx4 v[20:21], v[4:7], off
	ds_read_b128 v[4:7], v185 offset:9216
	s_waitcnt lgkmcnt(0)
	global_store_dwordx4 v[22:23], v[4:7], off
	s_cbranch_scc1 .LBB0_421
	v_readlane_b32 s94, v255, 33
	v_readlane_b32 s90, v255, 23
	v_readlane_b32 s58, v253, 24
	v_readlane_b32 s26, v255, 35
	v_readlane_b32 s95, v255, 34
	s_mov_b64 s[96:97], s[56:57]
	v_readlane_b32 s56, v255, 21
	v_readlane_b32 s91, v255, 24
	v_readlane_b32 s59, v253, 25
	v_readlane_b32 s27, v255, 36
	v_readlane_b32 s57, v255, 22
